# third combination: second combination + SGPR-base LDS-DMA (dead address adds removed), permlane swaps for ds_bpermute in the out-GEMM epilogues, counted waits after the residual loads
# speedup vs baseline: 1.0136x; 1.0012x over previous
; #define TIDX opq((int)threadIdx.x)
; #define PG8_STAGE(bufoff, gbase, voff) do { _Pragma("unroll") for (int _i = 0; _i < 2; ++_i) \
;         __builtin_amdgcn_global_load_lds((const unsigned*)((const char*)(gbase) + (voff)[_i]), (PG8_LAS unsigned*)(lds + (bufoff) + ldsw + _i * 8192), 16, 0, 0); } while (0)
; #define PG8_WAIT_V(n) asm volatile("s_waitcnt vmcnt(" #n ")" ::: "memory")
; #define PG8_BAR __builtin_amdgcn_s_barrier()
; template <class Epi, class Sched, class Gemm, bool ALIGN_EPI = false, bool SP2 = false>
; __device__ __forceinline__ void gemm_phase(PG8_LAS unsigned char* lds, const Gemm g, const Sched& S, const Epi& E) {
;     const int tid = TIDX, wid = __builtin_amdgcn_readfirstlane(tid >> 6), lane = tid & 63, wr = wid >> 2, wc = wid & 3, fr = lane & 15, fq = lane >> 4;
;     constexpr int K = Gemm::K, nt = K / BK, lda = Gemm::lda, ldb = Gemm::ldb;
;     constexpr int BP = epi_bperm<Epi>::value;
;     unsigned voffA[2], voffB[2], voffB1[2];
; #pragma unroll
;     for (int i = 0; i < 2; ++i) { int R, C; stage_rc(tid * 16 + i * 8192, R, C);
;         voffA[i] = (unsigned)(R * lda + C) * 2u;
;         if constexpr (BP == 2) { const int w_ = R >> 5, n_ = (R >> 4) & 1, j_ = R & 15, cb_ = w_ * 64 + 16 * (j_ >> 2) + 4 * n_ + (j_ & 3);
;             voffB[i] = (unsigned)(cb_ * ldb + C) * 2u; voffB1[i] = voffB[i]; }
;         else { const int Rb = (BP == 1) ? ((R & ~31) + perm32(R & 31)) : R; voffB[i] = (unsigned)(Rb * ldb + C) * 2u; voffB1[i] = voffB[i]; } }
;     const size_t kstep = (size_t)(BK * 2);
;     const size_t hstepA = (size_t)HALF * lda * 2, hstepB = (size_t)HALF * ldb * 2, hB1 = (BP == 2) ? (size_t)8 * ldb * 2 : hstepB;
;     const size_t tstepA = 2 * hstepA, tstepB = 2 * hstepB;
;     const unsigned ldsw = (unsigned)wid * 1024u;
;     const int aoff = lds_byte(wr * 64 + fr, fq * 8), boff = lds_byte(wc * 32 + fr, fq * 8);
;     ...
;     if constexpr (SP2) {
;         PG8_STAGE(PG8_SB(0, 0), cB, voffB); PG8_STAGE(PG8_SB(0, 1), cB + hB1, voffB1); PG8_STAGE(PG8_SA(0, 0), cA, voffA); PG8_STAGE(PG8_SA(0, 1), cA + hstepA, voffA);
;         if (wr == 1) PG8_BAR;
;         PG8_WAIT_V(2); PG8_BAR;
;         PG8_STAGE(PG8_SB(1, 0), cB + kstep, voffB); PG8_STAGE(PG8_SA(1, 0), cA + kstep, voffA); PG8_STAGE(PG8_SB(1, 1), cB + hB1 + kstep, voffB1);
;         PG8_WAIT_V(6); PG8_BAR;
.LBB0_129:
	s_add_u32 s28, s24, 0x6b28000
	s_addc_u32 s29, s25, 0
	s_add_u32 s30, s24, 0x1dd08000
	s_addc_u32 s31, s25, 0
	s_add_u32 s34, s24, 0x1dd30000
	s_addc_u32 s35, s25, 0
	s_lshl_b32 s70, s4, 6
	s_lshl_b32 s1, s4, 13
	s_lshl_b32 s4, s5, 5
	s_mov_b64 s[36:37], 0x80
	s_and_b32 s71, s4, 0x60
	s_add_i32 m0, s65, 0x18000
	v_lshl_add_u64 v[8:9], v[8:9], 0, s[36:37]
	s_lshl_b32 s7, s71, 7
	s_waitcnt vmcnt(2)
	s_barrier
	global_load_lds_dwordx4 v[8:9], off
	v_lshl_add_u64 v[6:7], v[6:7], 0, s[36:37]
	s_add_i32 m0, s65, 0x1a000
	s_add_i32 s72, s65, 0x8000
	s_add_i32 s73, s65, 0xa000
	global_load_lds_dwordx4 v[6:7], off
	v_lshl_add_u64 v[2:3], v[2:3], 0, s[36:37]
	s_mov_b32 m0, s72
	s_add_u32 s4, s48, 0x20080
	global_load_lds_dwordx4 v[2:3], off
	v_lshl_add_u64 v[2:3], v[4:5], 0, s[36:37]
	s_mov_b32 m0, s73
	s_addc_u32 s5, s49, 0
	global_load_lds_dwordx4 v[2:3], off
	s_add_i32 m0, s65, 0x1c000
	v_lshl_add_u64 v[2:3], s[4:5], 0, v[212:213]
	global_load_lds_dwordx4 v212, s[4:5]
	v_lshl_add_u64 v[2:3], s[4:5], 0, v[216:217]
	s_add_i32 m0, s65, 0x1e000
	v_and_b32_e32 v1, 15, v10
	global_load_lds_dwordx4 v216, s[4:5]
	v_and_b32_e32 v2, 48, v10
	v_lshlrev_b32_e32 v3, 2, v10
	v_lshl_or_b32 v2, v1, 6, v2
	v_and_b32_e32 v3, 32, v3
	v_bitop3_b32 v4, v2, s1, v3 bitop3:0xde
	v_bitop3_b32 v251, s7, v2, v3 bitop3:0xf6
	v_lshrrev_b32_e32 v2, 1, v10
	v_and_or_b32 v252, v2, 24, s71
	v_lshlrev_b32_e32 v2, 13, v14
	v_and_b32_e32 v2, 0xffffc000, v2
	v_lshl_add_u32 v2, v15, 10, v2
	v_and_b32_e32 v3, 1, v14
	v_lshl_or_b32 v2, v3, 6, v2
	v_lshl_add_u32 v218, v16, 1, v2
	v_lshlrev_b32_e32 v2, 13, v11
	v_and_b32_e32 v2, 0xffffc000, v2
	s_waitcnt vmcnt(6)
	s_cmpk_lt_u32 s33, 0x100
	v_lshl_add_u32 v2, v12, 10, v2
	v_and_b32_e32 v3, 1, v11
	s_cselect_b64 s[38:39], -1, 0
	v_lshl_or_b32 v2, v3, 6, v2
	s_add_i32 s76, 0, 0x10000
	s_add_i32 s77, 0, 0x14000
	v_bfe_u32 v250, v10, 4, 2
	s_ashr_i32 s74, s58, 31
	s_ashr_i32 s75, s59, 31
	v_mov_b32_e32 v219, v213
	v_lshl_add_u32 v220, v13, 1, v2
	v_mov_b32_e32 v221, v213
	v_add_u32_e32 v253, s76, v251
	v_add_u32_e32 v254, s77, v251
	v_add_u32_e32 v222, 0, v4
	s_movk_i32 s78, 0x2200
	s_barrier
	s_branch .LBB0_132

; #define PG8_STAGE(bufoff, gbase, voff) do { _Pragma("unroll") for (int _i = 0; _i < 2; ++_i) \
;         __builtin_amdgcn_global_load_lds((const unsigned*)((const char*)(gbase) + (voff)[_i]), (PG8_LAS unsigned*)(lds + (bufoff) + ldsw + _i * 8192), 16, 0, 0); } while (0)
; #define PG8_LDA(dst, b, h) do { _Pragma("unroll") for (int m = 0; m < 4; ++m) _Pragma("unroll") for (int k = 0; k < 2; ++k) dst[m][k] = *(const PG8_LAS bf16x8*)(lds + PG8_SA(b, h) + aoff + m * 2048 + k * 1024); } while (0)
; #define PG8_WAIT_V(n) asm volatile("s_waitcnt vmcnt(" #n ")" ::: "memory")
; template <class Epi, class Sched, class Gemm, bool ALIGN_EPI = false, bool SP2 = false>
; __device__ __forceinline__ void gemm_phase(PG8_LAS unsigned char* lds, const Gemm g, const Sched& S, const Epi& E) {
;     ...
;         for (int t = 0; t < nt; t += 2) {
;             const bool last = (t == nt - 2);
;             const char* a1 = cA + (size_t)(t + 1) * kstep;
;             const char* a2 = last ? nA : cA + (size_t)(t + 2) * kstep; const char* b2 = last ? nB : cB + (size_t)(t + 2) * kstep;
;             const char* a3 = a2 + kstep; const char* b3 = b2 + kstep;
;             if (last && has_next) S.a_ready(nxt);
;             if constexpr (SP2) {
;             PG8_LDB(B0, 0, 0); PG8_LDB(B1, 0, 1); PG8_SCHED; PG8_LDA(At, 0, 0); PG8_STAGE(PG8_SA(1, 1), a1 + hstepA, voffA);
;             PG8_WAIT_V(8); PG8_WAIT_L(0); PG8_BAR; PG8_MMA(0, 0, At, B0); PG8_MMA(0, 1, At, B1); PG8_BAR; PG8_SCHED;
;             PG8_LDA(At, 0, 1); PG8_STAGE(PG8_SB(0, 0), b2, voffB); PG8_STAGE(PG8_SB(0, 1), b2 + hB1, voffB1); PG8_STAGE(PG8_SA(0, 0), a2, voffA);
;             PG8_WAIT_V(8); PG8_WAIT_L(0); PG8_BAR; PG8_MMA(1, 0, At, B0); PG8_MMA(1, 1, At, B1); PG8_BAR; PG8_SCHED;
;             PG8_LDB(B0, 1, 0); PG8_LDB(B1, 1, 1); PG8_SCHED; PG8_LDA(At, 1, 0); PG8_STAGE(PG8_SA(0, 1), a2 + hstepA, voffA);
;             PG8_WAIT_V(8); PG8_WAIT_L(0); PG8_BAR; PG8_MMA(0, 0, At, B0); PG8_MMA(0, 1, At, B1); PG8_BAR; PG8_SCHED;
;             PG8_LDA(At, 1, 1); PG8_STAGE(PG8_SB(1, 0), b3, voffB); PG8_STAGE(PG8_SB(1, 1), b3 + hB1, voffB1); PG8_STAGE(PG8_SA(1, 0), a3, voffA);
;             PG8_WAIT_V(8);
;             if constexpr (epi_pre<Epi>::value) { if (last) E.pre(pre, cur, wr, wc, lane); }
;             PG8_WAIT_L(0); PG8_BAR; PG8_MMA(1, 0, At, B0); PG8_MMA(1, 1, At, B1); PG8_BAR; PG8_SCHED;
.LBB0_136:
	s_add_u32 s0, s48, 0xfffe0080
	s_addc_u32 s1, s49, -1
	s_cmp_eq_u32 s2, 4
	s_cselect_b32 s53, s7, s1
	s_cselect_b32 s52, s43, s0
	s_cselect_b32 s55, s79, s82
	s_cselect_b32 s54, s80, s81
	s_add_i32 s95, s76, s64
	ds_read_b128 v[174:177], v253
	ds_read_b128 v[170:173], v253 offset:1024
	ds_read_b128 v[166:169], v253 offset:2048
	ds_read_b128 v[162:165], v253 offset:3072
	ds_read_b128 v[158:161], v254
	ds_read_b128 v[154:157], v254 offset:1024
	ds_read_b128 v[150:153], v254 offset:2048
	ds_read_b128 v[146:149], v254 offset:3072
	s_add_i32 m0, s65, 0xc000
	s_add_i32 s96, s65, 0xe000
	s_add_i32 s92, s95, 0x2000
	s_add_u32 s56, s54, 0x20000
	s_addc_u32 s57, s55, 0
	s_add_i32 s94, s77, s64
	s_add_i32 s93, s94, 0x2000
	s_add_i32 s91, 0, 0x18000
	s_add_i32 s90, 0, 0x1c000
	s_add_u32 s50, s52, 0x20000
	s_addc_u32 s51, s53, 0
	s_add_i32 s83, s91, s64
	s_add_i32 s3, s83, 0x2000
	s_add_u32 s0, s54, 0x20080
	s_addc_u32 s1, s55, 0
	s_add_i32 s89, s90, s64
	s_add_i32 s88, s89, 0x2000
	s_cmp_lg_u32 s2, 4
	ds_read_b128 v[190:193], v222
	ds_read_b128 v[194:197], v222 offset:1024
	ds_read_b128 v[198:201], v222 offset:2048
	ds_read_b128 v[202:205], v222 offset:3072
	ds_read_b128 v[206:209], v222 offset:4096
	ds_read_b128 v[186:189], v222 offset:5120
	ds_read_b128 v[182:185], v222 offset:6144
	ds_read_b128 v[178:181], v222 offset:7168
	global_load_lds_dwordx4 v220, s[48:49]
	s_mov_b32 m0, s96
	s_nop 0
	global_load_lds_dwordx4 v218, s[48:49]
	s_waitcnt vmcnt(8)
	s_waitcnt lgkmcnt(0)
	s_barrier
	s_setprio 1
	s_waitcnt lgkmcnt(0)
	v_mfma_i32_16x16x64_i8 v[142:145], v[174:177], v[190:193], v[142:145]
	v_mfma_i32_16x16x64_i8 v[138:141], v[166:169], v[190:193], v[138:141]
	v_mfma_i32_16x16x64_i8 v[126:129], v[174:177], v[198:201], v[126:129]
	v_mfma_i32_16x16x64_i8 v[122:125], v[166:169], v[198:201], v[122:125]
	v_mfma_i32_16x16x64_i8 v[110:113], v[174:177], v[206:209], v[110:113]
	v_mfma_i32_16x16x64_i8 v[106:109], v[166:169], v[206:209], v[106:109]
	v_mfma_i32_16x16x64_i8 v[94:97], v[174:177], v[182:185], v[94:97]
	v_mfma_i32_16x16x64_i8 v[90:93], v[166:169], v[182:185], v[90:93]
	v_mfma_i32_16x16x64_i8 v[142:145], v[170:173], v[194:197], v[142:145]
	v_mfma_i32_16x16x64_i8 v[138:141], v[162:165], v[194:197], v[138:141]
	v_mfma_i32_16x16x64_i8 v[126:129], v[170:173], v[202:205], v[126:129]
	v_mfma_i32_16x16x64_i8 v[122:125], v[162:165], v[202:205], v[122:125]
	v_mfma_i32_16x16x64_i8 v[110:113], v[170:173], v[186:189], v[110:113]
	v_mfma_i32_16x16x64_i8 v[106:109], v[162:165], v[186:189], v[106:109]
	v_mfma_i32_16x16x64_i8 v[94:97], v[170:173], v[178:181], v[94:97]
	v_mfma_i32_16x16x64_i8 v[90:93], v[162:165], v[178:181], v[90:93]
	s_setprio 0
	s_setprio 1
	v_mfma_i32_16x16x64_i8 v[134:137], v[158:161], v[190:193], v[134:137]
	v_mfma_i32_16x16x64_i8 v[130:133], v[150:153], v[190:193], v[130:133]
	v_mfma_i32_16x16x64_i8 v[118:121], v[158:161], v[198:201], v[118:121]
	v_mfma_i32_16x16x64_i8 v[114:117], v[150:153], v[198:201], v[114:117]
	v_mfma_i32_16x16x64_i8 v[102:105], v[158:161], v[206:209], v[102:105]
	v_mfma_i32_16x16x64_i8 v[98:101], v[150:153], v[206:209], v[98:101]
	v_mfma_i32_16x16x64_i8 v[86:89], v[158:161], v[182:185], v[86:89]
	v_mfma_i32_16x16x64_i8 v[82:85], v[150:153], v[182:185], v[82:85]
	v_mfma_i32_16x16x64_i8 v[134:137], v[154:157], v[194:197], v[134:137]
	v_mfma_i32_16x16x64_i8 v[130:133], v[146:149], v[194:197], v[130:133]
	v_mfma_i32_16x16x64_i8 v[118:121], v[154:157], v[202:205], v[118:121]
	v_mfma_i32_16x16x64_i8 v[114:117], v[146:149], v[202:205], v[114:117]
	v_mfma_i32_16x16x64_i8 v[102:105], v[154:157], v[186:189], v[102:105]
	v_mfma_i32_16x16x64_i8 v[98:101], v[146:149], v[186:189], v[98:101]
	v_mfma_i32_16x16x64_i8 v[86:89], v[154:157], v[178:181], v[86:89]
	v_mfma_i32_16x16x64_i8 v[82:85], v[146:149], v[178:181], v[82:85]
	s_setprio 0
	s_barrier
	s_mov_b32 m0, s95
	v_lshl_add_u64 v[242:243], s[54:55], 0, v[212:213]
	ds_read_b128 v[190:193], v222 offset:16384
	ds_read_b128 v[194:197], v222 offset:17408
	ds_read_b128 v[198:201], v222 offset:18432
	ds_read_b128 v[202:205], v222 offset:19456
	ds_read_b128 v[206:209], v222 offset:20480
	ds_read_b128 v[186:189], v222 offset:21504
	ds_read_b128 v[182:185], v222 offset:22528
	ds_read_b128 v[178:181], v222 offset:23552
	global_load_lds_dwordx4 v212, s[54:55]
	v_lshl_add_u64 v[244:245], s[54:55], 0, v[216:217]
	s_mov_b32 m0, s92
	v_lshl_add_u64 v[246:247], s[56:57], 0, v[212:213]
	global_load_lds_dwordx4 v216, s[54:55]
	s_mov_b32 m0, s94
	v_lshl_add_u64 v[248:249], s[52:53], 0, v[214:215]
	global_load_lds_dwordx4 v212, s[56:57]
	s_mov_b32 m0, s93
	s_nop 0
	global_load_lds_dwordx4 v216, s[56:57]
	v_lshl_add_u64 v[246:247], s[52:53], 0, v[210:211]
	s_mov_b32 m0, s65
	s_nop 0
	global_load_lds_dwordx4 v210, s[52:53]
	s_mov_b32 m0, s66
	s_nop 0
	global_load_lds_dwordx4 v214, s[52:53]
	s_waitcnt vmcnt(8)
	s_waitcnt lgkmcnt(0)
	s_barrier
; #define PG8_STAGE(bufoff, gbase, voff) do { _Pragma("unroll") for (int _i = 0; _i < 2; ++_i) \
;         __builtin_amdgcn_global_load_lds((const unsigned*)((const char*)(gbase) + (voff)[_i]), (PG8_LAS unsigned*)(lds + (bufoff) + ldsw + _i * 8192), 16, 0, 0); } while (0)
; #define PG8_LDA(dst, b, h) do { _Pragma("unroll") for (int m = 0; m < 4; ++m) _Pragma("unroll") for (int k = 0; k < 2; ++k) dst[m][k] = *(const PG8_LAS bf16x8*)(lds + PG8_SA(b, h) + aoff + m * 2048 + k * 1024); } while (0)
; #define PG8_WAIT_V(n) asm volatile("s_waitcnt vmcnt(" #n ")" ::: "memory")
; template <class Epi, class Sched, class Gemm, bool ALIGN_EPI = false, bool SP2 = false>
; __device__ __forceinline__ void gemm_phase(PG8_LAS unsigned char* lds, const Gemm g, const Sched& S, const Epi& E) {
;     ...
;         for (int t = 0; t < nt; t += 2) {
;             const bool last = (t == nt - 2);
;             const char* a1 = cA + (size_t)(t + 1) * kstep;
;             const char* a2 = last ? nA : cA + (size_t)(t + 2) * kstep; const char* b2 = last ? nB : cB + (size_t)(t + 2) * kstep;
;             const char* a3 = a2 + kstep; const char* b3 = b2 + kstep;
;             if (last && has_next) S.a_ready(nxt);
;             if constexpr (SP2) {
;             PG8_LDB(B0, 0, 0); PG8_LDB(B1, 0, 1); PG8_SCHED; PG8_LDA(At, 0, 0); PG8_STAGE(PG8_SA(1, 1), a1 + hstepA, voffA);
;             PG8_WAIT_V(8); PG8_WAIT_L(0); PG8_BAR; PG8_MMA(0, 0, At, B0); PG8_MMA(0, 1, At, B1); PG8_BAR; PG8_SCHED;
;             PG8_LDA(At, 0, 1); PG8_STAGE(PG8_SB(0, 0), b2, voffB); PG8_STAGE(PG8_SB(0, 1), b2 + hB1, voffB1); PG8_STAGE(PG8_SA(0, 0), a2, voffA);
;             PG8_WAIT_V(8); PG8_WAIT_L(0); PG8_BAR; PG8_MMA(1, 0, At, B0); PG8_MMA(1, 1, At, B1); PG8_BAR; PG8_SCHED;
;             PG8_LDB(B0, 1, 0); PG8_LDB(B1, 1, 1); PG8_SCHED; PG8_LDA(At, 1, 0); PG8_STAGE(PG8_SA(0, 1), a2 + hstepA, voffA);
;             PG8_WAIT_V(8); PG8_WAIT_L(0); PG8_BAR; PG8_MMA(0, 0, At, B0); PG8_MMA(0, 1, At, B1); PG8_BAR; PG8_SCHED;
;             PG8_LDA(At, 1, 1); PG8_STAGE(PG8_SB(1, 0), b3, voffB); PG8_STAGE(PG8_SB(1, 1), b3 + hB1, voffB1); PG8_STAGE(PG8_SA(1, 0), a3, voffA);
;             PG8_WAIT_V(8);
;             if constexpr (epi_pre<Epi>::value) { if (last) E.pre(pre, cur, wr, wc, lane); }
;             PG8_WAIT_L(0); PG8_BAR; PG8_MMA(1, 0, At, B0); PG8_MMA(1, 1, At, B1); PG8_BAR; PG8_SCHED;
	s_setprio 1
	s_waitcnt lgkmcnt(0)
	v_mfma_i32_16x16x64_i8 v[78:81], v[174:177], v[190:193], v[78:81]
	v_mfma_i32_16x16x64_i8 v[74:77], v[166:169], v[190:193], v[74:77]
	v_mfma_i32_16x16x64_i8 v[62:65], v[174:177], v[198:201], v[62:65]
	v_mfma_i32_16x16x64_i8 v[58:61], v[166:169], v[198:201], v[58:61]
	v_mfma_i32_16x16x64_i8 v[46:49], v[174:177], v[206:209], v[46:49]
	v_mfma_i32_16x16x64_i8 v[42:45], v[166:169], v[206:209], v[42:45]
	v_mfma_i32_16x16x64_i8 v[30:33], v[174:177], v[182:185], v[30:33]
	v_mfma_i32_16x16x64_i8 v[26:29], v[166:169], v[182:185], v[26:29]
	v_mfma_i32_16x16x64_i8 v[78:81], v[170:173], v[194:197], v[78:81]
	v_mfma_i32_16x16x64_i8 v[74:77], v[162:165], v[194:197], v[74:77]
	v_mfma_i32_16x16x64_i8 v[62:65], v[170:173], v[202:205], v[62:65]
	v_mfma_i32_16x16x64_i8 v[58:61], v[162:165], v[202:205], v[58:61]
	v_mfma_i32_16x16x64_i8 v[46:49], v[170:173], v[186:189], v[46:49]
	v_mfma_i32_16x16x64_i8 v[42:45], v[162:165], v[186:189], v[42:45]
	v_mfma_i32_16x16x64_i8 v[30:33], v[170:173], v[178:181], v[30:33]
	v_mfma_i32_16x16x64_i8 v[26:29], v[162:165], v[178:181], v[26:29]
	s_setprio 0
	s_setprio 1
	v_mfma_i32_16x16x64_i8 v[70:73], v[158:161], v[190:193], v[70:73]
	v_mfma_i32_16x16x64_i8 v[66:69], v[150:153], v[190:193], v[66:69]
	v_mfma_i32_16x16x64_i8 v[54:57], v[158:161], v[198:201], v[54:57]
	v_mfma_i32_16x16x64_i8 v[50:53], v[150:153], v[198:201], v[50:53]
	v_mfma_i32_16x16x64_i8 v[38:41], v[158:161], v[206:209], v[38:41]
	v_mfma_i32_16x16x64_i8 v[34:37], v[150:153], v[206:209], v[34:37]
	v_mfma_i32_16x16x64_i8 v[22:25], v[158:161], v[182:185], v[22:25]
	v_mfma_i32_16x16x64_i8 v[18:21], v[150:153], v[182:185], v[18:21]
	v_mfma_i32_16x16x64_i8 v[70:73], v[154:157], v[194:197], v[70:73]
	v_mfma_i32_16x16x64_i8 v[66:69], v[146:149], v[194:197], v[66:69]
	v_mfma_i32_16x16x64_i8 v[54:57], v[154:157], v[202:205], v[54:57]
	v_mfma_i32_16x16x64_i8 v[50:53], v[146:149], v[202:205], v[50:53]
	v_mfma_i32_16x16x64_i8 v[38:41], v[154:157], v[186:189], v[38:41]
	v_mfma_i32_16x16x64_i8 v[34:37], v[146:149], v[186:189], v[34:37]
	v_mfma_i32_16x16x64_i8 v[22:25], v[154:157], v[178:181], v[22:25]
	v_mfma_i32_16x16x64_i8 v[18:21], v[146:149], v[178:181], v[18:21]
	s_setprio 0
	s_barrier
	v_add_u32_e32 v146, s91, v251
	ds_read_b128 v[174:177], v146
	ds_read_b128 v[170:173], v146 offset:1024
	ds_read_b128 v[166:169], v146 offset:2048
	ds_read_b128 v[162:165], v146 offset:3072
	v_add_u32_e32 v146, s90, v251
	ds_read_b128 v[150:153], v146
	ds_read_b128 v[154:157], v146 offset:1024
	ds_read_b128 v[158:161], v146 offset:2048
	ds_read_b128 v[146:149], v146 offset:3072
	s_mov_b32 m0, s67
	ds_read_b128 v[190:193], v222 offset:32768
	ds_read_b128 v[194:197], v222 offset:33792
	ds_read_b128 v[198:201], v222 offset:34816
	ds_read_b128 v[202:205], v222 offset:35840
	ds_read_b128 v[206:209], v222 offset:36864
	ds_read_b128 v[186:189], v222 offset:37888
	ds_read_b128 v[182:185], v222 offset:38912
	ds_read_b128 v[178:181], v222 offset:39936
	global_load_lds_dwordx4 v210, s[50:51]
	s_mov_b32 m0, s68
	s_nop 0
	global_load_lds_dwordx4 v214, s[50:51]
	s_waitcnt vmcnt(8)
	s_waitcnt lgkmcnt(0)
	s_barrier
	s_setprio 1
	s_waitcnt lgkmcnt(0)
	v_mfma_i32_16x16x64_i8 v[142:145], v[174:177], v[190:193], v[142:145]
	v_mfma_i32_16x16x64_i8 v[138:141], v[166:169], v[190:193], v[138:141]
	v_mfma_i32_16x16x64_i8 v[126:129], v[174:177], v[198:201], v[126:129]
	v_mfma_i32_16x16x64_i8 v[122:125], v[166:169], v[198:201], v[122:125]
	v_mfma_i32_16x16x64_i8 v[110:113], v[174:177], v[206:209], v[110:113]
	v_mfma_i32_16x16x64_i8 v[106:109], v[166:169], v[206:209], v[106:109]
	v_mfma_i32_16x16x64_i8 v[94:97], v[174:177], v[182:185], v[94:97]
	v_mfma_i32_16x16x64_i8 v[90:93], v[166:169], v[182:185], v[90:93]
	v_mfma_i32_16x16x64_i8 v[142:145], v[170:173], v[194:197], v[142:145]
	v_mfma_i32_16x16x64_i8 v[138:141], v[162:165], v[194:197], v[138:141]
	v_mfma_i32_16x16x64_i8 v[126:129], v[170:173], v[202:205], v[126:129]
	v_mfma_i32_16x16x64_i8 v[122:125], v[162:165], v[202:205], v[122:125]
	v_mfma_i32_16x16x64_i8 v[110:113], v[170:173], v[186:189], v[110:113]
	v_mfma_i32_16x16x64_i8 v[106:109], v[162:165], v[186:189], v[106:109]
	v_mfma_i32_16x16x64_i8 v[94:97], v[170:173], v[178:181], v[94:97]
	v_mfma_i32_16x16x64_i8 v[90:93], v[162:165], v[178:181], v[90:93]
	s_setprio 0
	s_setprio 1
	v_mfma_i32_16x16x64_i8 v[134:137], v[150:153], v[190:193], v[134:137]
	v_mfma_i32_16x16x64_i8 v[130:133], v[158:161], v[190:193], v[130:133]
	v_mfma_i32_16x16x64_i8 v[118:121], v[150:153], v[198:201], v[118:121]
	v_mfma_i32_16x16x64_i8 v[114:117], v[158:161], v[198:201], v[114:117]
	v_mfma_i32_16x16x64_i8 v[102:105], v[150:153], v[206:209], v[102:105]
	v_mfma_i32_16x16x64_i8 v[98:101], v[158:161], v[206:209], v[98:101]
	v_mfma_i32_16x16x64_i8 v[86:89], v[150:153], v[182:185], v[86:89]
	v_mfma_i32_16x16x64_i8 v[82:85], v[158:161], v[182:185], v[82:85]
	v_mfma_i32_16x16x64_i8 v[134:137], v[154:157], v[194:197], v[134:137]
	v_mfma_i32_16x16x64_i8 v[130:133], v[146:149], v[194:197], v[130:133]
	v_mfma_i32_16x16x64_i8 v[118:121], v[154:157], v[202:205], v[118:121]
	v_mfma_i32_16x16x64_i8 v[114:117], v[146:149], v[202:205], v[114:117]
	v_mfma_i32_16x16x64_i8 v[102:105], v[154:157], v[186:189], v[102:105]
	v_mfma_i32_16x16x64_i8 v[98:101], v[146:149], v[186:189], v[98:101]
	v_mfma_i32_16x16x64_i8 v[86:89], v[154:157], v[178:181], v[86:89]
	v_mfma_i32_16x16x64_i8 v[82:85], v[146:149], v[178:181], v[82:85]
	s_setprio 0
	s_barrier
	s_mov_b32 m0, s83
	v_lshl_add_u64 v[224:225], v[242:243], 0, s[36:37]
	ds_read_b128 v[206:209], v222 offset:49152
	ds_read_b128 v[202:205], v222 offset:50176
	ds_read_b128 v[194:197], v222 offset:51200
	ds_read_b128 v[198:201], v222 offset:52224
	ds_read_b128 v[186:189], v222 offset:53248
	ds_read_b128 v[190:193], v222 offset:54272
	ds_read_b128 v[182:185], v222 offset:55296
	ds_read_b128 v[178:181], v222 offset:56320
	global_load_lds_dwordx4 v[224:225], off
	v_lshl_add_u64 v[224:225], v[244:245], 0, s[36:37]
	s_mov_b32 m0, s3
	s_nop 0
	global_load_lds_dwordx4 v[224:225], off
	s_mov_b32 m0, s89
	s_nop 0
	global_load_lds_dwordx4 v212, s[0:1]
	s_mov_b32 m0, s88
	s_nop 0
	global_load_lds_dwordx4 v216, s[0:1]
	v_lshl_add_u64 v[224:225], v[246:247], 0, s[36:37]
	s_mov_b32 m0, s72
	s_nop 0
	global_load_lds_dwordx4 v[224:225], off
	v_lshl_add_u64 v[224:225], v[248:249], 0, s[36:37]
	s_mov_b32 m0, s73
	s_nop 0
	global_load_lds_dwordx4 v[224:225], off
	s_waitcnt vmcnt(8)
	s_cbranch_scc1 .LBB0_135
	s_branch .LBB0_135

; __device__ __forceinline__ unsigned xb_ld(unsigned* p)              { return __hip_atomic_load(p, __ATOMIC_RELAXED, __HIP_MEMORY_SCOPE_AGENT); }
; #define XB_SPIN(cond, bar) do { unsigned _sp = 0; while (cond) { __builtin_amdgcn_s_sleep(1); \
;     if ((++_sp & 255u) == 0u) { if (xb_ld(&(bar)[XB_TMO])) break; if (_sp > XB_SPIN_CAP) { atomicAdd(&(bar)[XB_TMO], 1u); break; } } } } while (0)
; __device__ __forceinline__ void xcd_barrier(const XcdBarrier& b) {
;     ...
;         } else {
;             XB_SPIN(xb_ld(&bar[XB_XGEN(b.x)]) == gen, bar);
;             __builtin_amdgcn_fence(__ATOMIC_ACQUIRE, "agent");
;             asm volatile("s_waitcnt vmcnt(0)" ::: "memory");
;         }
;     }
;     __syncthreads();
.LBB0_334:
	s_or_b64 exec, exec, s[0:1]
	s_waitcnt lgkmcnt(0)
	s_barrier
	s_nop 0
	s_nop 0
	s_nop 0
	s_nop 0
	s_nop 0
	s_nop 0
	s_nop 0
	s_nop 0
	s_nop 0
	s_nop 0
	s_nop 0
	s_nop 0
	s_nop 0
	s_nop 0

; #define TIDX opq((int)threadIdx.x)
; #define PG8_STAGE(bufoff, gbase, voff) do { _Pragma("unroll") for (int _i = 0; _i < 2; ++_i) \
;         __builtin_amdgcn_global_load_lds((const unsigned*)((const char*)(gbase) + (voff)[_i]), (PG8_LAS unsigned*)(lds + (bufoff) + ldsw + _i * 8192), 16, 0, 0); } while (0)
; #define PG8_WAIT_V(n) asm volatile("s_waitcnt vmcnt(" #n ")" ::: "memory")
; #define PG8_BAR __builtin_amdgcn_s_barrier()
; template <class Epi, class Sched, class Gemm, bool ALIGN_EPI = false, bool SP2 = false>
; __device__ __forceinline__ void gemm_phase(PG8_LAS unsigned char* lds, const Gemm g, const Sched& S, const Epi& E) {
;     const int tid = TIDX, wid = __builtin_amdgcn_readfirstlane(tid >> 6), lane = tid & 63, wr = wid >> 2, wc = wid & 3, fr = lane & 15, fq = lane >> 4;
;     constexpr int K = Gemm::K, nt = K / BK, lda = Gemm::lda, ldb = Gemm::ldb;
;     constexpr int BP = epi_bperm<Epi>::value;
;     unsigned voffA[2], voffB[2], voffB1[2];
; #pragma unroll
;     for (int i = 0; i < 2; ++i) { int R, C; stage_rc(tid * 16 + i * 8192, R, C);
;         voffA[i] = (unsigned)(R * lda + C) * 2u;
;         if constexpr (BP == 2) { const int w_ = R >> 5, n_ = (R >> 4) & 1, j_ = R & 15, cb_ = w_ * 64 + 16 * (j_ >> 2) + 4 * n_ + (j_ & 3);
;             voffB[i] = (unsigned)(cb_ * ldb + C) * 2u; voffB1[i] = voffB[i]; }
;         else { const int Rb = (BP == 1) ? ((R & ~31) + perm32(R & 31)) : R; voffB[i] = (unsigned)(Rb * ldb + C) * 2u; voffB1[i] = voffB[i]; } }
;     const size_t kstep = (size_t)(BK * 2);
;     const size_t hstepA = (size_t)HALF * lda * 2, hstepB = (size_t)HALF * ldb * 2, hB1 = (BP == 2) ? (size_t)8 * ldb * 2 : hstepB;
;     const size_t tstepA = 2 * hstepA, tstepB = 2 * hstepB;
;     const unsigned ldsw = (unsigned)wid * 1024u;
;     const int aoff = lds_byte(wr * 64 + fr, fq * 8), boff = lds_byte(wc * 32 + fr, fq * 8);
;     ...
;     if constexpr (SP2) {
;         PG8_STAGE(PG8_SB(0, 0), cB, voffB); PG8_STAGE(PG8_SB(0, 1), cB + hB1, voffB1); PG8_STAGE(PG8_SA(0, 0), cA, voffA); PG8_STAGE(PG8_SA(0, 1), cA + hstepA, voffA);
;         if (wr == 1) PG8_BAR;
;         PG8_WAIT_V(2); PG8_BAR;
;         PG8_STAGE(PG8_SB(1, 0), cB + kstep, voffB); PG8_STAGE(PG8_SA(1, 0), cA + kstep, voffA); PG8_STAGE(PG8_SB(1, 1), cB + hB1 + kstep, voffB1);
;         PG8_WAIT_V(6); PG8_BAR;
.LBB0_1182:
	s_and_b32 s22, s16, 3
	s_lshl_b32 s50, s17, 6
	s_lshl_b32 s24, s17, 13
	s_lshl_b32 s26, s22, 12
	s_add_u32 s16, s14, 0x1dd08000
	s_addc_u32 s17, s15, 0
	s_add_u32 s14, s14, 0x1dd28000
	s_mov_b64 s[18:19], 0x80
	s_addc_u32 s15, s15, 0
	s_add_i32 m0, s39, 0x18000
	v_lshl_add_u64 v[8:9], v[8:9], 0, s[18:19]
	s_waitcnt vmcnt(2)
	s_barrier
	global_load_lds_dwordx4 v[8:9], off
	v_lshl_add_u64 v[6:7], v[6:7], 0, s[18:19]
	s_add_i32 m0, s39, 0x1a000
	s_add_i32 s51, s39, 0x8000
	s_add_i32 s52, s39, 0xa000
	global_load_lds_dwordx4 v[6:7], off
	v_lshl_add_u64 v[2:3], v[2:3], 0, s[18:19]
	s_mov_b32 m0, s51
	s_add_u32 s20, s0, 0x2080
	global_load_lds_dwordx4 v[2:3], off
	v_lshl_add_u64 v[2:3], v[4:5], 0, s[18:19]
	s_mov_b32 m0, s52
	s_addc_u32 s21, s1, 0
	global_load_lds_dwordx4 v[2:3], off
	s_add_i32 m0, s39, 0x1c000
	v_lshl_add_u64 v[2:3], s[20:21], 0, v[148:149]
	global_load_lds_dwordx4 v148, s[20:21]
	v_lshl_add_u64 v[2:3], s[20:21], 0, v[152:153]
	s_add_i32 m0, s39, 0x1e000
	v_bfe_u32 v179, v10, 4, 2
	global_load_lds_dwordx4 v152, s[20:21]
	v_and_b32_e32 v1, 15, v10
	v_lshlrev_b32_e32 v2, 4, v179
	v_lshlrev_b32_e32 v3, 2, v10
	v_lshl_or_b32 v2, v1, 6, v2
	v_and_b32_e32 v3, 32, v3
	v_bitop3_b32 v4, v2, s24, v3 bitop3:0xde
	v_bitop3_b32 v181, v2, s26, v3 bitop3:0xde
	v_lshlrev_b32_e32 v2, 13, v14
	v_and_b32_e32 v2, 0xffffc000, v2
	v_lshl_add_u32 v2, v15, 10, v2
	v_and_b32_e32 v3, 1, v14
	v_lshl_or_b32 v2, v3, 6, v2
	v_lshl_add_u32 v156, v16, 1, v2
	v_lshlrev_b32_e32 v2, 13, v11
	v_and_b32_e32 v2, 0xffffc000, v2
	s_waitcnt vmcnt(6)
	s_cmpk_lt_u32 s5, 0x100
	v_lshl_add_u32 v2, v12, 10, v2
	v_and_b32_e32 v3, 1, v11
	s_cselect_b64 s[20:21], -1, 0
	v_lshl_or_b32 v2, v3, 6, v2
	s_add_i32 s55, 0, 0x10000
	s_add_i32 s56, 0, 0x14000
	s_sext_i32_i8 s59, s4
	s_lshl_b32 s53, s22, 6
	s_ashr_i32 s54, s23, 31
	v_mov_b32_e32 v157, v155
	v_lshl_add_u32 v158, v13, 1, v2
	v_mov_b32_e32 v159, v155
	v_mov_b64_e32 v[252:253], 0x800
	v_add_u32_e32 v183, s55, v181
	v_add_u32_e32 v185, s56, v181
	v_add_u32_e32 v187, 0, v4
	s_mov_b32 s22, 0xbfb8aa3b
	s_movk_i32 s57, 0x2200
	s_mov_b32 s24, 0x4b000000
	s_mov_b32 s26, 0x437f0000
	s_mov_b32 s58, 0xc0c0400
	s_barrier
	s_waitcnt vmcnt(0)
	s_nop 0
	s_branch .LBB0_1185

; #define PG8_STAGE(bufoff, gbase, voff) do { _Pragma("unroll") for (int _i = 0; _i < 2; ++_i) \
;         __builtin_amdgcn_global_load_lds((const unsigned*)((const char*)(gbase) + (voff)[_i]), (PG8_LAS unsigned*)(lds + (bufoff) + ldsw + _i * 8192), 16, 0, 0); } while (0)
; #define PG8_LDA(dst, b, h) do { _Pragma("unroll") for (int m = 0; m < 4; ++m) _Pragma("unroll") for (int k = 0; k < 2; ++k) dst[m][k] = *(const PG8_LAS bf16x8*)(lds + PG8_SA(b, h) + aoff + m * 2048 + k * 1024); } while (0)
; #define PG8_WAIT_V(n) asm volatile("s_waitcnt vmcnt(" #n ")" ::: "memory")
; template <class Epi, class Sched, class Gemm, bool ALIGN_EPI = false, bool SP2 = false>
; __device__ __forceinline__ void gemm_phase(PG8_LAS unsigned char* lds, const Gemm g, const Sched& S, const Epi& E) {
;     ...
;         for (int t = 0; t < nt; t += 2) {
;             const bool last = (t == nt - 2);
;             const char* a1 = cA + (size_t)(t + 1) * kstep;
;             const char* a2 = last ? nA : cA + (size_t)(t + 2) * kstep; const char* b2 = last ? nB : cB + (size_t)(t + 2) * kstep;
;             const char* a3 = a2 + kstep; const char* b3 = b2 + kstep;
;             if (last && has_next) S.a_ready(nxt);
;             if constexpr (SP2) {
;             PG8_LDB(B0, 0, 0); PG8_LDB(B1, 0, 1); PG8_SCHED; PG8_LDA(At, 0, 0); PG8_STAGE(PG8_SA(1, 1), a1 + hstepA, voffA);
;             PG8_WAIT_V(8); PG8_WAIT_L(0); PG8_BAR; PG8_MMA(0, 0, At, B0); PG8_MMA(0, 1, At, B1); PG8_BAR; PG8_SCHED;
;             PG8_LDA(At, 0, 1); PG8_STAGE(PG8_SB(0, 0), b2, voffB); PG8_STAGE(PG8_SB(0, 1), b2 + hB1, voffB1); PG8_STAGE(PG8_SA(0, 0), a2, voffA);
;             PG8_WAIT_V(8); PG8_WAIT_L(0); PG8_BAR; PG8_MMA(1, 0, At, B0); PG8_MMA(1, 1, At, B1); PG8_BAR; PG8_SCHED;
;             PG8_LDB(B0, 1, 0); PG8_LDB(B1, 1, 1); PG8_SCHED; PG8_LDA(At, 1, 0); PG8_STAGE(PG8_SA(0, 1), a2 + hstepA, voffA);
;             PG8_WAIT_V(8); PG8_WAIT_L(0); PG8_BAR; PG8_MMA(0, 0, At, B0); PG8_MMA(0, 1, At, B1); PG8_BAR; PG8_SCHED;
;             PG8_LDA(At, 1, 1); PG8_STAGE(PG8_SB(1, 0), b3, voffB); PG8_STAGE(PG8_SB(1, 1), b3 + hB1, voffB1); PG8_STAGE(PG8_SA(1, 0), a3, voffA);
;             PG8_WAIT_V(8);
;             if constexpr (epi_pre<Epi>::value) { if (last) E.pre(pre, cur, wr, wc, lane); }
;             PG8_WAIT_L(0); PG8_BAR; PG8_MMA(1, 0, At, B0); PG8_MMA(1, 1, At, B1); PG8_BAR; PG8_SCHED;
.LBB0_1192:
	ds_read_b128 v[172:175], v183
	ds_read_b128 v[188:191], v183 offset:1024
	ds_read_b128 v[192:195], v183 offset:2048
	ds_read_b128 v[196:199], v183 offset:3072
	ds_read_b128 v[134:137], v185
	ds_read_b128 v[138:141], v185 offset:1024
	ds_read_b128 v[142:145], v185 offset:2048
	ds_read_b128 v[130:133], v185 offset:3072
	s_add_u32 s2, s0, 0xfffe0080
	s_addc_u32 s3, s1, -1
	s_cmp_eq_u32 s64, 4
	s_cselect_b32 s3, s31, s3
	s_cselect_b32 s2, s60, s2
	s_cselect_b32 s41, s29, s63
	s_cselect_b32 s40, s61, s62
	s_add_i32 m0, s39, 0xc000
	ds_read_b128 v[164:167], v187
	ds_read_b128 v[168:171], v187 offset:1024
	ds_read_b128 v[200:203], v187 offset:2048
	ds_read_b128 v[204:207], v187 offset:3072
	ds_read_b128 v[208:211], v187 offset:4096
	ds_read_b128 v[212:215], v187 offset:5120
	ds_read_b128 v[216:219], v187 offset:6144
	ds_read_b128 v[220:223], v187 offset:7168
	global_load_lds_dwordx4 v158, s[0:1]
	v_lshl_add_u64 v[160:161], s[0:1], 0, v[156:157]
	s_add_i32 m0, s39, 0xe000
	s_nop 0
	global_load_lds_dwordx4 v156, s[0:1]
	s_cbranch_vccnz .Lfw_0
	s_waitcnt vmcnt(8)
.Lfw_0:
	s_waitcnt lgkmcnt(0)
	s_barrier
	s_setprio 1
	s_waitcnt lgkmcnt(0)
	v_mfma_i32_16x16x64_i8 v[224:227], v[172:175], v[164:167], v[126:129]
	v_mfma_i32_16x16x64_i8 v[126:129], v[188:191], v[168:171], v[224:227]
	v_mfma_i32_16x16x64_i8 v[228:231], v[192:195], v[164:167], v[122:125]
	v_mfma_i32_16x16x64_i8 v[232:235], v[172:175], v[200:203], v[110:113]
	v_mfma_i32_16x16x64_i8 v[236:239], v[192:195], v[200:203], v[106:109]
	v_mfma_i32_16x16x64_i8 v[240:243], v[172:175], v[208:211], v[94:97]
	v_mfma_i32_16x16x64_i8 v[244:247], v[192:195], v[208:211], v[90:93]
	v_mfma_i32_16x16x64_i8 v[224:227], v[172:175], v[216:219], v[78:81]
	v_mfma_i32_16x16x64_i8 v[74:77], v[192:195], v[216:219], v[74:77]
	v_mfma_i32_16x16x64_i8 v[122:125], v[196:199], v[168:171], v[228:231]
	v_mfma_i32_16x16x64_i8 v[110:113], v[188:191], v[204:207], v[232:235]
	v_mfma_i32_16x16x64_i8 v[106:109], v[196:199], v[204:207], v[236:239]
	v_mfma_i32_16x16x64_i8 v[94:97], v[188:191], v[212:215], v[240:243]
	v_mfma_i32_16x16x64_i8 v[90:93], v[196:199], v[212:215], v[244:247]
	v_mfma_i32_16x16x64_i8 v[78:81], v[188:191], v[220:223], v[224:227]
	v_mfma_i32_16x16x64_i8 v[74:77], v[196:199], v[220:223], v[74:77]
	s_setprio 0
	s_setprio 1
	v_mfma_i32_16x16x64_i8 v[224:227], v[134:137], v[164:167], v[118:121]
	v_mfma_i32_16x16x64_i8 v[118:121], v[138:141], v[168:171], v[224:227]
	v_mfma_i32_16x16x64_i8 v[228:231], v[142:145], v[164:167], v[114:117]
	v_mfma_i32_16x16x64_i8 v[232:235], v[134:137], v[200:203], v[102:105]
	v_mfma_i32_16x16x64_i8 v[236:239], v[142:145], v[200:203], v[98:101]
	v_mfma_i32_16x16x64_i8 v[240:243], v[134:137], v[208:211], v[86:89]
	v_mfma_i32_16x16x64_i8 v[244:247], v[142:145], v[208:211], v[82:85]
	v_mfma_i32_16x16x64_i8 v[164:167], v[134:137], v[216:219], v[70:73]
	v_mfma_i32_16x16x64_i8 v[66:69], v[142:145], v[216:219], v[66:69]
	v_mfma_i32_16x16x64_i8 v[114:117], v[130:133], v[168:171], v[228:231]
	v_mfma_i32_16x16x64_i8 v[102:105], v[138:141], v[204:207], v[232:235]
	v_mfma_i32_16x16x64_i8 v[98:101], v[130:133], v[204:207], v[236:239]
	v_mfma_i32_16x16x64_i8 v[86:89], v[138:141], v[212:215], v[240:243]
	v_mfma_i32_16x16x64_i8 v[82:85], v[130:133], v[212:215], v[244:247]
	v_mfma_i32_16x16x64_i8 v[70:73], v[138:141], v[220:223], v[164:167]
	v_mfma_i32_16x16x64_i8 v[66:69], v[130:133], v[220:223], v[66:69]
	s_setprio 0
	s_barrier
	s_add_i32 s65, s55, s33
	v_lshl_add_u64 v[164:165], s[40:41], 0, v[148:149]
	s_mov_b32 m0, s65
	ds_read_b128 v[200:203], v187 offset:16384
	ds_read_b128 v[204:207], v187 offset:17408
	ds_read_b128 v[208:211], v187 offset:18432
	ds_read_b128 v[212:215], v187 offset:19456
	ds_read_b128 v[216:219], v187 offset:20480
	ds_read_b128 v[220:223], v187 offset:21504
	ds_read_b128 v[224:227], v187 offset:22528
	ds_read_b128 v[228:231], v187 offset:23552
	global_load_lds_dwordx4 v148, s[40:41]
	s_add_i32 m0, s65, 0x2000
	s_add_u32 s66, s40, 0x2000
	v_lshl_add_u64 v[166:167], s[40:41], 0, v[152:153]
	s_addc_u32 s67, s41, 0
	s_add_i32 s65, s56, s33
	global_load_lds_dwordx4 v152, s[40:41]
	s_mov_b32 m0, s65
	v_lshl_add_u64 v[168:169], s[2:3], 0, v[146:147]
	global_load_lds_dwordx4 v148, s[66:67]
	v_lshl_add_u64 v[160:161], s[66:67], 0, v[152:153]
	s_add_i32 m0, s65, 0x2000
	v_lshl_add_u64 v[170:171], s[2:3], 0, v[150:151]
	global_load_lds_dwordx4 v152, s[66:67]
	s_mov_b32 m0, s39
	s_nop 0
	global_load_lds_dwordx4 v146, s[2:3]
	s_mov_b32 m0, s46
	s_nop 0
	global_load_lds_dwordx4 v150, s[2:3]
	s_cbranch_vccnz .Lfw_1
	s_waitcnt vmcnt(8)
; #define PG8_STAGE(bufoff, gbase, voff) do { _Pragma("unroll") for (int _i = 0; _i < 2; ++_i) \
;         __builtin_amdgcn_global_load_lds((const unsigned*)((const char*)(gbase) + (voff)[_i]), (PG8_LAS unsigned*)(lds + (bufoff) + ldsw + _i * 8192), 16, 0, 0); } while (0)
; #define PG8_LDA(dst, b, h) do { _Pragma("unroll") for (int m = 0; m < 4; ++m) _Pragma("unroll") for (int k = 0; k < 2; ++k) dst[m][k] = *(const PG8_LAS bf16x8*)(lds + PG8_SA(b, h) + aoff + m * 2048 + k * 1024); } while (0)
; #define PG8_WAIT_V(n) asm volatile("s_waitcnt vmcnt(" #n ")" ::: "memory")
; template <class Epi, class Sched, class Gemm, bool ALIGN_EPI = false, bool SP2 = false>
; __device__ __forceinline__ void gemm_phase(PG8_LAS unsigned char* lds, const Gemm g, const Sched& S, const Epi& E) {
;     ...
;         for (int t = 0; t < nt; t += 2) {
;             const bool last = (t == nt - 2);
;             const char* a1 = cA + (size_t)(t + 1) * kstep;
;             const char* a2 = last ? nA : cA + (size_t)(t + 2) * kstep; const char* b2 = last ? nB : cB + (size_t)(t + 2) * kstep;
;             const char* a3 = a2 + kstep; const char* b3 = b2 + kstep;
;             if (last && has_next) S.a_ready(nxt);
;             if constexpr (SP2) {
;             PG8_LDB(B0, 0, 0); PG8_LDB(B1, 0, 1); PG8_SCHED; PG8_LDA(At, 0, 0); PG8_STAGE(PG8_SA(1, 1), a1 + hstepA, voffA);
;             PG8_WAIT_V(8); PG8_WAIT_L(0); PG8_BAR; PG8_MMA(0, 0, At, B0); PG8_MMA(0, 1, At, B1); PG8_BAR; PG8_SCHED;
;             PG8_LDA(At, 0, 1); PG8_STAGE(PG8_SB(0, 0), b2, voffB); PG8_STAGE(PG8_SB(0, 1), b2 + hB1, voffB1); PG8_STAGE(PG8_SA(0, 0), a2, voffA);
;             PG8_WAIT_V(8); PG8_WAIT_L(0); PG8_BAR; PG8_MMA(1, 0, At, B0); PG8_MMA(1, 1, At, B1); PG8_BAR; PG8_SCHED;
;             PG8_LDB(B0, 1, 0); PG8_LDB(B1, 1, 1); PG8_SCHED; PG8_LDA(At, 1, 0); PG8_STAGE(PG8_SA(0, 1), a2 + hstepA, voffA);
;             PG8_WAIT_V(8); PG8_WAIT_L(0); PG8_BAR; PG8_MMA(0, 0, At, B0); PG8_MMA(0, 1, At, B1); PG8_BAR; PG8_SCHED;
;             PG8_LDA(At, 1, 1); PG8_STAGE(PG8_SB(1, 0), b3, voffB); PG8_STAGE(PG8_SB(1, 1), b3 + hB1, voffB1); PG8_STAGE(PG8_SA(1, 0), a3, voffA);
;             PG8_WAIT_V(8);
;             if constexpr (epi_pre<Epi>::value) { if (last) E.pre(pre, cur, wr, wc, lane); }
;             PG8_WAIT_L(0); PG8_BAR; PG8_MMA(1, 0, At, B0); PG8_MMA(1, 1, At, B1); PG8_BAR; PG8_SCHED;
.Lfw_1:
	s_waitcnt lgkmcnt(0)
	s_barrier
	s_setprio 1
	s_waitcnt lgkmcnt(0)
	v_mfma_i32_16x16x64_i8 v[232:235], v[172:175], v[200:203], v[62:65]
	v_mfma_i32_16x16x64_i8 v[62:65], v[188:191], v[204:207], v[232:235]
	v_mfma_i32_16x16x64_i8 v[236:239], v[192:195], v[200:203], v[58:61]
	v_mfma_i32_16x16x64_i8 v[240:243], v[172:175], v[208:211], v[46:49]
	v_mfma_i32_16x16x64_i8 v[244:247], v[192:195], v[208:211], v[42:45]
	v_mfma_i32_16x16x64_i8 v[248:251], v[172:175], v[216:219], v[30:33]
	v_mfma_i32_16x16x64_i8 v[160:163], v[192:195], v[216:219], v[26:29]
	v_mfma_i32_16x16x64_i8 v[232:235], v[172:175], v[224:227], v[14:17]
	v_mfma_i32_16x16x64_i8 v[10:13], v[192:195], v[224:227], v[10:13]
	v_mfma_i32_16x16x64_i8 v[58:61], v[196:199], v[204:207], v[236:239]
	v_mfma_i32_16x16x64_i8 v[46:49], v[188:191], v[212:215], v[240:243]
	v_mfma_i32_16x16x64_i8 v[42:45], v[196:199], v[212:215], v[244:247]
	v_mfma_i32_16x16x64_i8 v[30:33], v[188:191], v[220:223], v[248:251]
	v_mfma_i32_16x16x64_i8 v[26:29], v[196:199], v[220:223], v[160:163]
	v_mfma_i32_16x16x64_i8 v[14:17], v[188:191], v[228:231], v[232:235]
	v_mfma_i32_16x16x64_i8 v[10:13], v[196:199], v[228:231], v[10:13]
	s_setprio 0
	s_setprio 1
	v_mfma_i32_16x16x64_i8 v[160:163], v[134:137], v[200:203], v[54:57]
	v_mfma_i32_16x16x64_i8 v[54:57], v[138:141], v[204:207], v[160:163]
	v_mfma_i32_16x16x64_i8 v[172:175], v[142:145], v[200:203], v[50:53]
	v_mfma_i32_16x16x64_i8 v[188:191], v[134:137], v[208:211], v[38:41]
	v_mfma_i32_16x16x64_i8 v[192:195], v[142:145], v[208:211], v[34:37]
	v_mfma_i32_16x16x64_i8 v[196:199], v[134:137], v[216:219], v[22:25]
	v_mfma_i32_16x16x64_i8 v[232:235], v[142:145], v[216:219], v[18:21]
	v_mfma_i32_16x16x64_i8 v[160:163], v[134:137], v[224:227], v[6:9]
	v_mfma_i32_16x16x64_i8 v[2:5], v[142:145], v[224:227], v[2:5]
	v_mfma_i32_16x16x64_i8 v[50:53], v[130:133], v[204:207], v[172:175]
	v_mfma_i32_16x16x64_i8 v[38:41], v[138:141], v[212:215], v[188:191]
	v_mfma_i32_16x16x64_i8 v[34:37], v[130:133], v[212:215], v[192:195]
	v_mfma_i32_16x16x64_i8 v[22:25], v[138:141], v[220:223], v[196:199]
	v_mfma_i32_16x16x64_i8 v[18:21], v[130:133], v[220:223], v[232:235]
	v_mfma_i32_16x16x64_i8 v[6:9], v[138:141], v[228:231], v[160:163]
	v_mfma_i32_16x16x64_i8 v[2:5], v[130:133], v[228:231], v[2:5]
	s_setprio 0
	s_barrier
	s_add_i32 s65, 0, 0x18000
	s_add_i32 s66, 0, 0x1c000
	v_add_u32_e32 v130, s65, v181
	v_add_u32_e32 v131, s66, v181
	ds_read_b128 v[160:163], v130
	ds_read_b128 v[172:175], v130 offset:1024
	ds_read_b128 v[188:191], v130 offset:2048
	ds_read_b128 v[192:195], v130 offset:3072
	ds_read_b128 v[134:137], v131
	ds_read_b128 v[138:141], v131 offset:1024
	ds_read_b128 v[142:145], v131 offset:2048
	ds_read_b128 v[130:133], v131 offset:3072
	s_add_u32 s2, s2, 0x20000
	s_addc_u32 s3, s3, 0
	s_mov_b32 m0, s47
	ds_read_b128 v[196:199], v187 offset:32768
	ds_read_b128 v[200:203], v187 offset:33792
	ds_read_b128 v[204:207], v187 offset:34816
	ds_read_b128 v[208:211], v187 offset:35840
	ds_read_b128 v[212:215], v187 offset:36864
	ds_read_b128 v[216:219], v187 offset:37888
	ds_read_b128 v[220:223], v187 offset:38912
	ds_read_b128 v[224:227], v187 offset:39936
	global_load_lds_dwordx4 v146, s[2:3]
	v_lshl_add_u64 v[176:177], s[2:3], 0, v[150:151]
	s_mov_b32 m0, s48
	s_nop 0
	global_load_lds_dwordx4 v150, s[2:3]
	s_waitcnt vmcnt(8)
	s_waitcnt lgkmcnt(0)
	s_barrier
	s_setprio 1
	s_waitcnt lgkmcnt(0)
	v_mfma_i32_16x16x64_i8 v[228:231], v[160:163], v[196:199], v[126:129]
	v_mfma_i32_16x16x64_i8 v[126:129], v[172:175], v[200:203], v[228:231]
	v_mfma_i32_16x16x64_i8 v[232:235], v[188:191], v[196:199], v[122:125]
	v_mfma_i32_16x16x64_i8 v[236:239], v[160:163], v[204:207], v[110:113]
	v_mfma_i32_16x16x64_i8 v[240:243], v[188:191], v[204:207], v[106:109]
	v_mfma_i32_16x16x64_i8 v[244:247], v[160:163], v[212:215], v[94:97]
	v_mfma_i32_16x16x64_i8 v[248:251], v[188:191], v[212:215], v[90:93]
	v_mfma_i32_16x16x64_i8 v[228:231], v[160:163], v[220:223], v[78:81]
	v_mfma_i32_16x16x64_i8 v[74:77], v[188:191], v[220:223], v[74:77]
	v_mfma_i32_16x16x64_i8 v[122:125], v[192:195], v[200:203], v[232:235]
	v_mfma_i32_16x16x64_i8 v[110:113], v[172:175], v[208:211], v[236:239]
	v_mfma_i32_16x16x64_i8 v[106:109], v[192:195], v[208:211], v[240:243]
	v_mfma_i32_16x16x64_i8 v[94:97], v[172:175], v[216:219], v[244:247]
	v_mfma_i32_16x16x64_i8 v[90:93], v[192:195], v[216:219], v[248:251]
	v_mfma_i32_16x16x64_i8 v[78:81], v[172:175], v[224:227], v[228:231]
	v_mfma_i32_16x16x64_i8 v[74:77], v[192:195], v[224:227], v[74:77]
	s_setprio 0
	s_setprio 1
	v_mfma_i32_16x16x64_i8 v[228:231], v[134:137], v[196:199], v[118:121]
	v_mfma_i32_16x16x64_i8 v[118:121], v[138:141], v[200:203], v[228:231]
	v_mfma_i32_16x16x64_i8 v[232:235], v[142:145], v[196:199], v[114:117]
	v_mfma_i32_16x16x64_i8 v[236:239], v[134:137], v[204:207], v[102:105]
	v_mfma_i32_16x16x64_i8 v[240:243], v[142:145], v[204:207], v[98:101]
	v_mfma_i32_16x16x64_i8 v[244:247], v[134:137], v[212:215], v[86:89]
	v_mfma_i32_16x16x64_i8 v[248:251], v[142:145], v[212:215], v[82:85]
	v_mfma_i32_16x16x64_i8 v[196:199], v[134:137], v[220:223], v[70:73]
	v_mfma_i32_16x16x64_i8 v[66:69], v[142:145], v[220:223], v[66:69]
	v_mfma_i32_16x16x64_i8 v[114:117], v[130:133], v[200:203], v[232:235]
	v_mfma_i32_16x16x64_i8 v[102:105], v[138:141], v[208:211], v[236:239]
	v_mfma_i32_16x16x64_i8 v[98:101], v[130:133], v[208:211], v[240:243]
	v_mfma_i32_16x16x64_i8 v[86:89], v[138:141], v[216:219], v[244:247]
	v_mfma_i32_16x16x64_i8 v[82:85], v[130:133], v[216:219], v[248:251]
	v_mfma_i32_16x16x64_i8 v[70:73], v[138:141], v[224:227], v[196:199]
	v_mfma_i32_16x16x64_i8 v[66:69], v[130:133], v[224:227], v[66:69]
	s_setprio 0
	s_barrier
; #define PG8_STAGE(bufoff, gbase, voff) do { _Pragma("unroll") for (int _i = 0; _i < 2; ++_i) \
;         __builtin_amdgcn_global_load_lds((const unsigned*)((const char*)(gbase) + (voff)[_i]), (PG8_LAS unsigned*)(lds + (bufoff) + ldsw + _i * 8192), 16, 0, 0); } while (0)
; #define PG8_LDA(dst, b, h) do { _Pragma("unroll") for (int m = 0; m < 4; ++m) _Pragma("unroll") for (int k = 0; k < 2; ++k) dst[m][k] = *(const PG8_LAS bf16x8*)(lds + PG8_SA(b, h) + aoff + m * 2048 + k * 1024); } while (0)
; #define PG8_WAIT_V(n) asm volatile("s_waitcnt vmcnt(" #n ")" ::: "memory")
; template <class Epi, class Sched, class Gemm, bool ALIGN_EPI = false, bool SP2 = false>
; __device__ __forceinline__ void gemm_phase(PG8_LAS unsigned char* lds, const Gemm g, const Sched& S, const Epi& E) {
;     ...
;         for (int t = 0; t < nt; t += 2) {
;             const bool last = (t == nt - 2);
;             const char* a1 = cA + (size_t)(t + 1) * kstep;
;             const char* a2 = last ? nA : cA + (size_t)(t + 2) * kstep; const char* b2 = last ? nB : cB + (size_t)(t + 2) * kstep;
;             const char* a3 = a2 + kstep; const char* b3 = b2 + kstep;
;             if (last && has_next) S.a_ready(nxt);
;             if constexpr (SP2) {
;             PG8_LDB(B0, 0, 0); PG8_LDB(B1, 0, 1); PG8_SCHED; PG8_LDA(At, 0, 0); PG8_STAGE(PG8_SA(1, 1), a1 + hstepA, voffA);
;             PG8_WAIT_V(8); PG8_WAIT_L(0); PG8_BAR; PG8_MMA(0, 0, At, B0); PG8_MMA(0, 1, At, B1); PG8_BAR; PG8_SCHED;
;             PG8_LDA(At, 0, 1); PG8_STAGE(PG8_SB(0, 0), b2, voffB); PG8_STAGE(PG8_SB(0, 1), b2 + hB1, voffB1); PG8_STAGE(PG8_SA(0, 0), a2, voffA);
;             PG8_WAIT_V(8); PG8_WAIT_L(0); PG8_BAR; PG8_MMA(1, 0, At, B0); PG8_MMA(1, 1, At, B1); PG8_BAR; PG8_SCHED;
;             PG8_LDB(B0, 1, 0); PG8_LDB(B1, 1, 1); PG8_SCHED; PG8_LDA(At, 1, 0); PG8_STAGE(PG8_SA(0, 1), a2 + hstepA, voffA);
;             PG8_WAIT_V(8); PG8_WAIT_L(0); PG8_BAR; PG8_MMA(0, 0, At, B0); PG8_MMA(0, 1, At, B1); PG8_BAR; PG8_SCHED;
;             PG8_LDA(At, 1, 1); PG8_STAGE(PG8_SB(1, 0), b3, voffB); PG8_STAGE(PG8_SB(1, 1), b3 + hB1, voffB1); PG8_STAGE(PG8_SA(1, 0), a3, voffA);
;             PG8_WAIT_V(8);
;             if constexpr (epi_pre<Epi>::value) { if (last) E.pre(pre, cur, wr, wc, lane); }
;             PG8_WAIT_L(0); PG8_BAR; PG8_MMA(1, 0, At, B0); PG8_MMA(1, 1, At, B1); PG8_BAR; PG8_SCHED;
	s_add_i32 s2, s65, s33
	v_lshl_add_u64 v[164:165], v[164:165], 0, s[18:19]
	s_mov_b32 m0, s2
	ds_read_b128 v[196:199], v187 offset:49152
	ds_read_b128 v[200:203], v187 offset:50176
	ds_read_b128 v[204:207], v187 offset:51200
	ds_read_b128 v[208:211], v187 offset:52224
	ds_read_b128 v[212:215], v187 offset:53248
	ds_read_b128 v[216:219], v187 offset:54272
	ds_read_b128 v[220:223], v187 offset:55296
	ds_read_b128 v[224:227], v187 offset:56320
	global_load_lds_dwordx4 v[164:165], off
	s_add_i32 m0, s2, 0x2000
	s_add_u32 s2, s40, 0x2080
	v_lshl_add_u64 v[164:165], v[166:167], 0, s[18:19]
	s_addc_u32 s3, s41, 0
	s_add_i32 s40, s66, s33
	global_load_lds_dwordx4 v[164:165], off
	s_mov_b32 m0, s40
	s_nop 0
	global_load_lds_dwordx4 v148, s[2:3]
	s_add_i32 m0, s40, 0x2000
	s_nop 0
	global_load_lds_dwordx4 v152, s[2:3]
	v_lshl_add_u64 v[164:165], v[168:169], 0, s[18:19]
	s_mov_b32 m0, s51
	s_nop 0
	global_load_lds_dwordx4 v[164:165], off
	v_lshl_add_u64 v[164:165], v[170:171], 0, s[18:19]
	s_mov_b32 m0, s52
	s_nop 0
	global_load_lds_dwordx4 v[164:165], off
	s_waitcnt vmcnt(8)
	s_waitcnt lgkmcnt(0)
	s_barrier
	s_setprio 1
	s_waitcnt lgkmcnt(0)
	v_mfma_i32_16x16x64_i8 v[164:167], v[160:163], v[196:199], v[62:65]
	v_mfma_i32_16x16x64_i8 v[62:65], v[172:175], v[200:203], v[164:167]
	v_mfma_i32_16x16x64_i8 v[168:171], v[188:191], v[196:199], v[58:61]
	v_mfma_i32_16x16x64_i8 v[228:231], v[160:163], v[204:207], v[46:49]
	v_mfma_i32_16x16x64_i8 v[232:235], v[188:191], v[204:207], v[42:45]
	v_mfma_i32_16x16x64_i8 v[236:239], v[160:163], v[212:215], v[30:33]
	v_mfma_i32_16x16x64_i8 v[240:243], v[188:191], v[212:215], v[26:29]
	v_mfma_i32_16x16x64_i8 v[164:167], v[160:163], v[220:223], v[14:17]
	v_mfma_i32_16x16x64_i8 v[10:13], v[188:191], v[220:223], v[10:13]
	v_mfma_i32_16x16x64_i8 v[58:61], v[192:195], v[200:203], v[168:171]
	v_mfma_i32_16x16x64_i8 v[46:49], v[172:175], v[208:211], v[228:231]
	v_mfma_i32_16x16x64_i8 v[42:45], v[192:195], v[208:211], v[232:235]
	v_mfma_i32_16x16x64_i8 v[30:33], v[172:175], v[216:219], v[236:239]
	v_mfma_i32_16x16x64_i8 v[26:29], v[192:195], v[216:219], v[240:243]
	v_mfma_i32_16x16x64_i8 v[14:17], v[172:175], v[224:227], v[164:167]
	v_mfma_i32_16x16x64_i8 v[10:13], v[192:195], v[224:227], v[10:13]
	s_setprio 0
	s_setprio 1
	v_mfma_i32_16x16x64_i8 v[160:163], v[134:137], v[196:199], v[54:57]
	v_mfma_i32_16x16x64_i8 v[54:57], v[138:141], v[200:203], v[160:163]
	v_mfma_i32_16x16x64_i8 v[164:167], v[142:145], v[196:199], v[50:53]
	v_mfma_i32_16x16x64_i8 v[168:171], v[134:137], v[204:207], v[38:41]
	v_mfma_i32_16x16x64_i8 v[172:175], v[142:145], v[204:207], v[34:37]
	v_mfma_i32_16x16x64_i8 v[188:191], v[134:137], v[212:215], v[22:25]
	v_mfma_i32_16x16x64_i8 v[192:195], v[142:145], v[212:215], v[18:21]
	v_mfma_i32_16x16x64_i8 v[160:163], v[134:137], v[220:223], v[6:9]
	v_mfma_i32_16x16x64_i8 v[2:5], v[142:145], v[220:223], v[2:5]
	v_mfma_i32_16x16x64_i8 v[50:53], v[130:133], v[200:203], v[164:167]
	v_mfma_i32_16x16x64_i8 v[38:41], v[138:141], v[208:211], v[168:171]
	v_mfma_i32_16x16x64_i8 v[34:37], v[130:133], v[208:211], v[172:175]
	v_mfma_i32_16x16x64_i8 v[22:25], v[138:141], v[216:219], v[188:191]
	v_mfma_i32_16x16x64_i8 v[18:21], v[130:133], v[216:219], v[192:195]
	v_mfma_i32_16x16x64_i8 v[6:9], v[138:141], v[224:227], v[160:163]
	v_mfma_i32_16x16x64_i8 v[2:5], v[130:133], v[224:227], v[2:5]
	s_setprio 0
	s_barrier
	s_add_i32 s64, s64, 2
	s_add_u32 s62, s62, 0x100
	s_addc_u32 s63, s63, 0
	s_add_u32 s0, s0, 0x100
	s_addc_u32 s1, s1, 0
	s_cmp_gt_u32 s64, 5
	s_mov_b64 vcc, 0
	s_cbranch_scc0 .LBB0_1192
;     __device__ __forceinline__ void operator()(const f32x4 (&acc)[2][2][4][2], const Unit& u, int wr, int wc, int fr, int fq) const {
;         asm volatile("" : "+v"(fr), "+v"(fq));
;         const int row0 = u.pm * BM + wr * 64 + fr, col0 = u.pn * BM + wc * 64 + 16 * fq;
;         const int gn = u.pn >> 2, gbase = (gn < 3) ? 3072 + 1024 * gn : 0;
;         f32x4 bv[2][2];
; #pragma unroll
;         for (int bj = 0; bj < 2; ++bj)
; #pragma unroll
;             for (int n = 0; n < 2; ++n) bv[bj][n] = *(const f32x4*)(bias + col0 + 8 * bj + 4 * n) * -1.44269504f;
;         f32x4 wv[2][2];
; #pragma unroll
;         for (int bj = 0; bj < 2; ++bj)
; #pragma unroll
;             for (int n = 0; n < 2; ++n) wv[bj][n] = *(const f32x4*)(SW + col0 + 8 * bj + 4 * n) * -1.44269504f;
;         float rsv[8];
; #pragma unroll
;         for (int i = 0; i < 8; ++i) rsv[i] = SH[row0 + (i >> 2) * HALF + (i & 3) * 16];
;     ...
; #pragma unroll
;         for (int ai = 0; ai < 2; ++ai)
; #pragma unroll
;             for (int m = 0; m < 4; ++m) { unsigned char* rowp = O + (size_t)(row0 + ai * HALF + m * 16) * 8704 + gbase + (col0 & 1023);
;                 const float rs = rsv[ai * 4 + m];
;                 u32x4 w; EPG_Q4(w.x, acc[ai][0][m][0], wv[0][0], rs, bv[0][0]); EPG_Q4(w.y, acc[ai][0][m][1], wv[0][1], rs, bv[0][1]);
;                 EPG_Q4(w.z, acc[ai][1][m][0], wv[1][0], rs, bv[1][0]); EPG_Q4(w.w, acc[ai][1][m][1], wv[1][1], rs, bv[1][1]);
	s_lshl_b32 s0, s59, 8
	v_mov_b32_e32 v130, v179
	v_mov_b32_e32 v154, v1
	s_or_b32 s0, s0, s53
	v_cvt_f32_i32_e32 v212, v122
	v_lshl_add_u32 v144, v130, 4, s0
	s_lshl_b32 s0, s38, 8
	v_ashrrev_i32_e32 v145, 31, v144
	s_add_i32 s0, s0, s50
	v_lshlrev_b64 v[142:143], 2, v[144:145]
	v_add_u32_e32 v164, s0, v154
	v_lshl_add_u64 v[160:161], s[10:11], 0, v[142:143]
	v_ashrrev_i32_e32 v165, 31, v164
	global_load_dwordx4 v[130:133], v[160:161], off
	global_load_dwordx4 v[134:137], v[160:161], off offset:16
	global_load_dwordx4 v[138:141], v[160:161], off offset:32
	s_nop 0
	global_load_dwordx4 v[160:163], v[160:161], off offset:48
	v_lshl_add_u64 v[142:143], s[14:15], 0, v[142:143]
	v_lshl_add_u64 v[170:171], v[164:165], 2, s[16:17]
	global_load_dwordx4 v[166:169], v[142:143], off
	global_load_dwordx4 v[194:197], v[142:143], off offset:16
	global_load_dwordx4 v[198:201], v[142:143], off offset:32
	global_load_dwordx4 v[202:205], v[142:143], off offset:48
	global_load_dword v206, v[170:171], off
	global_load_dword v188, v[170:171], off offset:64
	global_load_dword v186, v[170:171], off offset:128
	global_load_dword v184, v[170:171], off offset:192
	global_load_dword v182, v[170:171], off offset:512
	global_load_dword v180, v[170:171], off offset:576
	global_load_dword v178, v[170:171], off offset:640
	global_load_dword v122, v[170:171], off offset:704
	s_ashr_i32 s0, s59, 2
	s_lshl_b32 s1, s0, 10
	v_mov_b64_e32 v[142:143], s[12:13]
	s_add_i32 s2, s1, 0xc00
	v_cvt_f32_i32_e32 v209, v127
	v_cvt_f32_i32_e32 v208, v126
	v_cvt_f32_i32_e32 v215, v125
	v_cvt_f32_i32_e32 v214, v124
	s_cmp_lt_i32 s0, 3
	v_mad_i64_i32 v[124:125], s[0:1], v164, s57, v[142:143]
	s_cselect_b32 s0, s2, 0
	v_cvt_f32_i32_e32 v211, v129
	v_cvt_f32_i32_e32 v210, v128
	s_ashr_i32 s1, s0, 31
	v_cvt_f32_i32_e32 v115, v115
	v_cvt_f32_i32_e32 v114, v114
	v_cvt_f32_i32_e32 v99, v99
	v_cvt_f32_i32_e32 v98, v98
	v_cvt_f32_i32_e32 v83, v83
	v_cvt_f32_i32_e32 v82, v82
	v_cvt_f32_i32_e32 v67, v67
	v_cvt_f32_i32_e32 v66, v66
	v_cvt_f32_i32_e32 v51, v51
	v_cvt_f32_i32_e32 v50, v50
	v_cvt_f32_i32_e32 v35, v35
	v_cvt_f32_i32_e32 v34, v34
	v_cvt_f32_i32_e32 v19, v19
	v_cvt_f32_i32_e32 v18, v18
	v_and_b32_e32 v154, 0x3f0, v144
	v_lshl_add_u64 v[124:125], v[124:125], 0, s[0:1]
	v_cvt_f32_i32_e32 v117, v117
	v_cvt_f32_i32_e32 v116, v116
	v_cvt_f32_i32_e32 v111, v111
	v_cvt_f32_i32_e32 v110, v110
	v_cvt_f32_i32_e32 v101, v101
	v_cvt_f32_i32_e32 v100, v100
	v_cvt_f32_i32_e32 v95, v95
	v_cvt_f32_i32_e32 v94, v94
	v_cvt_f32_i32_e32 v85, v85
	v_cvt_f32_i32_e32 v84, v84
	v_cvt_f32_i32_e32 v79, v79
	v_cvt_f32_i32_e32 v78, v78
	v_cvt_f32_i32_e32 v69, v69
	v_cvt_f32_i32_e32 v68, v68
	v_cvt_f32_i32_e32 v63, v63
	v_cvt_f32_i32_e32 v62, v62
	v_cvt_f32_i32_e32 v53, v53
	v_cvt_f32_i32_e32 v52, v52
	v_cvt_f32_i32_e32 v47, v47
	v_cvt_f32_i32_e32 v46, v46
	v_cvt_f32_i32_e32 v37, v37
	v_cvt_f32_i32_e32 v36, v36
	v_cvt_f32_i32_e32 v31, v31
	v_cvt_f32_i32_e32 v30, v30
	v_cvt_f32_i32_e32 v21, v21
	v_cvt_f32_i32_e32 v20, v20
	v_cvt_f32_i32_e32 v15, v15
	v_cvt_f32_i32_e32 v14, v14
	v_add_u32_e32 v207, 32, v164
	v_lshl_add_u64 v[216:217], v[124:125], 0, v[154:155]
	v_add_u32_e32 v189, 0xa0, v164
	v_cvt_f32_i32_e32 v213, v123
	v_add_u32_e32 v123, 0xb0, v164
	v_cvt_f32_i32_e32 v119, v119
	v_cvt_f32_i32_e32 v118, v118
	v_cvt_f32_i32_e32 v109, v109
	v_cvt_f32_i32_e32 v108, v108
	v_cvt_f32_i32_e32 v103, v103
	v_cvt_f32_i32_e32 v102, v102
	v_cvt_f32_i32_e32 v93, v93
	v_cvt_f32_i32_e32 v121, v121
	v_cvt_f32_i32_e32 v120, v120
	v_cvt_f32_i32_e32 v113, v113
	v_cvt_f32_i32_e32 v112, v112
	v_cvt_f32_i32_e32 v107, v107
	v_cvt_f32_i32_e32 v106, v106
	v_cvt_f32_i32_e32 v105, v105
	v_cvt_f32_i32_e32 v104, v104
	v_cvt_f32_i32_e32 v92, v92
	v_cvt_f32_i32_e32 v87, v87
	v_cvt_f32_i32_e32 v86, v86
	v_cvt_f32_i32_e32 v97, v97
	v_cvt_f32_i32_e32 v96, v96
	v_cvt_f32_i32_e32 v91, v91
	v_cvt_f32_i32_e32 v90, v90
	v_cvt_f32_i32_e32 v89, v89
	v_cvt_f32_i32_e32 v88, v88
	v_cvt_f32_i32_e32 v77, v77
	v_cvt_f32_i32_e32 v76, v76
	v_cvt_f32_i32_e32 v71, v71
	v_cvt_f32_i32_e32 v70, v70
	v_cvt_f32_i32_e32 v81, v81
	v_cvt_f32_i32_e32 v80, v80
	v_cvt_f32_i32_e32 v75, v75
	v_cvt_f32_i32_e32 v74, v74
	v_cvt_f32_i32_e32 v73, v73
	v_cvt_f32_i32_e32 v72, v72
	v_cvt_f32_i32_e32 v61, v61
	v_cvt_f32_i32_e32 v60, v60
	v_cvt_f32_i32_e32 v55, v55
	v_cvt_f32_i32_e32 v54, v54
	v_cvt_f32_i32_e32 v65, v65
	v_cvt_f32_i32_e32 v64, v64
	v_cvt_f32_i32_e32 v59, v59
	v_cvt_f32_i32_e32 v58, v58
	v_cvt_f32_i32_e32 v57, v57
	v_cvt_f32_i32_e32 v56, v56
	v_cvt_f32_i32_e32 v45, v45
	v_cvt_f32_i32_e32 v44, v44
	v_cvt_f32_i32_e32 v39, v39
	v_cvt_f32_i32_e32 v38, v38
	v_cvt_f32_i32_e32 v49, v49
	v_cvt_f32_i32_e32 v48, v48
	v_cvt_f32_i32_e32 v43, v43
	v_cvt_f32_i32_e32 v42, v42
	v_cvt_f32_i32_e32 v41, v41
	v_cvt_f32_i32_e32 v40, v40
	v_cvt_f32_i32_e32 v29, v29
	v_cvt_f32_i32_e32 v28, v28
	v_cvt_f32_i32_e32 v23, v23
	v_cvt_f32_i32_e32 v22, v22
	v_cvt_f32_i32_e32 v33, v33
	v_cvt_f32_i32_e32 v32, v32
	v_cvt_f32_i32_e32 v27, v27
	v_cvt_f32_i32_e32 v26, v26
	v_cvt_f32_i32_e32 v25, v25
	v_cvt_f32_i32_e32 v24, v24
	v_cvt_f32_i32_e32 v7, v7
	v_cvt_f32_i32_e32 v6, v6
	v_cvt_f32_i32_e32 v3, v3
	v_cvt_f32_i32_e32 v2, v2
	v_cvt_f32_i32_e32 v17, v17
	v_cvt_f32_i32_e32 v16, v16
	v_cvt_f32_i32_e32 v11, v11
	v_cvt_f32_i32_e32 v13, v13
	v_cvt_f32_i32_e32 v12, v12
	v_cvt_f32_i32_e32 v10, v10
	v_cvt_f32_i32_e32 v9, v9
	v_cvt_f32_i32_e32 v8, v8
	v_cvt_f32_i32_e32 v5, v5
	v_cvt_f32_i32_e32 v4, v4
	s_and_b64 vcc, exec, s[20:21]
	s_cbranch_vccz .LBB0_1195
	s_barrier

; __device__ __forceinline__ unsigned xb_ld(unsigned* p)              { return __hip_atomic_load(p, __ATOMIC_RELAXED, __HIP_MEMORY_SCOPE_AGENT); }
; #define XB_SPIN(cond, bar) do { unsigned _sp = 0; while (cond) { __builtin_amdgcn_s_sleep(1); \
;     if ((++_sp & 255u) == 0u) { if (xb_ld(&(bar)[XB_TMO])) break; if (_sp > XB_SPIN_CAP) { atomicAdd(&(bar)[XB_TMO], 1u); break; } } } } while (0)
; __device__ __forceinline__ void xcd_barrier(const XcdBarrier& b) {
;     ...
;         } else {
;             XB_SPIN(xb_ld(&bar[XB_XGEN(b.x)]) == gen, bar);
;             __builtin_amdgcn_fence(__ATOMIC_ACQUIRE, "agent");
;             asm volatile("s_waitcnt vmcnt(0)" ::: "memory");
;         }
;     }
;     __syncthreads();
.LBB0_1252:
	s_or_b64 exec, exec, s[0:1]
	s_waitcnt lgkmcnt(0)
	s_barrier
	s_nop 0
	s_nop 0
	s_nop 0
	s_nop 0
	s_nop 0
	s_nop 0
	s_nop 0
	s_nop 0
	s_nop 0
	s_nop 0

; #define TIDX opq((int)threadIdx.x)
; template <class Epi, class Sched, class Gemm, bool ALIGN_EPI = false, bool SP2 = false>
; __device__ __forceinline__ void gemm_phase(PG8_LAS unsigned char* lds, const Gemm g, const Sched& S, const Epi& E) {
;     const int tid = TIDX, wid = __builtin_amdgcn_readfirstlane(tid >> 6), lane = tid & 63, wr = wid >> 2, wc = wid & 3, fr = lane & 15, fq = lane >> 4;
;     constexpr int K = Gemm::K, nt = K / BK, lda = Gemm::lda, ldb = Gemm::ldb;
;     constexpr int BP = epi_bperm<Epi>::value;
;     unsigned voffA[2], voffB[2], voffB1[2];
; #pragma unroll
;     for (int i = 0; i < 2; ++i) { int R, C; stage_rc(tid * 16 + i * 8192, R, C);
;         voffA[i] = (unsigned)(R * lda + C) * 2u;
;         if constexpr (BP == 2) { const int w_ = R >> 5, n_ = (R >> 4) & 1, j_ = R & 15, cb_ = w_ * 64 + 16 * (j_ >> 2) + 4 * n_ + (j_ & 3);
;             voffB[i] = (unsigned)(cb_ * ldb + C) * 2u; voffB1[i] = voffB[i]; }
;         else { const int Rb = (BP == 1) ? ((R & ~31) + perm32(R & 31)) : R; voffB[i] = (unsigned)(Rb * ldb + C) * 2u; voffB1[i] = voffB[i]; } }
;     const size_t kstep = (size_t)(BK * 2);
;     const size_t hstepA = (size_t)HALF * lda * 2, hstepB = (size_t)HALF * ldb * 2, hB1 = (BP == 2) ? (size_t)8 * ldb * 2 : hstepB;
;     ...
;     Unit cur, nxt; int ui = 0;
;     if (!S.next(0, cur)) return;
;     typename epi_pre<Epi>::Pre pre;
;     f32x4 acc[2][2][4][2];
; #pragma unroll
;     for (int a = 0; a < 2; ++a)
; #pragma unroll
;         for (int b = 0; b < 2; ++b)
; #pragma unroll
;             for (int m = 0; m < 4; ++m)
; #pragma unroll
;                 for (int n = 0; n < 2; ++n) acc[a][b][m][n] = (f32x4){0.f, 0.f, 0.f, 0.f};
;     bf16x8 At[4][2], B0[2][2], B1[2][2];
;     const char* cA = (const char*)g.A + (size_t)cur.pm * tstepA + (size_t)cur.sub * g.a_sub; const char* cB = (const char*)g.Bt + (size_t)cur.pn * tstepB + (size_t)cur.sub * g.b_sub;
;     S.a_ready(cur);
;     if constexpr (SP2) {
;         PG8_STAGE(PG8_SB(0, 0), cB, voffB); PG8_STAGE(PG8_SB(0, 1), cB + hB1, voffB1); PG8_STAGE(PG8_SA(0, 0), cA, voffA); PG8_STAGE(PG8_SA(0, 1), cA + hstepA, voffA);
;         if (wr == 1) PG8_BAR;
;         PG8_WAIT_V(2); PG8_BAR;
;         PG8_STAGE(PG8_SB(1, 0), cB + kstep, voffB); PG8_STAGE(PG8_SA(1, 0), cA + kstep, voffA); PG8_STAGE(PG8_SB(1, 1), cB + hB1 + kstep, voffB1);
;         PG8_WAIT_V(6); PG8_BAR;
.LBB0_1263:
	s_add_u32 s12, s2, 0x2b28000
	s_addc_u32 s13, s3, 0
	s_add_u32 s14, s2, 0x6b28000
	s_addc_u32 s15, s3, 0
	s_add_u32 s54, s2, 0xc000
	s_mov_b64 s[16:17], 0x80
	s_addc_u32 s55, s3, 0
	s_and_b32 s1, s4, 3
	s_add_i32 m0, s50, 0x18000
	v_lshl_add_u64 v[10:11], v[10:11], 0, s[16:17]
	s_lshl_b32 s56, s5, 6
	s_lshl_b32 s4, s5, 13
	s_lshl_b32 s5, s1, 12
	s_waitcnt vmcnt(2)
	s_barrier
	global_load_lds_dwordx4 v[10:11], off
	v_lshl_add_u64 v[8:9], v[8:9], 0, s[16:17]
	s_add_i32 m0, s50, 0x1a000
	s_add_i32 s57, s50, 0x8000
	s_add_i32 s58, s50, 0xa000
	global_load_lds_dwordx4 v[8:9], off
	v_lshl_add_u64 v[4:5], v[4:5], 0, s[16:17]
	s_mov_b32 m0, s57
	s_add_u32 s2, s28, 0x1080
	global_load_lds_dwordx4 v[4:5], off
	v_lshl_add_u64 v[4:5], v[6:7], 0, s[16:17]
	s_mov_b32 m0, s58
	s_addc_u32 s3, s29, 0
	global_load_lds_dwordx4 v[4:5], off
	s_add_i32 m0, s50, 0x1c000
	v_lshl_add_u64 v[4:5], s[2:3], 0, v[168:169]
	global_load_lds_dwordx4 v168, s[2:3]
	v_lshl_add_u64 v[4:5], s[2:3], 0, v[172:173]
	s_add_i32 m0, s50, 0x1e000
	v_bfe_u32 v181, v2, 4, 2
	global_load_lds_dwordx4 v172, s[2:3]
	v_and_b32_e32 v1, 15, v2
	v_lshlrev_b32_e32 v4, 4, v181
	v_lshlrev_b32_e32 v2, 2, v2
	v_lshl_or_b32 v4, v1, 6, v4
	v_and_b32_e32 v2, 32, v2
	v_bitop3_b32 v6, v4, s4, v2 bitop3:0xde
	v_bitop3_b32 v184, v4, s5, v2 bitop3:0xde
	s_waitcnt vmcnt(6)
	v_mov_b32_e32 v4, v3
	v_mov_b32_e32 v5, v3
	s_cmpk_lt_u32 s18, 0x100
	v_mov_b32_e32 v2, v3
	v_add_u32_e32 v185, 0, v6
	v_mov_b64_e32 v[24:25], v[4:5]
	v_mov_b64_e32 v[84:85], v[4:5]
	v_mov_b64_e32 v[16:17], v[4:5]
	v_mov_b64_e32 v[40:41], v[4:5]
	v_mov_b64_e32 v[12:13], v[4:5]
	v_mov_b64_e32 v[56:57], v[4:5]
	v_mov_b64_e32 v[8:9], v[4:5]
	v_mov_b64_e32 v[44:45], v[4:5]
	v_mov_b64_e32 v[108:109], v[4:5]
	v_mov_b64_e32 v[120:121], v[4:5]
	v_mov_b64_e32 v[96:97], v[4:5]
	v_mov_b64_e32 v[68:69], v[4:5]
	v_mov_b64_e32 v[88:89], v[4:5]
	v_mov_b64_e32 v[100:101], v[4:5]
	v_mov_b64_e32 v[60:61], v[4:5]
	v_mov_b64_e32 v[72:73], v[4:5]
	v_mov_b64_e32 v[28:29], v[4:5]
	v_mov_b64_e32 v[92:93], v[4:5]
	v_mov_b64_e32 v[20:21], v[4:5]
	v_mov_b64_e32 v[48:49], v[4:5]
	v_mov_b64_e32 v[36:37], v[4:5]
	v_mov_b64_e32 v[112:113], v[4:5]
	v_mov_b64_e32 v[32:33], v[4:5]
	v_mov_b64_e32 v[52:53], v[4:5]
	v_mov_b64_e32 v[116:117], v[4:5]
	v_mov_b64_e32 v[124:125], v[4:5]
	v_mov_b64_e32 v[104:105], v[4:5]
	v_mov_b64_e32 v[76:77], v[4:5]
	v_mov_b64_e32 v[128:129], v[4:5]
	v_mov_b64_e32 v[132:133], v[4:5]
	v_mov_b64_e32 v[64:65], v[4:5]
	v_mov_b64_e32 v[80:81], v[4:5]
	s_cselect_b64 s[18:19], -1, 0
	s_lshl_b32 s59, s1, 6
	s_ashr_i32 s60, s33, 31
	s_mov_b32 s7, 0
	v_mov_b64_e32 v[174:175], 0x200
	v_mov_b64_e32 v[176:177], 0x1ff
	s_add_i32 s61, 0, 0x10000
	s_add_i32 s62, 0, 0x14000
	s_movk_i32 s63, 0x2200
	s_movk_i32 s64, 0xe200
	v_mov_b64_e32 v[22:23], v[2:3]
	v_mov_b64_e32 v[82:83], v[2:3]
	v_mov_b64_e32 v[14:15], v[2:3]
	v_mov_b64_e32 v[38:39], v[2:3]
	v_mov_b64_e32 v[10:11], v[2:3]
	v_mov_b64_e32 v[54:55], v[2:3]
	v_mov_b64_e32 v[6:7], v[2:3]
	v_mov_b64_e32 v[42:43], v[2:3]
	v_mov_b64_e32 v[106:107], v[2:3]
	v_mov_b64_e32 v[118:119], v[2:3]
	v_mov_b64_e32 v[94:95], v[2:3]
	v_mov_b64_e32 v[66:67], v[2:3]
	v_mov_b64_e32 v[86:87], v[2:3]
	v_mov_b64_e32 v[98:99], v[2:3]
	v_mov_b64_e32 v[58:59], v[2:3]
	v_mov_b64_e32 v[70:71], v[2:3]
	v_mov_b64_e32 v[26:27], v[2:3]
	v_mov_b64_e32 v[90:91], v[2:3]
	v_mov_b64_e32 v[18:19], v[2:3]
	v_mov_b64_e32 v[46:47], v[2:3]
	v_mov_b64_e32 v[34:35], v[2:3]
	v_mov_b64_e32 v[110:111], v[2:3]
	v_mov_b64_e32 v[30:31], v[2:3]
	v_mov_b64_e32 v[50:51], v[2:3]
	v_mov_b64_e32 v[114:115], v[2:3]
	v_mov_b64_e32 v[122:123], v[2:3]
	v_mov_b64_e32 v[102:103], v[2:3]
	v_mov_b64_e32 v[74:75], v[2:3]
	v_mov_b64_e32 v[126:127], v[2:3]
	v_mov_b64_e32 v[130:131], v[2:3]
	v_mov_b64_e32 v[62:63], v[2:3]
	v_mov_b64_e32 v[78:79], v[2:3]
	s_mov_b32 s65, 0
	s_barrier
	s_branch .LBB0_1266

; #define PG8_STAGE(bufoff, gbase, voff) do { _Pragma("unroll") for (int _i = 0; _i < 2; ++_i) \
;         __builtin_amdgcn_global_load_lds((const unsigned*)((const char*)(gbase) + (voff)[_i]), (PG8_LAS unsigned*)(lds + (bufoff) + ldsw + _i * 8192), 16, 0, 0); } while (0)
; #define PG8_LDA(dst, b, h) do { _Pragma("unroll") for (int m = 0; m < 4; ++m) _Pragma("unroll") for (int k = 0; k < 2; ++k) dst[m][k] = *(const PG8_LAS bf16x8*)(lds + PG8_SA(b, h) + aoff + m * 2048 + k * 1024); } while (0)
; #define PG8_WAIT_V(n) asm volatile("s_waitcnt vmcnt(" #n ")" ::: "memory")
; template <class Epi, class Sched, class Gemm, bool ALIGN_EPI = false, bool SP2 = false>
; __device__ __forceinline__ void gemm_phase(PG8_LAS unsigned char* lds, const Gemm g, const Sched& S, const Epi& E) {
;     ...
;         for (int t = 0; t < nt; t += 2) {
;             const bool last = (t == nt - 2);
;             const char* a1 = cA + (size_t)(t + 1) * kstep;
;             const char* a2 = last ? nA : cA + (size_t)(t + 2) * kstep; const char* b2 = last ? nB : cB + (size_t)(t + 2) * kstep;
;             const char* a3 = a2 + kstep; const char* b3 = b2 + kstep;
;             if (last && has_next) S.a_ready(nxt);
;             if constexpr (SP2) {
;             PG8_LDB(B0, 0, 0); PG8_LDB(B1, 0, 1); PG8_SCHED; PG8_LDA(At, 0, 0); PG8_STAGE(PG8_SA(1, 1), a1 + hstepA, voffA);
;             PG8_WAIT_V(8); PG8_WAIT_L(0); PG8_BAR; PG8_MMA(0, 0, At, B0); PG8_MMA(0, 1, At, B1); PG8_BAR; PG8_SCHED;
;             PG8_LDA(At, 0, 1); PG8_STAGE(PG8_SB(0, 0), b2, voffB); PG8_STAGE(PG8_SB(0, 1), b2 + hB1, voffB1); PG8_STAGE(PG8_SA(0, 0), a2, voffA);
;             PG8_WAIT_V(8); PG8_WAIT_L(0); PG8_BAR; PG8_MMA(1, 0, At, B0); PG8_MMA(1, 1, At, B1); PG8_BAR; PG8_SCHED;
;             PG8_LDB(B0, 1, 0); PG8_LDB(B1, 1, 1); PG8_SCHED; PG8_LDA(At, 1, 0); PG8_STAGE(PG8_SA(0, 1), a2 + hstepA, voffA);
;             PG8_WAIT_V(8); PG8_WAIT_L(0); PG8_BAR; PG8_MMA(0, 0, At, B0); PG8_MMA(0, 1, At, B1); PG8_BAR; PG8_SCHED;
;             PG8_LDA(At, 1, 1); PG8_STAGE(PG8_SB(1, 0), b3, voffB); PG8_STAGE(PG8_SB(1, 1), b3 + hB1, voffB1); PG8_STAGE(PG8_SA(1, 0), a3, voffA);
;             PG8_WAIT_V(8);
;             if constexpr (epi_pre<Epi>::value) { if (last) E.pre(pre, cur, wr, wc, lane); }
;             PG8_WAIT_L(0); PG8_BAR; PG8_MMA(1, 0, At, B0); PG8_MMA(1, 1, At, B1); PG8_BAR; PG8_SCHED;
.LBB0_1273:
	s_add_u32 s42, s30, s36
	s_addc_u32 s43, s31, s37
	s_add_u32 s40, s42, 0x100
	s_addc_u32 s41, s43, 0
	s_and_b64 s[38:39], s[2:3], exec
	s_cselect_b32 s39, s1, s41
	s_cselect_b32 s38, s23, s40
	s_add_u32 s36, s28, s36
	s_addc_u32 s37, s29, s37
	s_add_u32 s36, s36, 0x100
	s_addc_u32 s37, s37, 0
	s_and_b64 s[2:3], s[2:3], exec
	s_cselect_b32 s41, s21, s37
	s_cselect_b32 s40, s67, s36
	s_add_u32 s74, s42, 0x40080
	s_addc_u32 s75, s43, 0
	s_add_i32 s77, s61, s49
	s_add_i32 m0, s50, 0xc000
	s_add_i32 s76, s50, 0xe000
	s_add_i32 s78, s77, 0x2000
	v_add_u32_e32 v2, s61, v184
	s_add_u32 s42, s40, 0x1000
	ds_read_b128 v[158:161], v2
	ds_read_b128 v[162:165], v2 offset:1024
	ds_read_b128 v[186:189], v2 offset:2048
	ds_read_b128 v[190:193], v2 offset:3072
	v_add_u32_e32 v2, s62, v184
	s_addc_u32 s43, s41, 0
	s_add_i32 s79, s62, s49
	ds_read_b128 v[138:141], v2
	ds_read_b128 v[142:145], v2 offset:1024
	ds_read_b128 v[146:149], v2 offset:2048
	ds_read_b128 v[134:137], v2 offset:3072
	s_add_i32 s80, s79, 0x2000
	s_add_i32 s73, 0, 0x18000
	s_add_i32 s72, 0, 0x1c000
	s_add_u32 s2, s38, 0x40000
	s_addc_u32 s3, s39, 0
	s_add_i32 s69, s73, s49
	s_add_i32 s68, s69, 0x2000
	s_add_u32 s36, s40, 0x1080
	s_addc_u32 s37, s41, 0
	s_add_i32 s71, s72, s49
	s_add_i32 s70, s71, 0x2000
	ds_read_b128 v[150:153], v185
	ds_read_b128 v[154:157], v185 offset:1024
	ds_read_b128 v[194:197], v185 offset:2048
	ds_read_b128 v[198:201], v185 offset:3072
	ds_read_b128 v[202:205], v185 offset:4096
	ds_read_b128 v[206:209], v185 offset:5120
	ds_read_b128 v[210:213], v185 offset:6144
	ds_read_b128 v[214:217], v185 offset:7168
	global_load_lds_dwordx4 v166, s[74:75]
	s_mov_b32 m0, s76
	s_nop 0
	global_load_lds_dwordx4 v170, s[74:75]
	s_waitcnt vmcnt(8)
	s_waitcnt lgkmcnt(0)
	s_barrier
	s_setprio 1
	s_waitcnt lgkmcnt(0)
	v_mfma_f32_16x16x32_bf16 v[218:221], v[158:161], v[150:153], v[78:81]
	v_mfma_f32_16x16x32_bf16 v[78:81], v[162:165], v[154:157], v[218:221]
	v_mfma_f32_16x16x32_bf16 v[222:225], v[186:189], v[150:153], v[62:65]
	v_mfma_f32_16x16x32_bf16 v[226:229], v[158:161], v[194:197], v[130:133]
	v_mfma_f32_16x16x32_bf16 v[230:233], v[186:189], v[194:197], v[126:129]
	v_mfma_f32_16x16x32_bf16 v[234:237], v[158:161], v[202:205], v[74:77]
	v_mfma_f32_16x16x32_bf16 v[238:241], v[186:189], v[202:205], v[102:105]
	v_mfma_f32_16x16x32_bf16 v[218:221], v[158:161], v[210:213], v[122:125]
	v_mfma_f32_16x16x32_bf16 v[114:117], v[186:189], v[210:213], v[114:117]
	v_mfma_f32_16x16x32_bf16 v[62:65], v[190:193], v[154:157], v[222:225]
	v_mfma_f32_16x16x32_bf16 v[130:133], v[162:165], v[198:201], v[226:229]
	v_mfma_f32_16x16x32_bf16 v[126:129], v[190:193], v[198:201], v[230:233]
	v_mfma_f32_16x16x32_bf16 v[74:77], v[162:165], v[206:209], v[234:237]
	v_mfma_f32_16x16x32_bf16 v[102:105], v[190:193], v[206:209], v[238:241]
	v_mfma_f32_16x16x32_bf16 v[122:125], v[162:165], v[214:217], v[218:221]
	v_mfma_f32_16x16x32_bf16 v[114:117], v[190:193], v[214:217], v[114:117]
	s_setprio 0
	s_setprio 1
	v_mfma_f32_16x16x32_bf16 v[218:221], v[138:141], v[150:153], v[50:53]
	v_mfma_f32_16x16x32_bf16 v[50:53], v[142:145], v[154:157], v[218:221]
	v_mfma_f32_16x16x32_bf16 v[222:225], v[146:149], v[150:153], v[30:33]
	v_mfma_f32_16x16x32_bf16 v[226:229], v[138:141], v[194:197], v[110:113]
	v_mfma_f32_16x16x32_bf16 v[230:233], v[146:149], v[194:197], v[34:37]
	v_mfma_f32_16x16x32_bf16 v[234:237], v[138:141], v[202:205], v[46:49]
	v_mfma_f32_16x16x32_bf16 v[238:241], v[146:149], v[202:205], v[18:21]
	v_mfma_f32_16x16x32_bf16 v[150:153], v[138:141], v[210:213], v[90:93]
	v_mfma_f32_16x16x32_bf16 v[26:29], v[146:149], v[210:213], v[26:29]
	v_mfma_f32_16x16x32_bf16 v[30:33], v[134:137], v[154:157], v[222:225]
	v_mfma_f32_16x16x32_bf16 v[110:113], v[142:145], v[198:201], v[226:229]
	v_mfma_f32_16x16x32_bf16 v[34:37], v[134:137], v[198:201], v[230:233]
	v_mfma_f32_16x16x32_bf16 v[46:49], v[142:145], v[206:209], v[234:237]
	v_mfma_f32_16x16x32_bf16 v[18:21], v[134:137], v[206:209], v[238:241]
	v_mfma_f32_16x16x32_bf16 v[90:93], v[142:145], v[214:217], v[150:153]
	v_mfma_f32_16x16x32_bf16 v[26:29], v[134:137], v[214:217], v[26:29]
	s_setprio 0
	s_barrier
	s_mov_b32 m0, s77
	v_lshl_add_u64 v[150:151], s[40:41], 0, v[168:169]
	ds_read_b128 v[194:197], v185 offset:16384
	ds_read_b128 v[198:201], v185 offset:17408
	ds_read_b128 v[202:205], v185 offset:18432
	ds_read_b128 v[206:209], v185 offset:19456
	ds_read_b128 v[210:213], v185 offset:20480
	ds_read_b128 v[214:217], v185 offset:21504
	ds_read_b128 v[218:221], v185 offset:22528
	ds_read_b128 v[222:225], v185 offset:23552
	global_load_lds_dwordx4 v168, s[40:41]
	v_lshl_add_u64 v[152:153], s[40:41], 0, v[172:173]
	s_mov_b32 m0, s78
	v_lshl_add_u64 v[4:5], s[42:43], 0, v[168:169]
	global_load_lds_dwordx4 v172, s[40:41]
	s_mov_b32 m0, s79
	v_lshl_add_u64 v[154:155], s[38:39], 0, v[166:167]
	global_load_lds_dwordx4 v168, s[42:43]
	v_lshl_add_u64 v[4:5], s[42:43], 0, v[172:173]
	s_mov_b32 m0, s80
	v_lshl_add_u64 v[156:157], s[38:39], 0, v[170:171]
	global_load_lds_dwordx4 v172, s[42:43]
	s_mov_b32 m0, s50
	s_nop 0
	global_load_lds_dwordx4 v166, s[38:39]
	s_mov_b32 m0, s51
	s_nop 0
	global_load_lds_dwordx4 v170, s[38:39]
	s_waitcnt vmcnt(8)
	s_waitcnt lgkmcnt(0)
	s_barrier
; #define PG8_STAGE(bufoff, gbase, voff) do { _Pragma("unroll") for (int _i = 0; _i < 2; ++_i) \
;         __builtin_amdgcn_global_load_lds((const unsigned*)((const char*)(gbase) + (voff)[_i]), (PG8_LAS unsigned*)(lds + (bufoff) + ldsw + _i * 8192), 16, 0, 0); } while (0)
; #define PG8_LDA(dst, b, h) do { _Pragma("unroll") for (int m = 0; m < 4; ++m) _Pragma("unroll") for (int k = 0; k < 2; ++k) dst[m][k] = *(const PG8_LAS bf16x8*)(lds + PG8_SA(b, h) + aoff + m * 2048 + k * 1024); } while (0)
; #define PG8_WAIT_V(n) asm volatile("s_waitcnt vmcnt(" #n ")" ::: "memory")
; template <class Epi, class Sched, class Gemm, bool ALIGN_EPI = false, bool SP2 = false>
; __device__ __forceinline__ void gemm_phase(PG8_LAS unsigned char* lds, const Gemm g, const Sched& S, const Epi& E) {
;     ...
;         for (int t = 0; t < nt; t += 2) {
;             const bool last = (t == nt - 2);
;             const char* a1 = cA + (size_t)(t + 1) * kstep;
;             const char* a2 = last ? nA : cA + (size_t)(t + 2) * kstep; const char* b2 = last ? nB : cB + (size_t)(t + 2) * kstep;
;             const char* a3 = a2 + kstep; const char* b3 = b2 + kstep;
;             if (last && has_next) S.a_ready(nxt);
;             if constexpr (SP2) {
;             PG8_LDB(B0, 0, 0); PG8_LDB(B1, 0, 1); PG8_SCHED; PG8_LDA(At, 0, 0); PG8_STAGE(PG8_SA(1, 1), a1 + hstepA, voffA);
;             PG8_WAIT_V(8); PG8_WAIT_L(0); PG8_BAR; PG8_MMA(0, 0, At, B0); PG8_MMA(0, 1, At, B1); PG8_BAR; PG8_SCHED;
;             PG8_LDA(At, 0, 1); PG8_STAGE(PG8_SB(0, 0), b2, voffB); PG8_STAGE(PG8_SB(0, 1), b2 + hB1, voffB1); PG8_STAGE(PG8_SA(0, 0), a2, voffA);
;             PG8_WAIT_V(8); PG8_WAIT_L(0); PG8_BAR; PG8_MMA(1, 0, At, B0); PG8_MMA(1, 1, At, B1); PG8_BAR; PG8_SCHED;
;             PG8_LDB(B0, 1, 0); PG8_LDB(B1, 1, 1); PG8_SCHED; PG8_LDA(At, 1, 0); PG8_STAGE(PG8_SA(0, 1), a2 + hstepA, voffA);
;             PG8_WAIT_V(8); PG8_WAIT_L(0); PG8_BAR; PG8_MMA(0, 0, At, B0); PG8_MMA(0, 1, At, B1); PG8_BAR; PG8_SCHED;
;             PG8_LDA(At, 1, 1); PG8_STAGE(PG8_SB(1, 0), b3, voffB); PG8_STAGE(PG8_SB(1, 1), b3 + hB1, voffB1); PG8_STAGE(PG8_SA(1, 0), a3, voffA);
;             PG8_WAIT_V(8);
;             if constexpr (epi_pre<Epi>::value) { if (last) E.pre(pre, cur, wr, wc, lane); }
;             PG8_WAIT_L(0); PG8_BAR; PG8_MMA(1, 0, At, B0); PG8_MMA(1, 1, At, B1); PG8_BAR; PG8_SCHED;
	s_setprio 1
	s_waitcnt lgkmcnt(0)
	v_mfma_f32_16x16x32_bf16 v[226:229], v[158:161], v[194:197], v[70:73]
	v_mfma_f32_16x16x32_bf16 v[70:73], v[162:165], v[198:201], v[226:229]
	v_mfma_f32_16x16x32_bf16 v[230:233], v[186:189], v[194:197], v[58:61]
	v_mfma_f32_16x16x32_bf16 v[234:237], v[158:161], v[202:205], v[98:101]
	v_mfma_f32_16x16x32_bf16 v[238:241], v[186:189], v[202:205], v[86:89]
	v_mfma_f32_16x16x32_bf16 v[242:245], v[158:161], v[210:213], v[66:69]
	v_mfma_f32_16x16x32_bf16 v[246:249], v[186:189], v[210:213], v[94:97]
	v_mfma_f32_16x16x32_bf16 v[226:229], v[158:161], v[218:221], v[118:121]
	v_mfma_f32_16x16x32_bf16 v[106:109], v[186:189], v[218:221], v[106:109]
	v_mfma_f32_16x16x32_bf16 v[58:61], v[190:193], v[198:201], v[230:233]
	v_mfma_f32_16x16x32_bf16 v[98:101], v[162:165], v[206:209], v[234:237]
	v_mfma_f32_16x16x32_bf16 v[86:89], v[190:193], v[206:209], v[238:241]
	v_mfma_f32_16x16x32_bf16 v[66:69], v[162:165], v[214:217], v[242:245]
	v_mfma_f32_16x16x32_bf16 v[94:97], v[190:193], v[214:217], v[246:249]
	v_mfma_f32_16x16x32_bf16 v[118:121], v[162:165], v[222:225], v[226:229]
	v_mfma_f32_16x16x32_bf16 v[106:109], v[190:193], v[222:225], v[106:109]
	s_setprio 0
	s_setprio 1
	v_mfma_f32_16x16x32_bf16 v[158:161], v[138:141], v[194:197], v[42:45]
	v_mfma_f32_16x16x32_bf16 v[42:45], v[142:145], v[198:201], v[158:161]
	v_mfma_f32_16x16x32_bf16 v[162:165], v[146:149], v[194:197], v[6:9]
	v_mfma_f32_16x16x32_bf16 v[186:189], v[138:141], v[202:205], v[54:57]
	v_mfma_f32_16x16x32_bf16 v[190:193], v[146:149], v[202:205], v[10:13]
	v_mfma_f32_16x16x32_bf16 v[226:229], v[138:141], v[210:213], v[38:41]
	v_mfma_f32_16x16x32_bf16 v[230:233], v[146:149], v[210:213], v[14:17]
	v_mfma_f32_16x16x32_bf16 v[158:161], v[138:141], v[218:221], v[82:85]
	v_mfma_f32_16x16x32_bf16 v[22:25], v[146:149], v[218:221], v[22:25]
	v_mfma_f32_16x16x32_bf16 v[4:7], v[134:137], v[198:201], v[162:165]
	v_mfma_f32_16x16x32_bf16 v[54:57], v[142:145], v[206:209], v[186:189]
	v_mfma_f32_16x16x32_bf16 v[10:13], v[134:137], v[206:209], v[190:193]
	v_mfma_f32_16x16x32_bf16 v[38:41], v[142:145], v[214:217], v[226:229]
	v_mfma_f32_16x16x32_bf16 v[14:17], v[134:137], v[214:217], v[230:233]
	v_mfma_f32_16x16x32_bf16 v[82:85], v[142:145], v[222:225], v[158:161]
	v_mfma_f32_16x16x32_bf16 v[22:25], v[134:137], v[222:225], v[22:25]
	s_setprio 0
	s_barrier
	v_add_u32_e32 v2, s73, v184
	ds_read_b128 v[158:161], v2
	ds_read_b128 v[162:165], v2 offset:1024
	ds_read_b128 v[186:189], v2 offset:2048
	ds_read_b128 v[190:193], v2 offset:3072
	v_add_u32_e32 v2, s72, v184
	ds_read_b128 v[138:141], v2
	ds_read_b128 v[142:145], v2 offset:1024
	ds_read_b128 v[146:149], v2 offset:2048
	ds_read_b128 v[134:137], v2 offset:3072
	s_mov_b32 m0, s52
	ds_read_b128 v[194:197], v185 offset:32768
	ds_read_b128 v[198:201], v185 offset:33792
	ds_read_b128 v[202:205], v185 offset:34816
	ds_read_b128 v[206:209], v185 offset:35840
	ds_read_b128 v[210:213], v185 offset:36864
	ds_read_b128 v[214:217], v185 offset:37888
	ds_read_b128 v[218:221], v185 offset:38912
	ds_read_b128 v[222:225], v185 offset:39936
	global_load_lds_dwordx4 v166, s[2:3]
	s_mov_b32 m0, s53
	s_nop 0
	global_load_lds_dwordx4 v170, s[2:3]
	s_waitcnt vmcnt(8)
	s_waitcnt lgkmcnt(0)
	s_barrier
	s_setprio 1
	s_waitcnt lgkmcnt(0)
	v_mfma_f32_16x16x32_bf16 v[226:229], v[158:161], v[194:197], v[78:81]
	v_mfma_f32_16x16x32_bf16 v[78:81], v[162:165], v[198:201], v[226:229]
	v_mfma_f32_16x16x32_bf16 v[230:233], v[186:189], v[194:197], v[62:65]
	v_mfma_f32_16x16x32_bf16 v[234:237], v[158:161], v[202:205], v[130:133]
	v_mfma_f32_16x16x32_bf16 v[238:241], v[186:189], v[202:205], v[126:129]
	v_mfma_f32_16x16x32_bf16 v[242:245], v[158:161], v[210:213], v[74:77]
	v_mfma_f32_16x16x32_bf16 v[246:249], v[186:189], v[210:213], v[102:105]
	v_mfma_f32_16x16x32_bf16 v[226:229], v[158:161], v[218:221], v[122:125]
	v_mfma_f32_16x16x32_bf16 v[114:117], v[186:189], v[218:221], v[114:117]
	v_mfma_f32_16x16x32_bf16 v[62:65], v[190:193], v[198:201], v[230:233]
	v_mfma_f32_16x16x32_bf16 v[130:133], v[162:165], v[206:209], v[234:237]
	v_mfma_f32_16x16x32_bf16 v[126:129], v[190:193], v[206:209], v[238:241]
	v_mfma_f32_16x16x32_bf16 v[74:77], v[162:165], v[214:217], v[242:245]
	v_mfma_f32_16x16x32_bf16 v[102:105], v[190:193], v[214:217], v[246:249]
	v_mfma_f32_16x16x32_bf16 v[122:125], v[162:165], v[222:225], v[226:229]
	v_mfma_f32_16x16x32_bf16 v[114:117], v[190:193], v[222:225], v[114:117]
	s_setprio 0
	s_setprio 1
	v_mfma_f32_16x16x32_bf16 v[226:229], v[138:141], v[194:197], v[50:53]
	v_mfma_f32_16x16x32_bf16 v[50:53], v[142:145], v[198:201], v[226:229]
	v_mfma_f32_16x16x32_bf16 v[230:233], v[146:149], v[194:197], v[30:33]
	v_mfma_f32_16x16x32_bf16 v[234:237], v[138:141], v[202:205], v[110:113]
	v_mfma_f32_16x16x32_bf16 v[238:241], v[146:149], v[202:205], v[34:37]
	v_mfma_f32_16x16x32_bf16 v[242:245], v[138:141], v[210:213], v[46:49]
	v_mfma_f32_16x16x32_bf16 v[246:249], v[146:149], v[210:213], v[18:21]
	v_mfma_f32_16x16x32_bf16 v[194:197], v[138:141], v[218:221], v[90:93]
	v_mfma_f32_16x16x32_bf16 v[26:29], v[146:149], v[218:221], v[26:29]
	v_mfma_f32_16x16x32_bf16 v[30:33], v[134:137], v[198:201], v[230:233]
	v_mfma_f32_16x16x32_bf16 v[110:113], v[142:145], v[206:209], v[234:237]
	v_mfma_f32_16x16x32_bf16 v[34:37], v[134:137], v[206:209], v[238:241]
	v_mfma_f32_16x16x32_bf16 v[46:49], v[142:145], v[214:217], v[242:245]
	v_mfma_f32_16x16x32_bf16 v[18:21], v[134:137], v[214:217], v[246:249]
	v_mfma_f32_16x16x32_bf16 v[90:93], v[142:145], v[222:225], v[194:197]
	v_mfma_f32_16x16x32_bf16 v[26:29], v[134:137], v[222:225], v[26:29]
	s_setprio 0
	s_barrier
; #define EPC_LOAD(i) do { const unsigned o_ = gbase + EPC_GOFF(i); gq[i] = *(const u32x4*)(MG + (o_ + go)); gr[i] = *(const u32x4*)(nbase + ((o_ + gn) & nmask)); } while (0)
; #define PG8_STAGE(bufoff, gbase, voff) do { _Pragma("unroll") for (int _i = 0; _i < 2; ++_i) \
;         __builtin_amdgcn_global_load_lds((const unsigned*)((const char*)(gbase) + (voff)[_i]), (PG8_LAS unsigned*)(lds + (bufoff) + ldsw + _i * 8192), 16, 0, 0); } while (0)
; #define PG8_WAIT_V(n) asm volatile("s_waitcnt vmcnt(" #n ")" ::: "memory")
; #define PG8_BAR __builtin_amdgcn_s_barrier()
;     __device__ __forceinline__ void chain(f32x4 (&acc)[2][2][4][2], const Unit& u, int wr, int wc, int fr, int fq) const {
;         constexpr int DEPTH = 4;
;     ...
;         asm volatile("" : "+v"(fr), "+v"(fq));
;         const bool last = (u.sub == 3);
;         const unsigned gbase = (unsigned)(u.pm * BM + wr * 64 + fr) * 8704u + (unsigned)(u.pn * BM + wc * 64 + 16 * fq);
;         const unsigned obase = (unsigned)(u.pm * BM + wr * 64 + fr) * 1024u + (unsigned)(u.pn * BM + wc * 64 + 16 * fq);
;         const unsigned go = last ? 0u : 3072u + 1024u * (unsigned)u.sub;
;         const unsigned gn = (u.sub < 2) ? go + 1024u : 0u, nmask = last ? 0u : 0xffffffffu;
;         const unsigned char* nbase = last ? FF : MG;
;         const float keep = last ? 0.f : 1.f;
;         u32x4 gq[8], gr[8];
;     ...
; #pragma unroll
;         for (int i = 0; i < DEPTH; ++i) EPC_LOAD(i);
; template <class Epi, class Sched, class Gemm, bool ALIGN_EPI = false, bool SP2 = false>
; __device__ __forceinline__ void gemm_phase(PG8_LAS unsigned char* lds, const Gemm g, const Sched& S, const Epi& E) {
;     ...
;             PG8_WAIT_V(8); PG8_WAIT_L(0); PG8_BAR; PG8_MMA(1, 0, At, B0); PG8_MMA(1, 1, At, B1); PG8_BAR; PG8_SCHED;
;             PG8_LDB(B0, 1, 0); PG8_LDB(B1, 1, 1); PG8_SCHED; PG8_LDA(At, 1, 0); PG8_STAGE(PG8_SA(0, 1), a2 + hstepA, voffA);
;             PG8_WAIT_V(8); PG8_WAIT_L(0); PG8_BAR; PG8_MMA(0, 0, At, B0); PG8_MMA(0, 1, At, B1); PG8_BAR; PG8_SCHED;
;             PG8_LDA(At, 1, 1); PG8_STAGE(PG8_SB(1, 0), b3, voffB); PG8_STAGE(PG8_SB(1, 1), b3 + hB1, voffB1); PG8_STAGE(PG8_SA(1, 0), a3, voffA);
;             PG8_WAIT_V(8);
;             if constexpr (epi_pre<Epi>::value) { if (last) E.pre(pre, cur, wr, wc, lane); }
;             PG8_WAIT_L(0); PG8_BAR; PG8_MMA(1, 0, At, B0); PG8_MMA(1, 1, At, B1); PG8_BAR; PG8_SCHED;
	s_mov_b32 m0, s69
	v_lshl_add_u64 v[8:9], v[150:151], 0, s[16:17]
	ds_read_b128 v[194:197], v185 offset:49152
	ds_read_b128 v[198:201], v185 offset:50176
	ds_read_b128 v[202:205], v185 offset:51200
	ds_read_b128 v[206:209], v185 offset:52224
	ds_read_b128 v[210:213], v185 offset:53248
	ds_read_b128 v[214:217], v185 offset:54272
	ds_read_b128 v[218:221], v185 offset:55296
	ds_read_b128 v[222:225], v185 offset:56320
	global_load_lds_dwordx4 v[8:9], off
	v_lshl_add_u64 v[8:9], v[152:153], 0, s[16:17]
	s_mov_b32 m0, s68
	s_nop 0
	global_load_lds_dwordx4 v[8:9], off
	s_mov_b32 m0, s71
	s_nop 0
	global_load_lds_dwordx4 v168, s[36:37]
	s_mov_b32 m0, s70
	s_nop 0
	global_load_lds_dwordx4 v172, s[36:37]
	v_lshl_add_u64 v[8:9], v[154:155], 0, s[16:17]
	s_mov_b32 m0, s57
	s_nop 0
	global_load_lds_dwordx4 v[8:9], off
	v_lshl_add_u64 v[8:9], v[156:157], 0, s[16:17]
	s_mov_b32 m0, s58
	s_nop 0
	global_load_lds_dwordx4 v[8:9], off
	s_waitcnt vmcnt(8)
	s_waitcnt lgkmcnt(0)
	s_barrier
	s_setprio 1
	s_waitcnt lgkmcnt(0)
	v_mfma_f32_16x16x32_bf16 v[150:153], v[158:161], v[194:197], v[70:73]
	v_mfma_f32_16x16x32_bf16 v[70:73], v[162:165], v[198:201], v[150:153]
	v_mfma_f32_16x16x32_bf16 v[154:157], v[186:189], v[194:197], v[58:61]
	v_mfma_f32_16x16x32_bf16 v[226:229], v[158:161], v[202:205], v[98:101]
	v_mfma_f32_16x16x32_bf16 v[230:233], v[186:189], v[202:205], v[86:89]
	v_mfma_f32_16x16x32_bf16 v[234:237], v[158:161], v[210:213], v[66:69]
	v_mfma_f32_16x16x32_bf16 v[238:241], v[186:189], v[210:213], v[94:97]
	v_mfma_f32_16x16x32_bf16 v[150:153], v[158:161], v[218:221], v[118:121]
	v_mfma_f32_16x16x32_bf16 v[106:109], v[186:189], v[218:221], v[106:109]
	v_mfma_f32_16x16x32_bf16 v[58:61], v[190:193], v[198:201], v[154:157]
	v_mfma_f32_16x16x32_bf16 v[98:101], v[162:165], v[206:209], v[226:229]
	v_mfma_f32_16x16x32_bf16 v[86:89], v[190:193], v[206:209], v[230:233]
	v_mfma_f32_16x16x32_bf16 v[66:69], v[162:165], v[214:217], v[234:237]
	v_mfma_f32_16x16x32_bf16 v[94:97], v[190:193], v[214:217], v[238:241]
	v_mfma_f32_16x16x32_bf16 v[118:121], v[162:165], v[222:225], v[150:153]
	v_mfma_f32_16x16x32_bf16 v[106:109], v[190:193], v[222:225], v[106:109]
	s_setprio 0
	s_setprio 1
	v_mfma_f32_16x16x32_bf16 v[150:153], v[138:141], v[194:197], v[42:45]
	v_mfma_f32_16x16x32_bf16 v[42:45], v[142:145], v[198:201], v[150:153]
	v_mfma_f32_16x16x32_bf16 v[154:157], v[146:149], v[194:197], v[4:7]
	v_mfma_f32_16x16x32_bf16 v[158:161], v[138:141], v[202:205], v[54:57]
	v_mfma_f32_16x16x32_bf16 v[162:165], v[146:149], v[202:205], v[10:13]
	v_mfma_f32_16x16x32_bf16 v[186:189], v[138:141], v[210:213], v[38:41]
	v_mfma_f32_16x16x32_bf16 v[190:193], v[146:149], v[210:213], v[14:17]
	v_mfma_f32_16x16x32_bf16 v[150:153], v[138:141], v[218:221], v[82:85]
	v_mfma_f32_16x16x32_bf16 v[22:25], v[146:149], v[218:221], v[22:25]
	v_mfma_f32_16x16x32_bf16 v[6:9], v[134:137], v[198:201], v[154:157]
	v_mfma_f32_16x16x32_bf16 v[54:57], v[142:145], v[206:209], v[158:161]
	v_mfma_f32_16x16x32_bf16 v[10:13], v[134:137], v[206:209], v[162:165]
	v_mfma_f32_16x16x32_bf16 v[38:41], v[142:145], v[214:217], v[186:189]
	v_mfma_f32_16x16x32_bf16 v[14:17], v[134:137], v[214:217], v[190:193]
	v_mfma_f32_16x16x32_bf16 v[82:85], v[142:145], v[222:225], v[150:153]
	v_mfma_f32_16x16x32_bf16 v[22:25], v[134:137], v[222:225], v[22:25]
	s_setprio 0
	s_barrier
	s_andn2_b64 vcc, exec, s[34:35]
	s_mov_b64 s[2:3], -1
	s_mov_b64 s[34:35], 0
	s_mov_b64 s[36:37], 0x100
	s_cbranch_vccz .LBB0_1273
	s_lshl_b32 s0, s0, 8
	s_lshl_b32 s1, s6, 8
	s_or_b32 s21, s0, s59
	s_lshl_b32 s0, s7, 10
	s_add_i32 s6, s1, s56
	s_add_i32 s23, s0, 0xc00
	s_cmp_eq_u32 s7, 3
	v_mov_b32_e32 v2, v1
	v_mov_b32_e32 v4, v181
	s_cselect_b64 s[0:1], -1, 0
	s_and_b64 s[2:3], s[0:1], exec
	s_cselect_b32 s2, 0, s23
	v_add_u32_e32 v2, s6, v2
	v_mul_lo_u32 v5, v2, s63
	v_lshlrev_b32_e32 v4, 4, v4
	s_cselect_b32 s28, s54, s14
	s_cselect_b32 s29, s55, s15
	s_add_i32 s3, s2, 0x400
	v_add3_u32 v180, s21, v4, v5
	s_cmp_lt_u32 s7, 2
	v_add_u32_e32 v4, s2, v180
	s_cselect_b32 s3, s3, 0
	global_load_dwordx4 v[142:145], v4, s[14:15]
	v_add_u32_e32 v4, s3, v180
	v_cndmask_b32_e64 v4, v4, 0, s[0:1]
	global_load_dwordx4 v[146:149], v4, s[28:29]
	v_add_u32_e32 v4, 0x22000, v180
	v_add_u32_e32 v138, 0x66000, v180
	v_add_u32_e32 v5, 0x44000, v180
	v_add_u32_e32 v134, s2, v4
	v_add_u32_e32 v136, s2, v138
	v_add_u32_e32 v4, s3, v4
	v_add_u32_e32 v138, s3, v138
	v_add_u32_e32 v135, s2, v5
	v_add_u32_e32 v5, s3, v5
	v_cndmask_b32_e64 v4, v4, 0, s[0:1]
	v_cndmask_b32_e64 v138, v138, 0, s[0:1]
	global_load_dwordx4 v[150:153], v134, s[14:15]
	global_load_dwordx4 v[154:157], v135, s[14:15]
	s_nop 0
	global_load_dwordx4 v[134:137], v136, s[14:15]
	v_cndmask_b32_e64 v5, v5, 0, s[0:1]
	global_load_dwordx4 v[158:161], v4, s[28:29]
	global_load_dwordx4 v[162:165], v5, s[28:29]
	s_nop 0
	global_load_dwordx4 v[138:141], v138, s[28:29]
	v_mad_u64_u32 v[4:5], s[30:31], v2, s64, v[180:181]
	s_and_b64 vcc, exec, s[18:19]
	s_cbranch_vccz .LBB0_1276
	s_barrier

; __device__ __forceinline__ unsigned xb_ld(unsigned* p)              { return __hip_atomic_load(p, __ATOMIC_RELAXED, __HIP_MEMORY_SCOPE_AGENT); }
; #define XB_SPIN(cond, bar) do { unsigned _sp = 0; while (cond) { __builtin_amdgcn_s_sleep(1); \
;     if ((++_sp & 255u) == 0u) { if (xb_ld(&(bar)[XB_TMO])) break; if (_sp > XB_SPIN_CAP) { atomicAdd(&(bar)[XB_TMO], 1u); break; } } } } while (0)
; __device__ __forceinline__ void xcd_barrier(const XcdBarrier& b) {
;     ...
;         } else {
;             XB_SPIN(xb_ld(&bar[XB_XGEN(b.x)]) == gen, bar);
;             __builtin_amdgcn_fence(__ATOMIC_ACQUIRE, "agent");
;             asm volatile("s_waitcnt vmcnt(0)" ::: "memory");
;         }
;     }
;     __syncthreads();
.LBB0_1349:
	s_or_b64 exec, exec, s[0:1]
	s_waitcnt lgkmcnt(0)
	s_barrier
	s_nop 0
	s_nop 0
	s_nop 0
	s_nop 0
	s_nop 0
	s_nop 0
	s_nop 0
	s_nop 0
	s_nop 0
	s_nop 0
	s_nop 0
	s_nop 0

; #define TIDX opq((int)threadIdx.x)
; template <class Epi, class Sched, class Gemm, bool ALIGN_EPI = false, bool SP2 = false>
; __device__ __forceinline__ void gemm_phase(PG8_LAS unsigned char* lds, const Gemm g, const Sched& S, const Epi& E) {
;     const int tid = TIDX, wid = __builtin_amdgcn_readfirstlane(tid >> 6), lane = tid & 63, wr = wid >> 2, wc = wid & 3, fr = lane & 15, fq = lane >> 4;
;     constexpr int K = Gemm::K, nt = K / BK, lda = Gemm::lda, ldb = Gemm::ldb;
;     constexpr int BP = epi_bperm<Epi>::value;
;     unsigned voffA[2], voffB[2], voffB1[2];
; #pragma unroll
;     for (int i = 0; i < 2; ++i) { int R, C; stage_rc(tid * 16 + i * 8192, R, C);
;         voffA[i] = (unsigned)(R * lda + C) * 2u;
;         if constexpr (BP == 2) { const int w_ = R >> 5, n_ = (R >> 4) & 1, j_ = R & 15, cb_ = w_ * 64 + 16 * (j_ >> 2) + 4 * n_ + (j_ & 3);
;             voffB[i] = (unsigned)(cb_ * ldb + C) * 2u; voffB1[i] = voffB[i]; }
;         else { const int Rb = (BP == 1) ? ((R & ~31) + perm32(R & 31)) : R; voffB[i] = (unsigned)(Rb * ldb + C) * 2u; voffB1[i] = voffB[i]; } }
;     const size_t kstep = (size_t)(BK * 2);
;     const size_t hstepA = (size_t)HALF * lda * 2, hstepB = (size_t)HALF * ldb * 2, hB1 = (BP == 2) ? (size_t)8 * ldb * 2 : hstepB;
;     ...
;     Unit cur, nxt; int ui = 0;
;     if (!S.next(0, cur)) return;
;     typename epi_pre<Epi>::Pre pre;
;     f32x4 acc[2][2][4][2];
; #pragma unroll
;     for (int a = 0; a < 2; ++a)
; #pragma unroll
;         for (int b = 0; b < 2; ++b)
; #pragma unroll
;             for (int m = 0; m < 4; ++m)
; #pragma unroll
;                 for (int n = 0; n < 2; ++n) acc[a][b][m][n] = (f32x4){0.f, 0.f, 0.f, 0.f};
;     bf16x8 At[4][2], B0[2][2], B1[2][2];
;     const char* cA = (const char*)g.A + (size_t)cur.pm * tstepA + (size_t)cur.sub * g.a_sub; const char* cB = (const char*)g.Bt + (size_t)cur.pn * tstepB + (size_t)cur.sub * g.b_sub;
;     S.a_ready(cur);
;     if constexpr (SP2) {
;         PG8_STAGE(PG8_SB(0, 0), cB, voffB); PG8_STAGE(PG8_SB(0, 1), cB + hB1, voffB1); PG8_STAGE(PG8_SA(0, 0), cA, voffA); PG8_STAGE(PG8_SA(0, 1), cA + hstepA, voffA);
;         if (wr == 1) PG8_BAR;
;         PG8_WAIT_V(2); PG8_BAR;
;         PG8_STAGE(PG8_SB(1, 0), cB + kstep, voffB); PG8_STAGE(PG8_SA(1, 0), cA + kstep, voffA); PG8_STAGE(PG8_SB(1, 1), cB + hB1 + kstep, voffB1);
;         PG8_WAIT_V(6); PG8_BAR;
.LBB0_1360:
	s_add_u32 s22, s18, 0x1dca8000
	s_addc_u32 s23, s19, 0
	s_add_u32 s57, s18, 0x4000
	s_addc_u32 s58, s19, 0
	s_add_u32 s24, s18, 0x1dce8000
	s_addc_u32 s25, s19, 0
	s_add_u32 s26, s18, 0x1dd08000
	s_addc_u32 s27, s19, 0
	s_add_u32 s18, s18, 0x1dd38800
	s_addc_u32 s19, s19, 0
	s_add_u32 s14, s14, 0x1000
	s_mov_b64 s[28:29], 0x80
	s_addc_u32 s15, s15, 0
	s_and_b32 s59, s4, 3
	s_add_i32 m0, s52, 0x18000
	v_lshl_add_u64 v[8:9], v[8:9], 0, s[28:29]
	s_lshl_b32 s60, s5, 6
	s_lshl_b32 s7, s5, 13
	s_lshl_b32 s61, s59, 5
	s_lshl_b32 s9, s59, 12
	s_waitcnt vmcnt(2)
	s_barrier
	global_load_lds_dwordx4 v[8:9], off
	v_lshl_add_u64 v[6:7], v[6:7], 0, s[28:29]
	s_add_i32 m0, s52, 0x1a000
	s_add_i32 s62, s52, 0x8000
	s_add_i32 s63, s52, 0xa000
	global_load_lds_dwordx4 v[6:7], off
	v_lshl_add_u64 v[2:3], v[2:3], 0, s[28:29]
	s_mov_b32 m0, s62
	s_add_u32 s4, s0, 0x40080
	global_load_lds_dwordx4 v[2:3], off
	v_lshl_add_u64 v[2:3], v[4:5], 0, s[28:29]
	s_mov_b32 m0, s63
	s_addc_u32 s5, s1, 0
	global_load_lds_dwordx4 v[2:3], off
	s_add_i32 m0, s52, 0x1c000
	v_lshl_add_u64 v[2:3], s[4:5], 0, v[196:197]
	global_load_lds_dwordx4 v196, s[4:5]
	v_lshl_add_u64 v[2:3], s[4:5], 0, v[200:201]
	s_add_i32 m0, s52, 0x1e000
	v_bfe_u32 v234, v10, 4, 2
	global_load_lds_dwordx4 v200, s[4:5]
	v_and_b32_e32 v1, 15, v10
	v_lshlrev_b32_e32 v2, 4, v234
	v_lshlrev_b32_e32 v3, 2, v10
	v_lshl_or_b32 v2, v1, 6, v2
	v_and_b32_e32 v3, 32, v3
	v_bitop3_b32 v4, v2, s7, v3 bitop3:0xde
	v_bitop3_b32 v235, v2, s9, v3 bitop3:0xde
	v_lshlrev_b32_e32 v2, 14, v14
	v_and_b32_e32 v2, 0xffff8000, v2
	v_lshl_add_u32 v2, v15, 11, v2
	v_and_b32_e32 v3, 1, v14
	v_lshl_or_b32 v2, v3, 6, v2
	v_lshl_add_u32 v202, v16, 1, v2
	v_lshlrev_b32_e32 v2, 14, v11
	v_and_b32_e32 v2, 0xffff8000, v2
	v_lshl_add_u32 v2, v12, 11, v2
	v_and_b32_e32 v3, 1, v11
	s_waitcnt vmcnt(6)
	s_cmpk_lt_u32 s6, 0x100
	v_lshl_or_b32 v2, v3, 6, v2
	s_cselect_b64 s[30:31], -1, 0
	v_lshl_add_u32 v204, v13, 1, v2
	s_add_i32 s66, 0, 0x10000
	s_add_i32 s67, 0, 0x14000
	v_mbcnt_lo_u32_b32 v2, -1, 0
	s_ashr_i32 s64, s46, 31
	s_ashr_i32 s65, s35, 31
	v_mov_b32_e32 v203, v197
	v_mov_b32_e32 v205, v197
	v_mov_b64_e32 v[206:207], 0x200
	v_mov_b64_e32 v[208:209], 0x1ff
	v_add_u32_e32 v236, s66, v235
	v_add_u32_e32 v237, s67, v235
	v_add_u32_e32 v238, 0, v4
	v_mbcnt_hi_u32_b32 v239, -1, v2
	v_mov_b32_e32 v240, 0x358637bd
	s_mov_b32 s68, 0xf800000
	v_mov_b32_e32 v241, 0x260
	s_mov_b32 s69, 0x42fe0000
	s_mov_b32 s34, 0x4b400000
	s_mov_b32 s70, 0x40c0c00
	s_barrier
	s_branch .LBB0_1363

; #define PG8_STAGE(bufoff, gbase, voff) do { _Pragma("unroll") for (int _i = 0; _i < 2; ++_i) \
;         __builtin_amdgcn_global_load_lds((const unsigned*)((const char*)(gbase) + (voff)[_i]), (PG8_LAS unsigned*)(lds + (bufoff) + ldsw + _i * 8192), 16, 0, 0); } while (0)
; #define PG8_LDA(dst, b, h) do { _Pragma("unroll") for (int m = 0; m < 4; ++m) _Pragma("unroll") for (int k = 0; k < 2; ++k) dst[m][k] = *(const PG8_LAS bf16x8*)(lds + PG8_SA(b, h) + aoff + m * 2048 + k * 1024); } while (0)
; #define PG8_WAIT_V(n) asm volatile("s_waitcnt vmcnt(" #n ")" ::: "memory")
; template <class Epi, class Sched, class Gemm, bool ALIGN_EPI = false, bool SP2 = false>
; __device__ __forceinline__ void gemm_phase(PG8_LAS unsigned char* lds, const Gemm g, const Sched& S, const Epi& E) {
;     ...
;         for (int t = 0; t < nt; t += 2) {
;             const bool last = (t == nt - 2);
;             const char* a1 = cA + (size_t)(t + 1) * kstep;
;             const char* a2 = last ? nA : cA + (size_t)(t + 2) * kstep; const char* b2 = last ? nB : cB + (size_t)(t + 2) * kstep;
;             const char* a3 = a2 + kstep; const char* b3 = b2 + kstep;
;             if (last && has_next) S.a_ready(nxt);
;             if constexpr (SP2) {
;             PG8_LDB(B0, 0, 0); PG8_LDB(B1, 0, 1); PG8_SCHED; PG8_LDA(At, 0, 0); PG8_STAGE(PG8_SA(1, 1), a1 + hstepA, voffA);
;             PG8_WAIT_V(8); PG8_WAIT_L(0); PG8_BAR; PG8_MMA(0, 0, At, B0); PG8_MMA(0, 1, At, B1); PG8_BAR; PG8_SCHED;
;             PG8_LDA(At, 0, 1); PG8_STAGE(PG8_SB(0, 0), b2, voffB); PG8_STAGE(PG8_SB(0, 1), b2 + hB1, voffB1); PG8_STAGE(PG8_SA(0, 0), a2, voffA);
;             PG8_WAIT_V(8); PG8_WAIT_L(0); PG8_BAR; PG8_MMA(1, 0, At, B0); PG8_MMA(1, 1, At, B1); PG8_BAR; PG8_SCHED;
;             PG8_LDB(B0, 1, 0); PG8_LDB(B1, 1, 1); PG8_SCHED; PG8_LDA(At, 1, 0); PG8_STAGE(PG8_SA(0, 1), a2 + hstepA, voffA);
;             PG8_WAIT_V(8); PG8_WAIT_L(0); PG8_BAR; PG8_MMA(0, 0, At, B0); PG8_MMA(0, 1, At, B1); PG8_BAR; PG8_SCHED;
;             PG8_LDA(At, 1, 1); PG8_STAGE(PG8_SB(1, 0), b3, voffB); PG8_STAGE(PG8_SB(1, 1), b3 + hB1, voffB1); PG8_STAGE(PG8_SA(1, 0), a3, voffA);
;             PG8_WAIT_V(8);
;             if constexpr (epi_pre<Epi>::value) { if (last) E.pre(pre, cur, wr, wc, lane); }
;             PG8_WAIT_L(0); PG8_BAR; PG8_MMA(1, 0, At, B0); PG8_MMA(1, 1, At, B1); PG8_BAR; PG8_SCHED;
.LBB0_1370:
	ds_read_b128 v[170:173], v236
	ds_read_b128 v[174:177], v236 offset:1024
	ds_read_b128 v[178:181], v236 offset:2048
	ds_read_b128 v[182:185], v236 offset:3072
	ds_read_b128 v[150:153], v237
	ds_read_b128 v[154:157], v237 offset:1024
	ds_read_b128 v[158:161], v237 offset:2048
	ds_read_b128 v[146:149], v237 offset:3072
	s_add_u32 s2, s0, 0xfffc0080
	s_addc_u32 s3, s1, -1
	s_cmp_eq_u32 s72, 12
	s_cselect_b32 s3, s9, s3
	s_cselect_b32 s2, s33, s2
	s_cselect_b32 s7, s37, s71
	s_cselect_b32 s6, s39, s45
	s_add_i32 m0, s52, 0xc000
	ds_read_b128 v[162:165], v238
	ds_read_b128 v[166:169], v238 offset:1024
	ds_read_b128 v[186:189], v238 offset:2048
	ds_read_b128 v[190:193], v238 offset:3072
	ds_read_b128 v[210:213], v238 offset:4096
	ds_read_b128 v[214:217], v238 offset:5120
	ds_read_b128 v[218:221], v238 offset:6144
	ds_read_b128 v[222:225], v238 offset:7168
	global_load_lds_dwordx4 v204, s[0:1]
	v_lshl_add_u64 v[2:3], s[0:1], 0, v[202:203]
	s_add_i32 m0, s52, 0xe000
	s_nop 0
	global_load_lds_dwordx4 v202, s[0:1]
	s_waitcnt vmcnt(8)
	s_waitcnt lgkmcnt(0)
	s_barrier
	s_setprio 1
	s_waitcnt lgkmcnt(0)
	v_mfma_f32_16x16x32_bf16 v[10:13], v[170:173], v[162:165], v[94:97]
	v_mfma_f32_16x16x32_bf16 v[14:17], v[178:181], v[162:165], v[90:93]
	v_mfma_f32_16x16x32_bf16 v[2:5], v[174:177], v[166:169], v[10:13]
	v_mfma_f32_16x16x32_bf16 v[90:93], v[182:185], v[166:169], v[14:17]
	v_mfma_f32_16x16x32_bf16 v[94:97], v[170:173], v[186:189], v[110:113]
	v_mfma_f32_16x16x32_bf16 v[226:229], v[178:181], v[186:189], v[106:109]
	v_mfma_f32_16x16x32_bf16 v[230:233], v[178:181], v[210:213], v[122:125]
	v_mfma_f32_16x16x32_bf16 v[10:13], v[170:173], v[218:221], v[142:145]
	v_mfma_f32_16x16x32_bf16 v[14:17], v[178:181], v[218:221], v[138:141]
	v_mfma_f32_16x16x32_bf16 v[110:113], v[174:177], v[190:193], v[94:97]
	v_mfma_f32_16x16x32_bf16 v[106:109], v[182:185], v[190:193], v[226:229]
	v_mfma_f32_16x16x32_bf16 v[130:133], v[170:173], v[210:213], v[130:133]
	v_mfma_f32_16x16x32_bf16 v[122:125], v[182:185], v[214:217], v[230:233]
	v_mfma_f32_16x16x32_bf16 v[142:145], v[174:177], v[222:225], v[10:13]
	v_mfma_f32_16x16x32_bf16 v[138:141], v[182:185], v[222:225], v[14:17]
	v_mfma_f32_16x16x32_bf16 v[6:9], v[174:177], v[214:217], v[130:133]
	s_setprio 0
	s_setprio 1
	v_mfma_f32_16x16x32_bf16 v[86:89], v[150:153], v[162:165], v[86:89]
	v_mfma_f32_16x16x32_bf16 v[82:85], v[158:161], v[162:165], v[82:85]
	v_mfma_f32_16x16x32_bf16 v[10:13], v[154:157], v[166:169], v[86:89]
	v_mfma_f32_16x16x32_bf16 v[14:17], v[146:149], v[166:169], v[82:85]
	v_mfma_f32_16x16x32_bf16 v[94:97], v[150:153], v[186:189], v[102:105]
	v_mfma_f32_16x16x32_bf16 v[130:133], v[158:161], v[186:189], v[98:101]
	v_mfma_f32_16x16x32_bf16 v[226:229], v[150:153], v[210:213], v[118:121]
	v_mfma_f32_16x16x32_bf16 v[230:233], v[158:161], v[210:213], v[114:117]
	v_mfma_f32_16x16x32_bf16 v[82:85], v[150:153], v[218:221], v[134:137]
	v_mfma_f32_16x16x32_bf16 v[86:89], v[158:161], v[218:221], v[126:129]
	v_mfma_f32_16x16x32_bf16 v[102:105], v[154:157], v[190:193], v[94:97]
	v_mfma_f32_16x16x32_bf16 v[98:101], v[146:149], v[190:193], v[130:133]
	v_mfma_f32_16x16x32_bf16 v[118:121], v[154:157], v[214:217], v[226:229]
	v_mfma_f32_16x16x32_bf16 v[114:117], v[146:149], v[214:217], v[230:233]
	v_mfma_f32_16x16x32_bf16 v[134:137], v[154:157], v[222:225], v[82:85]
	v_mfma_f32_16x16x32_bf16 v[126:129], v[146:149], v[222:225], v[86:89]
	s_setprio 0
	s_barrier
	s_add_i32 s73, s66, s51
	v_lshl_add_u64 v[162:163], s[6:7], 0, v[196:197]
	s_mov_b32 m0, s73
	ds_read_b128 v[82:85], v238 offset:16384
	ds_read_b128 v[86:89], v238 offset:17408
	ds_read_b128 v[94:97], v238 offset:18432
	ds_read_b128 v[130:133], v238 offset:19456
	ds_read_b128 v[186:189], v238 offset:20480
	ds_read_b128 v[190:193], v238 offset:21504
	ds_read_b128 v[210:213], v238 offset:22528
	ds_read_b128 v[214:217], v238 offset:23552
	global_load_lds_dwordx4 v196, s[6:7]
	s_add_i32 m0, s73, 0x2000
	s_add_u32 s74, s6, 0x40000
	v_lshl_add_u64 v[164:165], s[6:7], 0, v[200:201]
	s_addc_u32 s75, s7, 0
	s_add_i32 s73, s67, s51
	global_load_lds_dwordx4 v200, s[6:7]
	s_mov_b32 m0, s73
	v_lshl_add_u64 v[168:169], s[2:3], 0, v[198:199]
	global_load_lds_dwordx4 v196, s[74:75]
	s_add_i32 m0, s73, 0x2000
	s_nop 0
	global_load_lds_dwordx4 v200, s[74:75]
	v_lshl_add_u64 v[166:167], s[2:3], 0, v[194:195]
	s_mov_b32 m0, s52
	s_nop 0
	global_load_lds_dwordx4 v194, s[2:3]
	s_mov_b32 m0, s53
	s_nop 0
	global_load_lds_dwordx4 v198, s[2:3]
	s_waitcnt vmcnt(8)
	s_waitcnt lgkmcnt(0)
	s_barrier
; #define PG8_STAGE(bufoff, gbase, voff) do { _Pragma("unroll") for (int _i = 0; _i < 2; ++_i) \
;         __builtin_amdgcn_global_load_lds((const unsigned*)((const char*)(gbase) + (voff)[_i]), (PG8_LAS unsigned*)(lds + (bufoff) + ldsw + _i * 8192), 16, 0, 0); } while (0)
; #define PG8_LDA(dst, b, h) do { _Pragma("unroll") for (int m = 0; m < 4; ++m) _Pragma("unroll") for (int k = 0; k < 2; ++k) dst[m][k] = *(const PG8_LAS bf16x8*)(lds + PG8_SA(b, h) + aoff + m * 2048 + k * 1024); } while (0)
; #define PG8_WAIT_V(n) asm volatile("s_waitcnt vmcnt(" #n ")" ::: "memory")
; template <class Epi, class Sched, class Gemm, bool ALIGN_EPI = false, bool SP2 = false>
; __device__ __forceinline__ void gemm_phase(PG8_LAS unsigned char* lds, const Gemm g, const Sched& S, const Epi& E) {
;     ...
;         for (int t = 0; t < nt; t += 2) {
;             const bool last = (t == nt - 2);
;             const char* a1 = cA + (size_t)(t + 1) * kstep;
;             const char* a2 = last ? nA : cA + (size_t)(t + 2) * kstep; const char* b2 = last ? nB : cB + (size_t)(t + 2) * kstep;
;             const char* a3 = a2 + kstep; const char* b3 = b2 + kstep;
;             if (last && has_next) S.a_ready(nxt);
;             if constexpr (SP2) {
;             PG8_LDB(B0, 0, 0); PG8_LDB(B1, 0, 1); PG8_SCHED; PG8_LDA(At, 0, 0); PG8_STAGE(PG8_SA(1, 1), a1 + hstepA, voffA);
;             PG8_WAIT_V(8); PG8_WAIT_L(0); PG8_BAR; PG8_MMA(0, 0, At, B0); PG8_MMA(0, 1, At, B1); PG8_BAR; PG8_SCHED;
;             PG8_LDA(At, 0, 1); PG8_STAGE(PG8_SB(0, 0), b2, voffB); PG8_STAGE(PG8_SB(0, 1), b2 + hB1, voffB1); PG8_STAGE(PG8_SA(0, 0), a2, voffA);
;             PG8_WAIT_V(8); PG8_WAIT_L(0); PG8_BAR; PG8_MMA(1, 0, At, B0); PG8_MMA(1, 1, At, B1); PG8_BAR; PG8_SCHED;
;             PG8_LDB(B0, 1, 0); PG8_LDB(B1, 1, 1); PG8_SCHED; PG8_LDA(At, 1, 0); PG8_STAGE(PG8_SA(0, 1), a2 + hstepA, voffA);
;             PG8_WAIT_V(8); PG8_WAIT_L(0); PG8_BAR; PG8_MMA(0, 0, At, B0); PG8_MMA(0, 1, At, B1); PG8_BAR; PG8_SCHED;
;             PG8_LDA(At, 1, 1); PG8_STAGE(PG8_SB(1, 0), b3, voffB); PG8_STAGE(PG8_SB(1, 1), b3 + hB1, voffB1); PG8_STAGE(PG8_SA(1, 0), a3, voffA);
;             PG8_WAIT_V(8);
;             if constexpr (epi_pre<Epi>::value) { if (last) E.pre(pre, cur, wr, wc, lane); }
;             PG8_WAIT_L(0); PG8_BAR; PG8_MMA(1, 0, At, B0); PG8_MMA(1, 1, At, B1); PG8_BAR; PG8_SCHED;
	s_setprio 1
	s_waitcnt lgkmcnt(0)
	v_mfma_f32_16x16x32_bf16 v[218:221], v[170:173], v[82:85], v[78:81]
	v_mfma_f32_16x16x32_bf16 v[78:81], v[174:177], v[86:89], v[218:221]
	v_mfma_f32_16x16x32_bf16 v[222:225], v[178:181], v[82:85], v[74:77]
	v_mfma_f32_16x16x32_bf16 v[226:229], v[170:173], v[94:97], v[62:65]
	v_mfma_f32_16x16x32_bf16 v[230:233], v[178:181], v[94:97], v[58:61]
	v_mfma_f32_16x16x32_bf16 v[242:245], v[170:173], v[186:189], v[46:49]
	v_mfma_f32_16x16x32_bf16 v[246:249], v[178:181], v[186:189], v[42:45]
	v_mfma_f32_16x16x32_bf16 v[218:221], v[170:173], v[210:213], v[30:33]
	v_mfma_f32_16x16x32_bf16 v[26:29], v[178:181], v[210:213], v[26:29]
	v_mfma_f32_16x16x32_bf16 v[74:77], v[182:185], v[86:89], v[222:225]
	v_mfma_f32_16x16x32_bf16 v[62:65], v[174:177], v[130:133], v[226:229]
	v_mfma_f32_16x16x32_bf16 v[58:61], v[182:185], v[130:133], v[230:233]
	v_mfma_f32_16x16x32_bf16 v[46:49], v[174:177], v[190:193], v[242:245]
	v_mfma_f32_16x16x32_bf16 v[42:45], v[182:185], v[190:193], v[246:249]
	v_mfma_f32_16x16x32_bf16 v[30:33], v[174:177], v[214:217], v[218:221]
	v_mfma_f32_16x16x32_bf16 v[26:29], v[182:185], v[214:217], v[26:29]
	s_setprio 0
	s_setprio 1
	v_mfma_f32_16x16x32_bf16 v[170:173], v[150:153], v[82:85], v[70:73]
	v_mfma_f32_16x16x32_bf16 v[70:73], v[154:157], v[86:89], v[170:173]
	v_mfma_f32_16x16x32_bf16 v[174:177], v[158:161], v[82:85], v[66:69]
	v_mfma_f32_16x16x32_bf16 v[178:181], v[150:153], v[94:97], v[54:57]
	v_mfma_f32_16x16x32_bf16 v[182:185], v[158:161], v[94:97], v[50:53]
	v_mfma_f32_16x16x32_bf16 v[218:221], v[150:153], v[186:189], v[38:41]
	v_mfma_f32_16x16x32_bf16 v[222:225], v[158:161], v[186:189], v[34:37]
	v_mfma_f32_16x16x32_bf16 v[82:85], v[150:153], v[210:213], v[22:25]
	v_mfma_f32_16x16x32_bf16 v[18:21], v[158:161], v[210:213], v[18:21]
	v_mfma_f32_16x16x32_bf16 v[66:69], v[146:149], v[86:89], v[174:177]
	v_mfma_f32_16x16x32_bf16 v[54:57], v[154:157], v[130:133], v[178:181]
	v_mfma_f32_16x16x32_bf16 v[50:53], v[146:149], v[130:133], v[182:185]
	v_mfma_f32_16x16x32_bf16 v[38:41], v[154:157], v[190:193], v[218:221]
	v_mfma_f32_16x16x32_bf16 v[34:37], v[146:149], v[190:193], v[222:225]
	v_mfma_f32_16x16x32_bf16 v[22:25], v[154:157], v[214:217], v[82:85]
	v_mfma_f32_16x16x32_bf16 v[18:21], v[146:149], v[214:217], v[18:21]
	s_setprio 0
	s_barrier
	s_add_i32 s73, 0, 0x18000
	v_add_u32_e32 v82, s73, v235
	s_add_i32 s74, 0, 0x1c000
	ds_read_b128 v[170:173], v82
	ds_read_b128 v[174:177], v82 offset:1024
	ds_read_b128 v[178:181], v82 offset:2048
	ds_read_b128 v[182:185], v82 offset:3072
	v_add_u32_e32 v82, s74, v235
	ds_read_b128 v[150:153], v82
	ds_read_b128 v[154:157], v82 offset:1024
	ds_read_b128 v[158:161], v82 offset:2048
	ds_read_b128 v[146:149], v82 offset:3072
	s_add_u32 s2, s2, 0x40000
	s_addc_u32 s3, s3, 0
	s_mov_b32 m0, s54
	ds_read_b128 v[186:189], v238 offset:32768
	ds_read_b128 v[190:193], v238 offset:33792
	ds_read_b128 v[210:213], v238 offset:34816
	ds_read_b128 v[214:217], v238 offset:35840
	ds_read_b128 v[218:221], v238 offset:36864
	ds_read_b128 v[222:225], v238 offset:37888
	ds_read_b128 v[226:229], v238 offset:38912
	ds_read_b128 v[230:233], v238 offset:39936
	global_load_lds_dwordx4 v194, s[2:3]
	v_lshl_add_u64 v[82:83], s[2:3], 0, v[198:199]
	s_mov_b32 m0, s55
	s_nop 0
	global_load_lds_dwordx4 v198, s[2:3]
	s_waitcnt vmcnt(8)
	s_waitcnt lgkmcnt(0)
	s_barrier
	s_setprio 1
	s_waitcnt lgkmcnt(0)
	v_mfma_f32_16x16x32_bf16 v[2:5], v[170:173], v[186:189], v[2:5]
	v_mfma_f32_16x16x32_bf16 v[82:85], v[178:181], v[186:189], v[90:93]
	v_mfma_f32_16x16x32_bf16 v[86:89], v[170:173], v[210:213], v[110:113]
	v_mfma_f32_16x16x32_bf16 v[242:245], v[178:181], v[210:213], v[106:109]
	v_mfma_f32_16x16x32_bf16 v[6:9], v[170:173], v[218:221], v[6:9]
	v_mfma_f32_16x16x32_bf16 v[94:97], v[174:177], v[190:193], v[2:5]
	v_mfma_f32_16x16x32_bf16 v[90:93], v[182:185], v[190:193], v[82:85]
	v_mfma_f32_16x16x32_bf16 v[110:113], v[174:177], v[214:217], v[86:89]
	v_mfma_f32_16x16x32_bf16 v[106:109], v[182:185], v[214:217], v[242:245]
	v_mfma_f32_16x16x32_bf16 v[130:133], v[174:177], v[222:225], v[6:9]
	v_mfma_f32_16x16x32_bf16 v[246:249], v[178:181], v[218:221], v[122:125]
	v_mfma_f32_16x16x32_bf16 v[2:5], v[170:173], v[226:229], v[142:145]
	v_mfma_f32_16x16x32_bf16 v[6:9], v[178:181], v[226:229], v[138:141]
	v_mfma_f32_16x16x32_bf16 v[122:125], v[182:185], v[222:225], v[246:249]
	v_mfma_f32_16x16x32_bf16 v[142:145], v[174:177], v[230:233], v[2:5]
	v_mfma_f32_16x16x32_bf16 v[138:141], v[182:185], v[230:233], v[6:9]
	s_setprio 0
	s_setprio 1
	v_mfma_f32_16x16x32_bf16 v[2:5], v[150:153], v[186:189], v[10:13]
	v_mfma_f32_16x16x32_bf16 v[6:9], v[158:161], v[186:189], v[14:17]
	v_mfma_f32_16x16x32_bf16 v[86:89], v[154:157], v[190:193], v[2:5]
	v_mfma_f32_16x16x32_bf16 v[82:85], v[146:149], v[190:193], v[6:9]
	v_mfma_f32_16x16x32_bf16 v[10:13], v[150:153], v[210:213], v[102:105]
	v_mfma_f32_16x16x32_bf16 v[14:17], v[158:161], v[210:213], v[98:101]
	v_mfma_f32_16x16x32_bf16 v[242:245], v[150:153], v[218:221], v[118:121]
	v_mfma_f32_16x16x32_bf16 v[246:249], v[158:161], v[218:221], v[114:117]
	v_mfma_f32_16x16x32_bf16 v[2:5], v[150:153], v[226:229], v[134:137]
	v_mfma_f32_16x16x32_bf16 v[6:9], v[158:161], v[226:229], v[126:129]
	v_mfma_f32_16x16x32_bf16 v[102:105], v[154:157], v[214:217], v[10:13]
	v_mfma_f32_16x16x32_bf16 v[98:101], v[146:149], v[214:217], v[14:17]
	v_mfma_f32_16x16x32_bf16 v[118:121], v[154:157], v[222:225], v[242:245]
	v_mfma_f32_16x16x32_bf16 v[114:117], v[146:149], v[222:225], v[246:249]
	v_mfma_f32_16x16x32_bf16 v[134:137], v[154:157], v[230:233], v[2:5]
	v_mfma_f32_16x16x32_bf16 v[126:129], v[146:149], v[230:233], v[6:9]
	s_setprio 0
	s_barrier
; #define EPN_LOAD(i) do { const size_t off_ = EPN_OFF(i); x0q[i] = *(const f32x4*)(xin + off_); x1q[i] = *(const f32x4*)(xin + off_ + 4); } while (0)
; #define PG8_STAGE(bufoff, gbase, voff) do { _Pragma("unroll") for (int _i = 0; _i < 2; ++_i) \
;         __builtin_amdgcn_global_load_lds((const unsigned*)((const char*)(gbase) + (voff)[_i]), (PG8_LAS unsigned*)(lds + (bufoff) + ldsw + _i * 8192), 16, 0, 0); } while (0)
; #define PG8_WAIT_V(n) asm volatile("s_waitcnt vmcnt(" #n ")" ::: "memory")
;     __device__ __forceinline__ void operator()(f32x4 (&acc)[2][2][4][2], const Unit& u, int wr, int wc, int fr, int fq) const {
;         asm volatile("" : "+v"(fr), "+v"(fq));
;         const int row0 = u.pm * BM + wr * 64 + fr, col0 = u.pn * BM + wc * 32 + 8 * fq;
;         constexpr int DEPTH = FINAL ? 8 : 4;
;         f32x4 gv[2][2];
;         if constexpr (!FINAL) {
; #pragma unroll
;             for (int bj = 0; bj < 2; ++bj)
; #pragma unroll
;                 for (int n = 0; n < 2; ++n) gv[bj][n] = *(const f32x4*)(g + col0 + bj * HALF + 4 * n);
;         }
;         f32x4 x0q[16], x1q[16];
;     ...
; #pragma unroll
;         for (int i = 0; i < DEPTH; ++i) EPN_LOAD(i);
;         asm volatile("" ::: "memory");
; #pragma unroll
;         for (int i = 0; i < 16; ++i) {
;             const int ai = i >> 3, m = (i >> 1) & 3, bj = i & 1;
;             acc[ai][bj][m][0] += x0q[i]; acc[ai][bj][m][1] += x1q[i];
; template <class Epi, class Sched, class Gemm, bool ALIGN_EPI = false, bool SP2 = false>
; __device__ __forceinline__ void gemm_phase(PG8_LAS unsigned char* lds, const Gemm g, const Sched& S, const Epi& E) {
;     ...
;             PG8_WAIT_V(8); PG8_WAIT_L(0); PG8_BAR; PG8_MMA(1, 0, At, B0); PG8_MMA(1, 1, At, B1); PG8_BAR; PG8_SCHED;
;             PG8_LDB(B0, 1, 0); PG8_LDB(B1, 1, 1); PG8_SCHED; PG8_LDA(At, 1, 0); PG8_STAGE(PG8_SA(0, 1), a2 + hstepA, voffA);
;             PG8_WAIT_V(8); PG8_WAIT_L(0); PG8_BAR; PG8_MMA(0, 0, At, B0); PG8_MMA(0, 1, At, B1); PG8_BAR; PG8_SCHED;
;             PG8_LDA(At, 1, 1); PG8_STAGE(PG8_SB(1, 0), b3, voffB); PG8_STAGE(PG8_SB(1, 1), b3 + hB1, voffB1); PG8_STAGE(PG8_SA(1, 0), a3, voffA);
;             PG8_WAIT_V(8);
;             if constexpr (epi_pre<Epi>::value) { if (last) E.pre(pre, cur, wr, wc, lane); }
;             PG8_WAIT_L(0); PG8_BAR; PG8_MMA(1, 0, At, B0); PG8_MMA(1, 1, At, B1); PG8_BAR; PG8_SCHED;
	s_add_i32 s2, s73, s51
	v_lshl_add_u64 v[162:163], v[162:163], 0, s[28:29]
	s_mov_b32 m0, s2
	ds_read_b128 v[2:5], v238 offset:49152
	ds_read_b128 v[6:9], v238 offset:50176
	ds_read_b128 v[10:13], v238 offset:51200
	ds_read_b128 v[14:17], v238 offset:52224
	ds_read_b128 v[186:189], v238 offset:53248
	ds_read_b128 v[190:193], v238 offset:54272
	ds_read_b128 v[210:213], v238 offset:55296
	ds_read_b128 v[214:217], v238 offset:56320
	global_load_lds_dwordx4 v[162:163], off
	s_add_i32 m0, s2, 0x2000
	s_add_u32 s2, s6, 0x40080
	v_lshl_add_u64 v[162:163], v[164:165], 0, s[28:29]
	s_addc_u32 s3, s7, 0
	s_add_i32 s6, s74, s51
	global_load_lds_dwordx4 v[162:163], off
	s_mov_b32 m0, s6
	s_nop 0
	global_load_lds_dwordx4 v196, s[2:3]
	s_add_i32 m0, s6, 0x2000
	s_nop 0
	global_load_lds_dwordx4 v200, s[2:3]
	v_lshl_add_u64 v[162:163], v[166:167], 0, s[28:29]
	s_mov_b32 m0, s62
	s_nop 0
	global_load_lds_dwordx4 v[162:163], off
	v_lshl_add_u64 v[162:163], v[168:169], 0, s[28:29]
	s_mov_b32 m0, s63
	s_nop 0
	global_load_lds_dwordx4 v[162:163], off
	s_waitcnt vmcnt(8)
	s_waitcnt lgkmcnt(0)
	s_barrier
	s_setprio 1
	s_waitcnt lgkmcnt(0)
	v_mfma_f32_16x16x32_bf16 v[162:165], v[170:173], v[2:5], v[78:81]
	v_mfma_f32_16x16x32_bf16 v[78:81], v[174:177], v[6:9], v[162:165]
	v_mfma_f32_16x16x32_bf16 v[166:169], v[178:181], v[2:5], v[74:77]
	v_mfma_f32_16x16x32_bf16 v[218:221], v[170:173], v[10:13], v[62:65]
	v_mfma_f32_16x16x32_bf16 v[222:225], v[178:181], v[10:13], v[58:61]
	v_mfma_f32_16x16x32_bf16 v[226:229], v[170:173], v[186:189], v[46:49]
	v_mfma_f32_16x16x32_bf16 v[230:233], v[178:181], v[186:189], v[42:45]
	v_mfma_f32_16x16x32_bf16 v[162:165], v[170:173], v[210:213], v[30:33]
	v_mfma_f32_16x16x32_bf16 v[26:29], v[178:181], v[210:213], v[26:29]
	v_mfma_f32_16x16x32_bf16 v[74:77], v[182:185], v[6:9], v[166:169]
	v_mfma_f32_16x16x32_bf16 v[62:65], v[174:177], v[14:17], v[218:221]
	v_mfma_f32_16x16x32_bf16 v[58:61], v[182:185], v[14:17], v[222:225]
	v_mfma_f32_16x16x32_bf16 v[46:49], v[174:177], v[190:193], v[226:229]
	v_mfma_f32_16x16x32_bf16 v[42:45], v[182:185], v[190:193], v[230:233]
	v_mfma_f32_16x16x32_bf16 v[30:33], v[174:177], v[214:217], v[162:165]
	v_mfma_f32_16x16x32_bf16 v[26:29], v[182:185], v[214:217], v[26:29]
	s_setprio 0
	s_setprio 1
	v_mfma_f32_16x16x32_bf16 v[162:165], v[150:153], v[2:5], v[70:73]
	v_mfma_f32_16x16x32_bf16 v[166:169], v[158:161], v[2:5], v[66:69]
	v_mfma_f32_16x16x32_bf16 v[70:73], v[154:157], v[6:9], v[162:165]
	v_mfma_f32_16x16x32_bf16 v[66:69], v[146:149], v[6:9], v[166:169]
	v_mfma_f32_16x16x32_bf16 v[170:173], v[150:153], v[10:13], v[54:57]
	v_mfma_f32_16x16x32_bf16 v[174:177], v[158:161], v[10:13], v[50:53]
	v_mfma_f32_16x16x32_bf16 v[178:181], v[150:153], v[186:189], v[38:41]
	v_mfma_f32_16x16x32_bf16 v[182:185], v[158:161], v[186:189], v[34:37]
	v_mfma_f32_16x16x32_bf16 v[2:5], v[150:153], v[210:213], v[22:25]
	v_mfma_f32_16x16x32_bf16 v[6:9], v[158:161], v[210:213], v[18:21]
	v_mfma_f32_16x16x32_bf16 v[54:57], v[154:157], v[14:17], v[170:173]
	v_mfma_f32_16x16x32_bf16 v[50:53], v[146:149], v[14:17], v[174:177]
	v_mfma_f32_16x16x32_bf16 v[38:41], v[154:157], v[190:193], v[178:181]
	v_mfma_f32_16x16x32_bf16 v[34:37], v[146:149], v[190:193], v[182:185]
	v_mfma_f32_16x16x32_bf16 v[22:25], v[154:157], v[214:217], v[2:5]
	v_mfma_f32_16x16x32_bf16 v[18:21], v[146:149], v[214:217], v[6:9]
	s_setprio 0
	s_barrier
	s_add_i32 s72, s72, 2
	s_add_u32 s45, s45, 0x100
	s_addc_u32 s71, s71, 0
	s_add_u32 s0, s0, 0x100
	s_addc_u32 s1, s1, 0
	s_cmp_gt_u32 s72, 13
	s_cbranch_scc0 .LBB0_1370
	s_and_b64 vcc, exec, s[30:31]
	s_cbranch_vccz .LBB0_1373
	s_barrier
.LBB0_1373:
	s_lshl_b32 s1, s8, 8
	v_mov_b32_e32 v243, v1
	v_mov_b32_e32 v242, v234
	s_lshl_b32 s0, s44, 8
	s_or_b32 s1, s1, s61
	s_add_i32 s0, s0, s60
	v_lshl_add_u32 v210, v242, 3, s1
	v_ashrrev_i32_e32 v211, 31, v210
	v_add_u32_e32 v224, s0, v243
	v_lshlrev_b64 v[146:147], 2, v[210:211]
	v_ashrrev_i32_e32 v225, 31, v224
	v_lshl_add_u64 v[148:149], s[12:13], 0, v[146:147]
	v_lshlrev_b64 v[228:229], 12, v[224:225]
	v_lshl_add_u64 v[2:3], v[148:149], 0, v[228:229]
	global_load_dwordx4 v[162:165], v[2:3], off
	global_load_dwordx4 v[166:169], v[2:3], off offset:16
	global_load_dwordx4 v[170:173], v[2:3], off offset:512
	global_load_dwordx4 v[178:181], v[2:3], off offset:528
	v_add_u32_e32 v216, 16, v224
	v_add_u32_e32 v212, 32, v224
	v_ashrrev_i32_e32 v217, 31, v216
	v_ashrrev_i32_e32 v213, 31, v212
	v_lshlrev_b64 v[150:151], 12, v[216:217]
	v_lshl_add_u64 v[6:7], s[14:15], 0, v[146:147]
	v_lshlrev_b64 v[152:153], 12, v[212:213]
	v_lshl_add_u64 v[148:149], v[148:149], 0, v[150:151]
	global_load_dwordx4 v[10:13], v[6:7], off offset:16
	global_load_dwordx4 v[14:17], v[6:7], off
	global_load_dwordx4 v[2:5], v[6:7], off offset:528
	s_nop 0
	global_load_dwordx4 v[6:9], v[6:7], off offset:512
	v_lshl_add_u64 v[150:151], s[12:13], 0, v[152:153]
	global_load_dwordx4 v[182:185], v[148:149], off offset:16
	global_load_dwordx4 v[190:193], v[148:149], off
	global_load_dwordx4 v[174:177], v[148:149], off offset:528
	global_load_dwordx4 v[186:189], v[148:149], off offset:512
	v_lshl_add_u64 v[158:159], v[150:151], 0, v[146:147]
	global_load_dwordx4 v[146:149], v[158:159], off offset:16
	global_load_dwordx4 v[150:153], v[158:159], off
	global_load_dwordx4 v[154:157], v[158:159], off offset:528
	s_nop 0
	global_load_dwordx4 v[158:161], v[158:159], off offset:512
	v_and_b32_e32 v215, 64, v239
	v_xor_b32_e32 v214, 16, v239
	v_add_u32_e32 v215, 64, v215
	v_cmp_lt_i32_e32 vcc, v214, v215
	v_lshl_add_u64 v[230:231], v[224:225], 2, s[22:23]
	s_waitcnt vmcnt(15)
; #define EPN_LOAD(i) do { const size_t off_ = EPN_OFF(i); x0q[i] = *(const f32x4*)(xin + off_); x1q[i] = *(const f32x4*)(xin + off_ + 4); } while (0)
;     __device__ __forceinline__ void operator()(f32x4 (&acc)[2][2][4][2], const Unit& u, int wr, int wc, int fr, int fq) const {
;     ...
;         for (int i = 0; i < 16; ++i) {
;             const int ai = i >> 3, m = (i >> 1) & 3, bj = i & 1;
;             acc[ai][bj][m][0] += x0q[i]; acc[ai][bj][m][1] += x1q[i];
;             asm volatile("" ::: "memory");
;             if (i + DEPTH < 16) { EPN_LOAD(i + DEPTH); asm volatile("" ::: "memory"); }
;             if (bj == 1) {
;                 float q = 0.f;
; #pragma unroll
;                 for (int b2 = 0; b2 < 2; ++b2)
; #pragma unroll
;                     for (int n = 0; n < 2; ++n) { const f32x4 v = acc[ai][b2][m][n]; q += (v[0] * v[0] + v[1] * v[1]) + (v[2] * v[2] + v[3] * v[3]); }
;                 q += __shfl_xor(q, 16); q += __shfl_xor(q, 32);
;                 if (fq == 0) atomicAdd(SS + row0 + ai * HALF + m * 16, q);
;                 if constexpr (!FINAL) {
;                     float am = 0.f;
; #pragma unroll
;                     for (int b2 = 0; b2 < 2; ++b2)
; #pragma unroll
;                         for (int n = 0; n < 2; ++n) { const f32x4 v = acc[ai][b2][m][n] * gv[b2][n]; am = fmaxf(am, fmaxf(fmaxf(fabsf(v[0]), fabsf(v[1])), fmaxf(fabsf(v[2]), fabsf(v[3])))); }
;                     am = fmaxf(am, __shfl_xor(am, 16)); am = fmaxf(am, __shfl_xor(am, 32));
;                     if (fq == 0) atomicMax(AM + row0 + ai * HALF + m * 16, __float_as_uint(am));
;                 }
;             }
	v_pk_add_f32 v[96:97], v[96:97], v[164:165]
	v_pk_add_f32 v[94:95], v[94:95], v[162:163]
	s_waitcnt vmcnt(14)
	v_pk_add_f32 v[92:93], v[92:93], v[168:169]
	v_pk_add_f32 v[90:91], v[90:91], v[166:167]
	s_waitcnt vmcnt(13)
	v_pk_add_f32 v[88:89], v[88:89], v[172:173]
	v_pk_add_f32 v[86:87], v[86:87], v[170:171]
	v_mul_f32_e32 v162, v95, v95
	v_mul_f32_e32 v163, v97, v97
	v_mul_f32_e32 v164, v91, v91
	v_mul_f32_e32 v165, v93, v93
	s_waitcnt vmcnt(12)
	v_pk_add_f32 v[84:85], v[84:85], v[180:181]
	v_pk_add_f32 v[82:83], v[82:83], v[178:179]
	v_mul_f32_e32 v166, v87, v87
	v_mul_f32_e32 v167, v89, v89
	v_fmac_f32_e32 v162, v94, v94
	v_fmac_f32_e32 v163, v96, v96
	v_fmac_f32_e32 v164, v90, v90
	v_fmac_f32_e32 v165, v92, v92
	v_mul_f32_e32 v168, v83, v83
	v_mul_f32_e32 v169, v85, v85
	v_fmac_f32_e32 v166, v86, v86
	v_fmac_f32_e32 v167, v88, v88
	v_add_f32_e32 v162, v162, v163
	v_add_f32_e32 v163, v164, v165
	v_fmac_f32_e32 v168, v82, v82
	v_fmac_f32_e32 v169, v84, v84
	v_add_f32_e32 v164, v166, v167
	v_add_f32_e32 v162, v162, v163
	v_cndmask_b32_e32 v214, v239, v214, vcc
	v_add_f32_e32 v165, v168, v169
	v_add_f32_e32 v162, v162, v164
	v_lshlrev_b32_e32 v244, 2, v214
	v_add_f32_e32 v162, v162, v165
	v_mov_b32_e32 v163, v162
	s_nop 1
	v_permlane16_swap_b32_e32 v162, v163
	s_nop 0
	v_xor_b32_e32 v164, 32, v239
	v_cmp_lt_i32_e64 s[6:7], v164, v215
	v_cmp_eq_u32_e32 vcc, 0, v242
	s_waitcnt lgkmcnt(0)
	v_add_f32_e32 v162, v162, v163
	v_cndmask_b32_e64 v164, v239, v164, s[6:7]
	v_lshlrev_b32_e32 v245, 2, v164
	v_mov_b32_e32 v163, v162
	s_nop 1
	v_permlane32_swap_b32_e32 v162, v163
	s_nop 0
	s_and_saveexec_b64 s[0:1], vcc
	s_cbranch_execz .LBB0_1375
	s_waitcnt lgkmcnt(0)
	v_add_f32_e32 v162, v162, v163
	global_atomic_add_f32 v[230:231], v162, off
.LBB0_1375:
	s_or_b64 exec, exec, s[0:1]
	s_waitcnt lgkmcnt(0)
	s_waitcnt vmcnt(10)
	v_pk_mul_f32 v[162:163], v[16:17], v[96:97]
	v_pk_mul_f32 v[164:165], v[14:15], v[94:95]
	v_max_f32_e64 v162, |v162|, |v163|
	v_max3_f32 v166, |v164|, |v165|, v162
	v_pk_mul_f32 v[162:163], v[12:13], v[92:93]
	v_pk_mul_f32 v[164:165], v[10:11], v[90:91]
	v_max_f32_e64 v162, |v162|, |v163|
	v_max3_f32 v162, |v164|, |v165|, v162
	v_max3_f32 v166, v166, 0, v162
	s_waitcnt vmcnt(8)
	v_pk_mul_f32 v[162:163], v[8:9], v[88:89]
	v_pk_mul_f32 v[164:165], v[6:7], v[86:87]
	v_max_f32_e64 v162, |v162|, |v163|
	v_max3_f32 v167, |v164|, |v165|, v162
	v_pk_mul_f32 v[162:163], v[4:5], v[84:85]
	v_pk_mul_f32 v[164:165], v[2:3], v[82:83]
	v_max_f32_e64 v162, |v162|, |v163|
	v_max3_f32 v162, |v164|, |v165|, v162
	v_max3_f32 v162, v166, v167, v162
	v_mov_b32_e32 v163, v162
	s_nop 1
	v_permlane16_swap_b32_e32 v162, v163
	s_nop 0
	v_lshl_add_u64 v[232:233], v[224:225], 2, s[24:25]
	s_waitcnt lgkmcnt(0)
	v_max_f32_e32 v163, v163, v163
	v_max_f32_e32 v162, v162, v163
	v_mov_b32_e32 v163, v162
	s_nop 1
	v_permlane32_swap_b32_e32 v162, v163
	s_nop 0
	s_and_saveexec_b64 s[0:1], vcc
	s_cbranch_execz .LBB0_1377
	s_waitcnt lgkmcnt(0)
	v_max_f32_e32 v163, v163, v163
	v_max_f32_e32 v162, v162, v162
	v_max_f32_e32 v162, v162, v163
	global_atomic_umax v[232:233], v162, off
.LBB0_1377:
	s_or_b64 exec, exec, s[0:1]
	v_add_u32_e32 v214, 48, v224
	v_ashrrev_i32_e32 v215, 31, v214
	s_waitcnt lgkmcnt(0)
	v_lshlrev_b64 v[162:163], 12, v[214:215]
	v_lshl_add_u64 v[162:163], s[12:13], 0, v[162:163]
	v_lshl_add_u64 v[178:179], v[210:211], 2, v[162:163]
	global_load_dwordx4 v[162:165], v[178:179], off offset:16
	global_load_dwordx4 v[166:169], v[178:179], off
	global_load_dwordx4 v[170:173], v[178:179], off offset:528
	s_nop 0
	global_load_dwordx4 v[178:181], v[178:179], off offset:512
	s_waitcnt vmcnt(10)
	v_pk_add_f32 v[112:113], v[112:113], v[192:193]
	v_pk_add_f32 v[110:111], v[110:111], v[190:191]
	s_waitcnt vmcnt(9)
	v_pk_add_f32 v[98:99], v[98:99], v[174:175]
	v_mul_f32_e32 v174, v111, v111
	v_mul_f32_e32 v175, v113, v113
	v_pk_add_f32 v[108:109], v[108:109], v[184:185]
	v_pk_add_f32 v[106:107], v[106:107], v[182:183]
	v_fmac_f32_e32 v174, v110, v110
	v_fmac_f32_e32 v175, v112, v112
	v_pk_add_f32 v[100:101], v[100:101], v[176:177]
	v_add_f32_e32 v174, v174, v175
	v_mul_f32_e32 v175, v107, v107
	v_mul_f32_e32 v176, v109, v109
	v_fmac_f32_e32 v175, v106, v106
	v_fmac_f32_e32 v176, v108, v108
	s_waitcnt vmcnt(8)
	v_pk_add_f32 v[104:105], v[104:105], v[188:189]
	v_pk_add_f32 v[102:103], v[102:103], v[186:187]
	v_add_f32_e32 v175, v175, v176
	v_add_f32_e32 v174, v174, v175
	v_mul_f32_e32 v175, v103, v103
	v_mul_f32_e32 v176, v105, v105
	v_fmac_f32_e32 v175, v102, v102
	v_fmac_f32_e32 v176, v104, v104
	v_add_f32_e32 v175, v175, v176
	v_add_f32_e32 v174, v174, v175
	v_mul_f32_e32 v175, v99, v99
	v_mul_f32_e32 v176, v101, v101
	v_fmac_f32_e32 v175, v98, v98
	v_fmac_f32_e32 v176, v100, v100
	v_add_f32_e32 v175, v175, v176
	v_add_f32_e32 v174, v174, v175
	v_mov_b32_e32 v175, v174
	s_nop 1
	v_permlane16_swap_b32_e32 v174, v175
	s_nop 0
	s_waitcnt lgkmcnt(0)
	v_add_f32_e32 v174, v174, v175
	v_mov_b32_e32 v175, v174
	s_nop 1
	v_permlane32_swap_b32_e32 v174, v175
	s_nop 0
	s_and_saveexec_b64 s[0:1], vcc
	s_cbranch_execz .LBB0_1379
	s_waitcnt lgkmcnt(0)
	v_add_f32_e32 v174, v174, v175
	global_atomic_add_f32 v[230:231], v174, off offset:64
; #define EPN_LOAD(i) do { const size_t off_ = EPN_OFF(i); x0q[i] = *(const f32x4*)(xin + off_); x1q[i] = *(const f32x4*)(xin + off_ + 4); } while (0)
;     __device__ __forceinline__ void operator()(f32x4 (&acc)[2][2][4][2], const Unit& u, int wr, int wc, int fr, int fq) const {
;     ...
;         for (int i = 0; i < 16; ++i) {
;             const int ai = i >> 3, m = (i >> 1) & 3, bj = i & 1;
;             acc[ai][bj][m][0] += x0q[i]; acc[ai][bj][m][1] += x1q[i];
;             asm volatile("" ::: "memory");
;             if (i + DEPTH < 16) { EPN_LOAD(i + DEPTH); asm volatile("" ::: "memory"); }
;             if (bj == 1) {
;                 float q = 0.f;
; #pragma unroll
;                 for (int b2 = 0; b2 < 2; ++b2)
; #pragma unroll
;                     for (int n = 0; n < 2; ++n) { const f32x4 v = acc[ai][b2][m][n]; q += (v[0] * v[0] + v[1] * v[1]) + (v[2] * v[2] + v[3] * v[3]); }
;                 q += __shfl_xor(q, 16); q += __shfl_xor(q, 32);
;                 if (fq == 0) atomicAdd(SS + row0 + ai * HALF + m * 16, q);
;                 if constexpr (!FINAL) {
;                     float am = 0.f;
; #pragma unroll
;                     for (int b2 = 0; b2 < 2; ++b2)
; #pragma unroll
;                         for (int n = 0; n < 2; ++n) { const f32x4 v = acc[ai][b2][m][n] * gv[b2][n]; am = fmaxf(am, fmaxf(fmaxf(fabsf(v[0]), fabsf(v[1])), fmaxf(fabsf(v[2]), fabsf(v[3])))); }
;                     am = fmaxf(am, __shfl_xor(am, 16)); am = fmaxf(am, __shfl_xor(am, 32));
;                     if (fq == 0) atomicMax(AM + row0 + ai * HALF + m * 16, __float_as_uint(am));
;                 }
;             }
.LBB0_1379:
	s_or_b64 exec, exec, s[0:1]
	s_waitcnt lgkmcnt(0)
	v_pk_mul_f32 v[174:175], v[16:17], v[112:113]
	v_pk_mul_f32 v[176:177], v[14:15], v[110:111]
	v_max_f32_e64 v174, |v174|, |v175|
	v_max3_f32 v182, |v176|, |v177|, v174
	v_pk_mul_f32 v[174:175], v[12:13], v[108:109]
	v_pk_mul_f32 v[176:177], v[10:11], v[106:107]
	v_max_f32_e64 v174, |v174|, |v175|
	v_max3_f32 v174, |v176|, |v177|, v174
	v_max3_f32 v182, v182, 0, v174
	v_pk_mul_f32 v[174:175], v[8:9], v[104:105]
	v_pk_mul_f32 v[176:177], v[6:7], v[102:103]
	v_max_f32_e64 v174, |v174|, |v175|
	v_max3_f32 v183, |v176|, |v177|, v174
	v_pk_mul_f32 v[174:175], v[4:5], v[100:101]
	v_pk_mul_f32 v[176:177], v[2:3], v[98:99]
	v_max_f32_e64 v174, |v174|, |v175|
	v_max3_f32 v174, |v176|, |v177|, v174
	v_max3_f32 v174, v182, v183, v174
	v_mov_b32_e32 v175, v174
	s_nop 1
	v_permlane16_swap_b32_e32 v174, v175
	s_nop 0
	s_waitcnt lgkmcnt(0)
	v_max_f32_e32 v175, v175, v175
	v_max_f32_e32 v174, v174, v175
	v_mov_b32_e32 v175, v174
	s_nop 1
	v_permlane32_swap_b32_e32 v174, v175
	s_nop 0
	s_and_saveexec_b64 s[0:1], vcc
	s_cbranch_execz .LBB0_1381
	s_waitcnt lgkmcnt(0)
	v_max_f32_e32 v175, v175, v175
	v_max_f32_e32 v174, v174, v174
	v_max_f32_e32 v174, v174, v175
	global_atomic_umax v[232:233], v174, off offset:64
.LBB0_1381:
	s_or_b64 exec, exec, s[0:1]
	v_add_u32_e32 v218, 0x80, v224
	v_ashrrev_i32_e32 v219, 31, v218
	s_waitcnt lgkmcnt(0)
	v_lshlrev_b64 v[174:175], 12, v[218:219]
	v_lshl_add_u64 v[174:175], s[12:13], 0, v[174:175]
	v_lshl_add_u64 v[190:191], v[210:211], 2, v[174:175]
	global_load_dwordx4 v[174:177], v[190:191], off offset:16
	global_load_dwordx4 v[182:185], v[190:191], off
	global_load_dwordx4 v[186:189], v[190:191], off offset:528
	s_nop 0
	global_load_dwordx4 v[190:193], v[190:191], off offset:512
	s_waitcnt vmcnt(10)
	v_pk_add_f32 v[132:133], v[132:133], v[152:153]
	v_pk_add_f32 v[130:131], v[130:131], v[150:151]
	v_pk_add_f32 v[122:123], v[122:123], v[146:147]
	v_mul_f32_e32 v146, v131, v131
	v_mul_f32_e32 v147, v133, v133
	v_pk_add_f32 v[124:125], v[124:125], v[148:149]
	v_fmac_f32_e32 v146, v130, v130
	v_fmac_f32_e32 v147, v132, v132
	v_add_f32_e32 v146, v146, v147
	v_mul_f32_e32 v147, v123, v123
	v_mul_f32_e32 v148, v125, v125
	v_fmac_f32_e32 v147, v122, v122
	v_fmac_f32_e32 v148, v124, v124
	s_waitcnt vmcnt(8)
	v_pk_add_f32 v[120:121], v[120:121], v[160:161]
	v_pk_add_f32 v[118:119], v[118:119], v[158:159]
	v_add_f32_e32 v147, v147, v148
	v_add_f32_e32 v146, v146, v147
	v_mul_f32_e32 v147, v119, v119
	v_mul_f32_e32 v148, v121, v121
	v_fmac_f32_e32 v147, v118, v118
	v_fmac_f32_e32 v148, v120, v120
	v_pk_add_f32 v[116:117], v[116:117], v[156:157]
	v_pk_add_f32 v[114:115], v[114:115], v[154:155]
	v_add_f32_e32 v147, v147, v148
	v_add_f32_e32 v146, v146, v147
	v_mul_f32_e32 v147, v115, v115
	v_mul_f32_e32 v148, v117, v117
	v_fmac_f32_e32 v147, v114, v114
	v_fmac_f32_e32 v148, v116, v116
	v_add_f32_e32 v147, v147, v148
	v_add_f32_e32 v146, v146, v147
	v_mov_b32_e32 v147, v146
	s_nop 1
	v_permlane16_swap_b32_e32 v146, v147
	s_nop 0
	s_waitcnt lgkmcnt(0)
	v_add_f32_e32 v146, v146, v147
	v_mov_b32_e32 v147, v146
	s_nop 1
	v_permlane32_swap_b32_e32 v146, v147
	s_nop 0
	s_and_saveexec_b64 s[0:1], vcc
	s_cbranch_execz .LBB0_1383
	s_waitcnt lgkmcnt(0)
	v_add_f32_e32 v146, v146, v147
	global_atomic_add_f32 v[230:231], v146, off offset:128
.LBB0_1383:
	s_or_b64 exec, exec, s[0:1]
	s_waitcnt lgkmcnt(0)
	v_pk_mul_f32 v[146:147], v[16:17], v[132:133]
	v_pk_mul_f32 v[148:149], v[14:15], v[130:131]
	v_max_f32_e64 v146, |v146|, |v147|
	v_max3_f32 v150, |v148|, |v149|, v146
	v_pk_mul_f32 v[146:147], v[12:13], v[124:125]
	v_pk_mul_f32 v[148:149], v[10:11], v[122:123]
	v_max_f32_e64 v146, |v146|, |v147|
	v_max3_f32 v146, |v148|, |v149|, v146
	v_max3_f32 v150, v150, 0, v146
	v_pk_mul_f32 v[146:147], v[8:9], v[120:121]
	v_pk_mul_f32 v[148:149], v[6:7], v[118:119]
	v_max_f32_e64 v146, |v146|, |v147|
	v_max3_f32 v151, |v148|, |v149|, v146
	v_pk_mul_f32 v[146:147], v[4:5], v[116:117]
	v_pk_mul_f32 v[148:149], v[2:3], v[114:115]
	v_max_f32_e64 v146, |v146|, |v147|
	v_max3_f32 v146, |v148|, |v149|, v146
	v_max3_f32 v146, v150, v151, v146
	v_mov_b32_e32 v147, v146
	s_nop 1
	v_permlane16_swap_b32_e32 v146, v147
	s_nop 0
	s_waitcnt lgkmcnt(0)
	v_max_f32_e32 v147, v147, v147
	v_max_f32_e32 v146, v146, v147
	v_mov_b32_e32 v147, v146
	s_nop 1
	v_permlane32_swap_b32_e32 v146, v147
	s_nop 0
	s_and_saveexec_b64 s[0:1], vcc
	s_cbranch_execz .LBB0_1385
	s_waitcnt lgkmcnt(0)
	v_max_f32_e32 v147, v147, v147
	v_max_f32_e32 v146, v146, v146
	v_max_f32_e32 v146, v146, v147
	global_atomic_umax v[232:233], v146, off offset:128
; #define EPN_LOAD(i) do { const size_t off_ = EPN_OFF(i); x0q[i] = *(const f32x4*)(xin + off_); x1q[i] = *(const f32x4*)(xin + off_ + 4); } while (0)
;     __device__ __forceinline__ void operator()(f32x4 (&acc)[2][2][4][2], const Unit& u, int wr, int wc, int fr, int fq) const {
;     ...
;         for (int i = 0; i < 16; ++i) {
;             const int ai = i >> 3, m = (i >> 1) & 3, bj = i & 1;
;             acc[ai][bj][m][0] += x0q[i]; acc[ai][bj][m][1] += x1q[i];
;             asm volatile("" ::: "memory");
;             if (i + DEPTH < 16) { EPN_LOAD(i + DEPTH); asm volatile("" ::: "memory"); }
;             if (bj == 1) {
;                 float q = 0.f;
; #pragma unroll
;                 for (int b2 = 0; b2 < 2; ++b2)
; #pragma unroll
;                     for (int n = 0; n < 2; ++n) { const f32x4 v = acc[ai][b2][m][n]; q += (v[0] * v[0] + v[1] * v[1]) + (v[2] * v[2] + v[3] * v[3]); }
;                 q += __shfl_xor(q, 16); q += __shfl_xor(q, 32);
;                 if (fq == 0) atomicAdd(SS + row0 + ai * HALF + m * 16, q);
;                 if constexpr (!FINAL) {
;                     float am = 0.f;
; #pragma unroll
;                     for (int b2 = 0; b2 < 2; ++b2)
; #pragma unroll
;                         for (int n = 0; n < 2; ++n) { const f32x4 v = acc[ai][b2][m][n] * gv[b2][n]; am = fmaxf(am, fmaxf(fmaxf(fabsf(v[0]), fabsf(v[1])), fmaxf(fabsf(v[2]), fabsf(v[3])))); }
;                     am = fmaxf(am, __shfl_xor(am, 16)); am = fmaxf(am, __shfl_xor(am, 32));
;                     if (fq == 0) atomicMax(AM + row0 + ai * HALF + m * 16, __float_as_uint(am));
;                 }
;             }
.LBB0_1385:
	s_or_b64 exec, exec, s[0:1]
	v_add_u32_e32 v220, 0x90, v224
	v_ashrrev_i32_e32 v221, 31, v220
	s_waitcnt lgkmcnt(0)
	v_lshlrev_b64 v[146:147], 12, v[220:221]
	v_lshl_add_u64 v[146:147], s[12:13], 0, v[146:147]
	v_lshl_add_u64 v[158:159], v[210:211], 2, v[146:147]
	global_load_dwordx4 v[146:149], v[158:159], off offset:16
	global_load_dwordx4 v[150:153], v[158:159], off
	global_load_dwordx4 v[154:157], v[158:159], off offset:528
	s_nop 0
	global_load_dwordx4 v[158:161], v[158:159], off offset:512
	s_waitcnt vmcnt(10)
	v_pk_add_f32 v[144:145], v[144:145], v[168:169]
	v_pk_add_f32 v[142:143], v[142:143], v[166:167]
	v_pk_add_f32 v[138:139], v[138:139], v[162:163]
	v_mul_f32_e32 v162, v143, v143
	v_mul_f32_e32 v163, v145, v145
	v_pk_add_f32 v[140:141], v[140:141], v[164:165]
	v_fmac_f32_e32 v162, v142, v142
	v_fmac_f32_e32 v163, v144, v144
	v_add_f32_e32 v162, v162, v163
	v_mul_f32_e32 v163, v139, v139
	v_mul_f32_e32 v164, v141, v141
	v_fmac_f32_e32 v163, v138, v138
	v_fmac_f32_e32 v164, v140, v140
	s_waitcnt vmcnt(8)
	v_pk_add_f32 v[136:137], v[136:137], v[180:181]
	v_pk_add_f32 v[134:135], v[134:135], v[178:179]
	v_add_f32_e32 v163, v163, v164
	v_add_f32_e32 v162, v162, v163
	v_mul_f32_e32 v163, v135, v135
	v_mul_f32_e32 v164, v137, v137
	v_fmac_f32_e32 v163, v134, v134
	v_fmac_f32_e32 v164, v136, v136
	v_pk_add_f32 v[128:129], v[128:129], v[172:173]
	v_pk_add_f32 v[126:127], v[126:127], v[170:171]
	v_add_f32_e32 v163, v163, v164
	v_add_f32_e32 v162, v162, v163
	v_mul_f32_e32 v163, v127, v127
	v_mul_f32_e32 v164, v129, v129
	v_fmac_f32_e32 v163, v126, v126
	v_fmac_f32_e32 v164, v128, v128
	v_add_f32_e32 v163, v163, v164
	v_add_f32_e32 v162, v162, v163
	v_mov_b32_e32 v163, v162
	s_nop 1
	v_permlane16_swap_b32_e32 v162, v163
	s_nop 0
	s_waitcnt lgkmcnt(0)
	v_add_f32_e32 v162, v162, v163
	v_mov_b32_e32 v163, v162
	s_nop 1
	v_permlane32_swap_b32_e32 v162, v163
	s_nop 0
	s_and_saveexec_b64 s[0:1], vcc
	s_cbranch_execz .LBB0_1387
	s_waitcnt lgkmcnt(0)
	v_add_f32_e32 v162, v162, v163
	global_atomic_add_f32 v[230:231], v162, off offset:192
.LBB0_1387:
	s_or_b64 exec, exec, s[0:1]
	s_waitcnt lgkmcnt(0)
	v_pk_mul_f32 v[162:163], v[16:17], v[144:145]
	v_pk_mul_f32 v[164:165], v[14:15], v[142:143]
	v_max_f32_e64 v162, |v162|, |v163|
	v_max3_f32 v166, |v164|, |v165|, v162
	v_pk_mul_f32 v[162:163], v[12:13], v[140:141]
	v_pk_mul_f32 v[164:165], v[10:11], v[138:139]
	v_max_f32_e64 v162, |v162|, |v163|
	v_max3_f32 v162, |v164|, |v165|, v162
	v_max3_f32 v166, v166, 0, v162
	v_pk_mul_f32 v[162:163], v[8:9], v[136:137]
	v_pk_mul_f32 v[164:165], v[6:7], v[134:135]
	v_max_f32_e64 v162, |v162|, |v163|
	v_max3_f32 v167, |v164|, |v165|, v162
	v_pk_mul_f32 v[162:163], v[4:5], v[128:129]
	v_pk_mul_f32 v[164:165], v[2:3], v[126:127]
	v_max_f32_e64 v162, |v162|, |v163|
	v_max3_f32 v162, |v164|, |v165|, v162
	v_max3_f32 v162, v166, v167, v162
	v_mov_b32_e32 v163, v162
	s_nop 1
	v_permlane16_swap_b32_e32 v162, v163
	s_nop 0
	s_waitcnt lgkmcnt(0)
	v_max_f32_e32 v163, v163, v163
	v_max_f32_e32 v162, v162, v163
	v_mov_b32_e32 v163, v162
	s_nop 1
	v_permlane32_swap_b32_e32 v162, v163
	s_nop 0
	s_and_saveexec_b64 s[0:1], vcc
	s_cbranch_execz .LBB0_1389
	s_waitcnt lgkmcnt(0)
	v_max_f32_e32 v163, v163, v163
	v_max_f32_e32 v162, v162, v162
	v_max_f32_e32 v162, v162, v163
	global_atomic_umax v[232:233], v162, off offset:192
.LBB0_1389:
	s_or_b64 exec, exec, s[0:1]
	v_add_u32_e32 v222, 0xa0, v224
	v_ashrrev_i32_e32 v223, 31, v222
	s_waitcnt lgkmcnt(0)
	v_lshlrev_b64 v[162:163], 12, v[222:223]
	v_lshl_add_u64 v[162:163], s[12:13], 0, v[162:163]
	v_lshl_add_u64 v[178:179], v[210:211], 2, v[162:163]
	global_load_dwordx4 v[162:165], v[178:179], off offset:16
	global_load_dwordx4 v[170:173], v[178:179], off
	global_load_dwordx4 v[166:169], v[178:179], off offset:528
	s_nop 0
	global_load_dwordx4 v[178:181], v[178:179], off offset:512
	s_waitcnt vmcnt(10)
	v_pk_add_f32 v[80:81], v[80:81], v[184:185]
	v_pk_add_f32 v[78:79], v[78:79], v[182:183]
	v_pk_add_f32 v[74:75], v[74:75], v[174:175]
	v_mul_f32_e32 v174, v79, v79
	v_mul_f32_e32 v175, v81, v81
	v_pk_add_f32 v[76:77], v[76:77], v[176:177]
	v_fmac_f32_e32 v174, v78, v78
	v_fmac_f32_e32 v175, v80, v80
	v_add_f32_e32 v174, v174, v175
	v_mul_f32_e32 v175, v75, v75
	v_mul_f32_e32 v176, v77, v77
	v_fmac_f32_e32 v175, v74, v74
	v_fmac_f32_e32 v176, v76, v76
	s_waitcnt vmcnt(8)
	v_pk_add_f32 v[72:73], v[72:73], v[192:193]
	v_pk_add_f32 v[70:71], v[70:71], v[190:191]
	v_add_f32_e32 v175, v175, v176
	v_add_f32_e32 v174, v174, v175
	v_mul_f32_e32 v175, v71, v71
	v_mul_f32_e32 v176, v73, v73
	v_fmac_f32_e32 v175, v70, v70
	v_fmac_f32_e32 v176, v72, v72
	v_pk_add_f32 v[68:69], v[68:69], v[188:189]
	v_pk_add_f32 v[66:67], v[66:67], v[186:187]
	v_add_f32_e32 v175, v175, v176
	v_add_f32_e32 v174, v174, v175
	v_mul_f32_e32 v175, v67, v67
	v_mul_f32_e32 v176, v69, v69
	v_fmac_f32_e32 v175, v66, v66
	v_fmac_f32_e32 v176, v68, v68
	v_add_f32_e32 v175, v175, v176
	v_add_f32_e32 v174, v174, v175
	v_mov_b32_e32 v175, v174
	s_nop 1
	v_permlane16_swap_b32_e32 v174, v175
	s_nop 0
	s_waitcnt lgkmcnt(0)
	v_add_f32_e32 v174, v174, v175
	v_mov_b32_e32 v175, v174
	s_nop 1
	v_permlane32_swap_b32_e32 v174, v175
	s_nop 0
	s_and_saveexec_b64 s[0:1], vcc
	s_cbranch_execz .LBB0_1391
	s_waitcnt lgkmcnt(0)
	v_add_f32_e32 v174, v174, v175
	global_atomic_add_f32 v[230:231], v174, off offset:512
; #define EPN_LOAD(i) do { const size_t off_ = EPN_OFF(i); x0q[i] = *(const f32x4*)(xin + off_); x1q[i] = *(const f32x4*)(xin + off_ + 4); } while (0)
;     __device__ __forceinline__ void operator()(f32x4 (&acc)[2][2][4][2], const Unit& u, int wr, int wc, int fr, int fq) const {
;     ...
;         for (int i = 0; i < 16; ++i) {
;             const int ai = i >> 3, m = (i >> 1) & 3, bj = i & 1;
;             acc[ai][bj][m][0] += x0q[i]; acc[ai][bj][m][1] += x1q[i];
;             asm volatile("" ::: "memory");
;             if (i + DEPTH < 16) { EPN_LOAD(i + DEPTH); asm volatile("" ::: "memory"); }
;             if (bj == 1) {
;                 float q = 0.f;
; #pragma unroll
;                 for (int b2 = 0; b2 < 2; ++b2)
; #pragma unroll
;                     for (int n = 0; n < 2; ++n) { const f32x4 v = acc[ai][b2][m][n]; q += (v[0] * v[0] + v[1] * v[1]) + (v[2] * v[2] + v[3] * v[3]); }
;                 q += __shfl_xor(q, 16); q += __shfl_xor(q, 32);
;                 if (fq == 0) atomicAdd(SS + row0 + ai * HALF + m * 16, q);
;                 if constexpr (!FINAL) {
;                     float am = 0.f;
; #pragma unroll
;                     for (int b2 = 0; b2 < 2; ++b2)
; #pragma unroll
;                         for (int n = 0; n < 2; ++n) { const f32x4 v = acc[ai][b2][m][n] * gv[b2][n]; am = fmaxf(am, fmaxf(fmaxf(fabsf(v[0]), fabsf(v[1])), fmaxf(fabsf(v[2]), fabsf(v[3])))); }
;                     am = fmaxf(am, __shfl_xor(am, 16)); am = fmaxf(am, __shfl_xor(am, 32));
;                     if (fq == 0) atomicMax(AM + row0 + ai * HALF + m * 16, __float_as_uint(am));
;                 }
;             }
.LBB0_1391:
	s_or_b64 exec, exec, s[0:1]
	s_waitcnt lgkmcnt(0)
	v_pk_mul_f32 v[174:175], v[16:17], v[80:81]
	v_pk_mul_f32 v[176:177], v[14:15], v[78:79]
	v_max_f32_e64 v174, |v174|, |v175|
	v_max3_f32 v182, |v176|, |v177|, v174
	v_pk_mul_f32 v[174:175], v[12:13], v[76:77]
	v_pk_mul_f32 v[176:177], v[10:11], v[74:75]
	v_max_f32_e64 v174, |v174|, |v175|
	v_max3_f32 v174, |v176|, |v177|, v174
	v_max3_f32 v182, v182, 0, v174
	v_pk_mul_f32 v[174:175], v[8:9], v[72:73]
	v_pk_mul_f32 v[176:177], v[6:7], v[70:71]
	v_max_f32_e64 v174, |v174|, |v175|
	v_max3_f32 v183, |v176|, |v177|, v174
	v_pk_mul_f32 v[174:175], v[4:5], v[68:69]
	v_pk_mul_f32 v[176:177], v[2:3], v[66:67]
	v_max_f32_e64 v174, |v174|, |v175|
	v_max3_f32 v174, |v176|, |v177|, v174
	v_max3_f32 v174, v182, v183, v174
	v_mov_b32_e32 v175, v174
	s_nop 1
	v_permlane16_swap_b32_e32 v174, v175
	s_nop 0
	s_waitcnt lgkmcnt(0)
	v_max_f32_e32 v175, v175, v175
	v_max_f32_e32 v174, v174, v175
	v_mov_b32_e32 v175, v174
	s_nop 1
	v_permlane32_swap_b32_e32 v174, v175
	s_nop 0
	s_and_saveexec_b64 s[0:1], vcc
	s_cbranch_execz .LBB0_1393
	s_waitcnt lgkmcnt(0)
	v_max_f32_e32 v175, v175, v175
	v_max_f32_e32 v174, v174, v174
	v_max_f32_e32 v174, v174, v175
	global_atomic_umax v[232:233], v174, off offset:512
.LBB0_1393:
	s_or_b64 exec, exec, s[0:1]
	v_add_u32_e32 v226, 0xb0, v224
	v_ashrrev_i32_e32 v227, 31, v226
	s_waitcnt lgkmcnt(0)
	v_lshlrev_b64 v[174:175], 12, v[226:227]
	v_lshl_add_u64 v[174:175], s[12:13], 0, v[174:175]
	v_lshl_add_u64 v[190:191], v[210:211], 2, v[174:175]
	global_load_dwordx4 v[174:177], v[190:191], off offset:16
	global_load_dwordx4 v[186:189], v[190:191], off
	global_load_dwordx4 v[182:185], v[190:191], off offset:528
	s_nop 0
	global_load_dwordx4 v[190:193], v[190:191], off offset:512
	s_waitcnt vmcnt(10)
	v_pk_add_f32 v[64:65], v[64:65], v[152:153]
	v_pk_add_f32 v[62:63], v[62:63], v[150:151]
	v_pk_add_f32 v[58:59], v[58:59], v[146:147]
	v_mul_f32_e32 v146, v63, v63
	v_mul_f32_e32 v147, v65, v65
	v_pk_add_f32 v[60:61], v[60:61], v[148:149]
	v_fmac_f32_e32 v146, v62, v62
	v_fmac_f32_e32 v147, v64, v64
	v_add_f32_e32 v146, v146, v147
	v_mul_f32_e32 v147, v59, v59
	v_mul_f32_e32 v148, v61, v61
	v_fmac_f32_e32 v147, v58, v58
	v_fmac_f32_e32 v148, v60, v60
	s_waitcnt vmcnt(8)
	v_pk_add_f32 v[56:57], v[56:57], v[160:161]
	v_pk_add_f32 v[54:55], v[54:55], v[158:159]
	v_add_f32_e32 v147, v147, v148
	v_add_f32_e32 v146, v146, v147
	v_mul_f32_e32 v147, v55, v55
	v_mul_f32_e32 v148, v57, v57
	v_fmac_f32_e32 v147, v54, v54
	v_fmac_f32_e32 v148, v56, v56
	v_pk_add_f32 v[52:53], v[52:53], v[156:157]
	v_pk_add_f32 v[50:51], v[50:51], v[154:155]
	v_add_f32_e32 v147, v147, v148
	v_add_f32_e32 v146, v146, v147
	v_mul_f32_e32 v147, v51, v51
	v_mul_f32_e32 v148, v53, v53
	v_fmac_f32_e32 v147, v50, v50
	v_fmac_f32_e32 v148, v52, v52
	v_add_f32_e32 v147, v147, v148
	v_add_f32_e32 v146, v146, v147
	v_mov_b32_e32 v147, v146
	s_nop 1
	v_permlane16_swap_b32_e32 v146, v147
	s_nop 0
	s_waitcnt lgkmcnt(0)
	v_add_f32_e32 v146, v146, v147
	v_mov_b32_e32 v147, v146
	s_nop 1
	v_permlane32_swap_b32_e32 v146, v147
	s_nop 0
	s_and_saveexec_b64 s[0:1], vcc
	s_cbranch_execz .LBB0_1395
	s_waitcnt lgkmcnt(0)
	v_add_f32_e32 v146, v146, v147
	global_atomic_add_f32 v[230:231], v146, off offset:576
.LBB0_1395:
	s_or_b64 exec, exec, s[0:1]
	s_waitcnt lgkmcnt(0)
	v_pk_mul_f32 v[146:147], v[16:17], v[64:65]
	v_pk_mul_f32 v[148:149], v[14:15], v[62:63]
	v_max_f32_e64 v146, |v146|, |v147|
	v_max3_f32 v150, |v148|, |v149|, v146
	v_pk_mul_f32 v[146:147], v[12:13], v[60:61]
	v_pk_mul_f32 v[148:149], v[10:11], v[58:59]
	v_max_f32_e64 v146, |v146|, |v147|
	v_max3_f32 v146, |v148|, |v149|, v146
	v_max3_f32 v150, v150, 0, v146
	v_pk_mul_f32 v[146:147], v[8:9], v[56:57]
	v_pk_mul_f32 v[148:149], v[6:7], v[54:55]
	v_max_f32_e64 v146, |v146|, |v147|
	v_max3_f32 v151, |v148|, |v149|, v146
	v_pk_mul_f32 v[146:147], v[4:5], v[52:53]
	v_pk_mul_f32 v[148:149], v[2:3], v[50:51]
	v_max_f32_e64 v146, |v146|, |v147|
	v_max3_f32 v146, |v148|, |v149|, v146
	v_max3_f32 v146, v150, v151, v146
	v_mov_b32_e32 v147, v146
	s_nop 1
	v_permlane16_swap_b32_e32 v146, v147
	s_nop 0
	s_waitcnt lgkmcnt(0)
	v_max_f32_e32 v147, v147, v147
	v_max_f32_e32 v146, v146, v147
	v_mov_b32_e32 v147, v146
	s_nop 1
	v_permlane32_swap_b32_e32 v146, v147
	s_nop 0
	s_and_saveexec_b64 s[0:1], vcc
	s_cbranch_execz .LBB0_1397
	s_waitcnt lgkmcnt(0)
	v_max_f32_e32 v147, v147, v147
	v_max_f32_e32 v146, v146, v146
	v_max_f32_e32 v146, v146, v147
	global_atomic_umax v[232:233], v146, off offset:576
; #define EPN_LOAD(i) do { const size_t off_ = EPN_OFF(i); x0q[i] = *(const f32x4*)(xin + off_); x1q[i] = *(const f32x4*)(xin + off_ + 4); } while (0)
;     __device__ __forceinline__ void operator()(f32x4 (&acc)[2][2][4][2], const Unit& u, int wr, int wc, int fr, int fq) const {
;     ...
;         for (int i = 0; i < 16; ++i) {
;             const int ai = i >> 3, m = (i >> 1) & 3, bj = i & 1;
;             acc[ai][bj][m][0] += x0q[i]; acc[ai][bj][m][1] += x1q[i];
;             asm volatile("" ::: "memory");
;             if (i + DEPTH < 16) { EPN_LOAD(i + DEPTH); asm volatile("" ::: "memory"); }
;             if (bj == 1) {
;                 float q = 0.f;
; #pragma unroll
;                 for (int b2 = 0; b2 < 2; ++b2)
; #pragma unroll
;                     for (int n = 0; n < 2; ++n) { const f32x4 v = acc[ai][b2][m][n]; q += (v[0] * v[0] + v[1] * v[1]) + (v[2] * v[2] + v[3] * v[3]); }
;                 q += __shfl_xor(q, 16); q += __shfl_xor(q, 32);
;                 if (fq == 0) atomicAdd(SS + row0 + ai * HALF + m * 16, q);
;                 if constexpr (!FINAL) {
;                     float am = 0.f;
; #pragma unroll
;                     for (int b2 = 0; b2 < 2; ++b2)
; #pragma unroll
;                         for (int n = 0; n < 2; ++n) { const f32x4 v = acc[ai][b2][m][n] * gv[b2][n]; am = fmaxf(am, fmaxf(fmaxf(fabsf(v[0]), fabsf(v[1])), fmaxf(fabsf(v[2]), fabsf(v[3])))); }
;                     am = fmaxf(am, __shfl_xor(am, 16)); am = fmaxf(am, __shfl_xor(am, 32));
;                     if (fq == 0) atomicMax(AM + row0 + ai * HALF + m * 16, __float_as_uint(am));
;                 }
;             }
.LBB0_1397:
	s_or_b64 exec, exec, s[0:1]
	s_waitcnt vmcnt(6)
	v_pk_add_f32 v[48:49], v[48:49], v[172:173]
	v_pk_add_f32 v[46:47], v[46:47], v[170:171]
	s_waitcnt lgkmcnt(0)
	v_mul_f32_e32 v147, v49, v49
	v_mul_f32_e32 v146, v47, v47
	v_pk_add_f32 v[44:45], v[44:45], v[164:165]
	v_pk_add_f32 v[42:43], v[42:43], v[162:163]
	v_fmac_f32_e32 v146, v46, v46
	v_fmac_f32_e32 v147, v48, v48
	v_add_f32_e32 v146, v146, v147
	v_mul_f32_e32 v147, v43, v43
	v_mul_f32_e32 v148, v45, v45
	v_fmac_f32_e32 v147, v42, v42
	v_fmac_f32_e32 v148, v44, v44
	s_waitcnt vmcnt(4)
	v_pk_add_f32 v[40:41], v[40:41], v[180:181]
	v_pk_add_f32 v[38:39], v[38:39], v[178:179]
	v_add_f32_e32 v147, v147, v148
	v_add_f32_e32 v146, v146, v147
	v_mul_f32_e32 v147, v39, v39
	v_mul_f32_e32 v148, v41, v41
	v_fmac_f32_e32 v147, v38, v38
	v_fmac_f32_e32 v148, v40, v40
	v_pk_add_f32 v[36:37], v[36:37], v[168:169]
	v_pk_add_f32 v[34:35], v[34:35], v[166:167]
	v_add_f32_e32 v147, v147, v148
	v_add_f32_e32 v146, v146, v147
	v_mul_f32_e32 v147, v35, v35
	v_mul_f32_e32 v148, v37, v37
	v_fmac_f32_e32 v147, v34, v34
	v_fmac_f32_e32 v148, v36, v36
	v_add_f32_e32 v147, v147, v148
	v_add_f32_e32 v146, v146, v147
	v_mov_b32_e32 v147, v146
	s_nop 1
	v_permlane16_swap_b32_e32 v146, v147
	s_nop 0
	s_waitcnt lgkmcnt(0)
	v_add_f32_e32 v146, v146, v147
	v_mov_b32_e32 v147, v146
	s_nop 1
	v_permlane32_swap_b32_e32 v146, v147
	s_nop 0
	s_and_saveexec_b64 s[0:1], vcc
	s_cbranch_execz .LBB0_1399
	s_waitcnt lgkmcnt(0)
	v_add_f32_e32 v146, v146, v147
	global_atomic_add_f32 v[230:231], v146, off offset:640
.LBB0_1399:
	s_or_b64 exec, exec, s[0:1]
	s_waitcnt lgkmcnt(0)
	v_pk_mul_f32 v[146:147], v[16:17], v[48:49]
	v_pk_mul_f32 v[148:149], v[14:15], v[46:47]
	v_max_f32_e64 v146, |v146|, |v147|
	v_max3_f32 v150, |v148|, |v149|, v146
	v_pk_mul_f32 v[146:147], v[12:13], v[44:45]
	v_pk_mul_f32 v[148:149], v[10:11], v[42:43]
	v_max_f32_e64 v146, |v146|, |v147|
	v_max3_f32 v146, |v148|, |v149|, v146
	v_max3_f32 v150, v150, 0, v146
	v_pk_mul_f32 v[146:147], v[8:9], v[40:41]
	v_pk_mul_f32 v[148:149], v[6:7], v[38:39]
	v_max_f32_e64 v146, |v146|, |v147|
	v_max3_f32 v151, |v148|, |v149|, v146
	v_pk_mul_f32 v[146:147], v[4:5], v[36:37]
	v_pk_mul_f32 v[148:149], v[2:3], v[34:35]
	v_max_f32_e64 v146, |v146|, |v147|
	v_max3_f32 v146, |v148|, |v149|, v146
	v_max3_f32 v146, v150, v151, v146
	v_mov_b32_e32 v147, v146
	s_nop 1
	v_permlane16_swap_b32_e32 v146, v147
	s_nop 0
	s_waitcnt lgkmcnt(0)
	v_max_f32_e32 v147, v147, v147
	v_max_f32_e32 v146, v146, v147
	v_mov_b32_e32 v147, v146
	s_nop 1
	v_permlane32_swap_b32_e32 v146, v147
	s_nop 0
	s_and_saveexec_b64 s[0:1], vcc
	s_cbranch_execz .LBB0_1401
	s_waitcnt lgkmcnt(0)
	v_max_f32_e32 v147, v147, v147
	v_max_f32_e32 v146, v146, v146
	v_max_f32_e32 v146, v146, v147
	global_atomic_umax v[232:233], v146, off offset:640
.LBB0_1401:
	s_or_b64 exec, exec, s[0:1]
	s_waitcnt vmcnt(2)
	v_pk_add_f32 v[32:33], v[32:33], v[188:189]
	v_pk_add_f32 v[30:31], v[30:31], v[186:187]
	s_waitcnt lgkmcnt(0)
	v_mul_f32_e32 v147, v33, v33
	v_mul_f32_e32 v146, v31, v31
	v_pk_add_f32 v[28:29], v[28:29], v[176:177]
	v_pk_add_f32 v[26:27], v[26:27], v[174:175]
	v_fmac_f32_e32 v146, v30, v30
	v_fmac_f32_e32 v147, v32, v32
	v_add_f32_e32 v146, v146, v147
	v_mul_f32_e32 v147, v27, v27
	v_mul_f32_e32 v148, v29, v29
	v_fmac_f32_e32 v147, v26, v26
	v_fmac_f32_e32 v148, v28, v28
	s_waitcnt vmcnt(0)
	v_pk_add_f32 v[24:25], v[24:25], v[192:193]
	v_pk_add_f32 v[22:23], v[22:23], v[190:191]
	v_add_f32_e32 v147, v147, v148
	v_add_f32_e32 v146, v146, v147
	v_mul_f32_e32 v147, v23, v23
	v_mul_f32_e32 v148, v25, v25
	v_fmac_f32_e32 v147, v22, v22
	v_fmac_f32_e32 v148, v24, v24
	v_pk_add_f32 v[20:21], v[20:21], v[184:185]
	v_pk_add_f32 v[18:19], v[18:19], v[182:183]
	v_add_f32_e32 v147, v147, v148
	v_add_f32_e32 v146, v146, v147
	v_mul_f32_e32 v147, v19, v19
	v_mul_f32_e32 v148, v21, v21
	v_fmac_f32_e32 v147, v18, v18
	v_fmac_f32_e32 v148, v20, v20
	v_add_f32_e32 v147, v147, v148
	v_add_f32_e32 v146, v146, v147
	v_mov_b32_e32 v147, v146
	s_nop 1
	v_permlane16_swap_b32_e32 v146, v147
	s_nop 0
	s_waitcnt lgkmcnt(0)
	v_add_f32_e32 v146, v146, v147
	v_mov_b32_e32 v147, v146
	s_nop 1
	v_permlane32_swap_b32_e32 v146, v147
	s_nop 0
	s_and_saveexec_b64 s[0:1], vcc
	s_cbranch_execz .LBB0_1403
	s_waitcnt lgkmcnt(0)
	v_add_f32_e32 v146, v146, v147
	global_atomic_add_f32 v[230:231], v146, off offset:704
.LBB0_1403:
	s_or_b64 exec, exec, s[0:1]
	s_waitcnt lgkmcnt(0)
	v_pk_mul_f32 v[146:147], v[16:17], v[32:33]
	v_pk_mul_f32 v[148:149], v[14:15], v[30:31]
	v_max_f32_e64 v146, |v146|, |v147|
	v_max3_f32 v150, |v148|, |v149|, v146
	v_pk_mul_f32 v[146:147], v[12:13], v[28:29]
	v_pk_mul_f32 v[148:149], v[10:11], v[26:27]
	v_max_f32_e64 v146, |v146|, |v147|
	v_max3_f32 v146, |v148|, |v149|, v146
	v_max3_f32 v150, v150, 0, v146
	v_pk_mul_f32 v[146:147], v[8:9], v[24:25]
	v_pk_mul_f32 v[148:149], v[6:7], v[22:23]
	v_max_f32_e64 v146, |v146|, |v147|
	v_max3_f32 v151, |v148|, |v149|, v146
	v_pk_mul_f32 v[146:147], v[4:5], v[20:21]
	v_pk_mul_f32 v[148:149], v[2:3], v[18:19]
	v_max_f32_e64 v146, |v146|, |v147|
	v_max3_f32 v146, |v148|, |v149|, v146
	v_max3_f32 v146, v150, v151, v146
	v_mov_b32_e32 v147, v146
	s_nop 1
	v_permlane16_swap_b32_e32 v146, v147
	s_nop 0
	s_waitcnt lgkmcnt(0)
	v_max_f32_e32 v147, v147, v147
	v_max_f32_e32 v146, v146, v147
	ds_bpermute_b32 v147, v245, v146
	s_and_saveexec_b64 s[0:1], vcc
	s_cbranch_execz .LBB0_1405
	s_waitcnt lgkmcnt(0)
	v_max_f32_e32 v147, v147, v147
	v_max_f32_e32 v146, v146, v146
	v_max_f32_e32 v146, v146, v147
	global_atomic_umax v[232:233], v146, off offset:704

; __device__ __forceinline__ unsigned xb_ld(unsigned* p)              { return __hip_atomic_load(p, __ATOMIC_RELAXED, __HIP_MEMORY_SCOPE_AGENT); }
; #define XB_SPIN(cond, bar) do { unsigned _sp = 0; while (cond) { __builtin_amdgcn_s_sleep(1); \
;     if ((++_sp & 255u) == 0u) { if (xb_ld(&(bar)[XB_TMO])) break; if (_sp > XB_SPIN_CAP) { atomicAdd(&(bar)[XB_TMO], 1u); break; } } } } while (0)
; __device__ __forceinline__ void xcd_barrier(const XcdBarrier& b) {
;     ...
;         } else {
;             XB_SPIN(xb_ld(&bar[XB_XGEN(b.x)]) == gen, bar);
;             __builtin_amdgcn_fence(__ATOMIC_ACQUIRE, "agent");
;             asm volatile("s_waitcnt vmcnt(0)" ::: "memory");
;         }
;     }
;     __syncthreads();
.LBB0_1495:
	s_or_b64 exec, exec, s[0:1]
	s_waitcnt lgkmcnt(0)
	s_barrier
	s_nop 0
	s_nop 0
	s_nop 0
	s_nop 0
	s_nop 0
	s_nop 0
	s_nop 0
	s_nop 0
	s_nop 0
	s_nop 0
	s_nop 0
	s_nop 0
	s_nop 0
	s_nop 0
	s_nop 0
	s_nop 0
	s_nop 0
	s_nop 0
	s_nop 0
	s_nop 0
	s_nop 0
	s_nop 0
	s_nop 0
	s_nop 0
	s_nop 0
	s_nop 0
	s_nop 0
	s_nop 0
	s_nop 0
	s_nop 0
	s_nop 0
	s_nop 0
	s_nop 0
	s_nop 0
	s_nop 0
	s_nop 0
	s_nop 0
	s_nop 0
	s_nop 0
	s_nop 0
	s_nop 0
	s_nop 0
	s_nop 0
	s_nop 0
	s_nop 0
	s_nop 0
	s_nop 0
	s_nop 0
	s_nop 0
	s_nop 0
	s_nop 0
	s_nop 0
	s_nop 0
	s_nop 0
	s_nop 0
	s_nop 0
	s_nop 0
	s_nop 0
	s_nop 0
	s_nop 0
	s_nop 0
	s_nop 0
	s_nop 0
	s_nop 0
	s_nop 0
	s_nop 0
	s_nop 0
	s_nop 0

; #define TIDX opq((int)threadIdx.x)
; template <class Epi, class Sched, class Gemm, bool ALIGN_EPI = false, bool SP2 = false>
; __device__ __forceinline__ void gemm_phase(PG8_LAS unsigned char* lds, const Gemm g, const Sched& S, const Epi& E) {
;     const int tid = TIDX, wid = __builtin_amdgcn_readfirstlane(tid >> 6), lane = tid & 63, wr = wid >> 2, wc = wid & 3, fr = lane & 15, fq = lane >> 4;
;     constexpr int K = Gemm::K, nt = K / BK, lda = Gemm::lda, ldb = Gemm::ldb;
;     constexpr int BP = epi_bperm<Epi>::value;
;     unsigned voffA[2], voffB[2], voffB1[2];
; #pragma unroll
;     for (int i = 0; i < 2; ++i) { int R, C; stage_rc(tid * 16 + i * 8192, R, C);
;         voffA[i] = (unsigned)(R * lda + C) * 2u;
;         if constexpr (BP == 2) { const int w_ = R >> 5, n_ = (R >> 4) & 1, j_ = R & 15, cb_ = w_ * 64 + 16 * (j_ >> 2) + 4 * n_ + (j_ & 3);
;             voffB[i] = (unsigned)(cb_ * ldb + C) * 2u; voffB1[i] = voffB[i]; }
;         else { const int Rb = (BP == 1) ? ((R & ~31) + perm32(R & 31)) : R; voffB[i] = (unsigned)(Rb * ldb + C) * 2u; voffB1[i] = voffB[i]; } }
;     const size_t kstep = (size_t)(BK * 2);
;     const size_t hstepA = (size_t)HALF * lda * 2, hstepB = (size_t)HALF * ldb * 2, hB1 = (BP == 2) ? (size_t)8 * ldb * 2 : hstepB;
;     ...
;     Unit cur, nxt; int ui = 0;
;     if (!S.next(0, cur)) return;
;     typename epi_pre<Epi>::Pre pre;
;     f32x4 acc[2][2][4][2];
; #pragma unroll
;     for (int a = 0; a < 2; ++a)
; #pragma unroll
;         for (int b = 0; b < 2; ++b)
; #pragma unroll
;             for (int m = 0; m < 4; ++m)
; #pragma unroll
;                 for (int n = 0; n < 2; ++n) acc[a][b][m][n] = (f32x4){0.f, 0.f, 0.f, 0.f};
;     bf16x8 At[4][2], B0[2][2], B1[2][2];
;     const char* cA = (const char*)g.A + (size_t)cur.pm * tstepA + (size_t)cur.sub * g.a_sub; const char* cB = (const char*)g.Bt + (size_t)cur.pn * tstepB + (size_t)cur.sub * g.b_sub;
;     S.a_ready(cur);
;     if constexpr (SP2) {
;         PG8_STAGE(PG8_SB(0, 0), cB, voffB); PG8_STAGE(PG8_SB(0, 1), cB + hB1, voffB1); PG8_STAGE(PG8_SA(0, 0), cA, voffA); PG8_STAGE(PG8_SA(0, 1), cA + hstepA, voffA);
;         if (wr == 1) PG8_BAR;
;         PG8_WAIT_V(2); PG8_BAR;
;         PG8_STAGE(PG8_SB(1, 0), cB + kstep, voffB); PG8_STAGE(PG8_SA(1, 0), cA + kstep, voffA); PG8_STAGE(PG8_SB(1, 1), cB + hB1 + kstep, voffB1);
;         PG8_WAIT_V(6); PG8_BAR;
.LBB0_1502:
	s_add_u32 s28, s24, 0x6b28000
	s_addc_u32 s29, s25, 0
	s_add_u32 s30, s24, 0x1dd08000
	s_addc_u32 s31, s25, 0
	s_add_u32 s34, s24, 0x1dd34400
	s_addc_u32 s35, s25, 0
	s_lshl_b32 s70, s4, 6
	s_lshl_b32 s1, s4, 13
	s_lshl_b32 s4, s5, 5
	s_mov_b64 s[36:37], 0x80
	s_and_b32 s71, s4, 0x60
	s_add_i32 m0, s65, 0x18000
	v_lshl_add_u64 v[8:9], v[8:9], 0, s[36:37]
	s_lshl_b32 s7, s71, 7
	s_waitcnt vmcnt(2)
	s_barrier
	global_load_lds_dwordx4 v[8:9], off
	v_lshl_add_u64 v[6:7], v[6:7], 0, s[36:37]
	s_add_i32 m0, s65, 0x1a000
	s_add_i32 s72, s65, 0x8000
	s_add_i32 s73, s65, 0xa000
	global_load_lds_dwordx4 v[6:7], off
	v_lshl_add_u64 v[2:3], v[2:3], 0, s[36:37]
	s_mov_b32 m0, s72
	s_add_u32 s4, s48, 0x20080
	global_load_lds_dwordx4 v[2:3], off
	v_lshl_add_u64 v[2:3], v[4:5], 0, s[36:37]
	s_mov_b32 m0, s73
	s_addc_u32 s5, s49, 0
	global_load_lds_dwordx4 v[2:3], off
	s_add_i32 m0, s65, 0x1c000
	v_lshl_add_u64 v[2:3], s[4:5], 0, v[212:213]
	global_load_lds_dwordx4 v212, s[4:5]
	v_lshl_add_u64 v[2:3], s[4:5], 0, v[216:217]
	s_add_i32 m0, s65, 0x1e000
	v_and_b32_e32 v1, 15, v10
	global_load_lds_dwordx4 v216, s[4:5]
	v_and_b32_e32 v2, 48, v10
	v_lshlrev_b32_e32 v3, 2, v10
	v_lshl_or_b32 v2, v1, 6, v2
	v_and_b32_e32 v3, 32, v3
	v_bitop3_b32 v4, v2, s1, v3 bitop3:0xde
	v_bitop3_b32 v251, s7, v2, v3 bitop3:0xf6
	v_lshrrev_b32_e32 v2, 1, v10
	v_and_or_b32 v252, v2, 24, s71
	v_lshlrev_b32_e32 v2, 13, v14
	v_and_b32_e32 v2, 0xffffc000, v2
	v_lshl_add_u32 v2, v15, 10, v2
	v_and_b32_e32 v3, 1, v14
	v_lshl_or_b32 v2, v3, 6, v2
	v_lshl_add_u32 v218, v16, 1, v2
	v_lshlrev_b32_e32 v2, 13, v11
	v_and_b32_e32 v2, 0xffffc000, v2
	s_waitcnt vmcnt(6)
	s_cmpk_lt_u32 s33, 0x100
	v_lshl_add_u32 v2, v12, 10, v2
	v_and_b32_e32 v3, 1, v11
	s_cselect_b64 s[38:39], -1, 0
	v_lshl_or_b32 v2, v3, 6, v2
	s_add_i32 s76, 0, 0x10000
	s_add_i32 s77, 0, 0x14000
	v_bfe_u32 v250, v10, 4, 2
	s_waitcnt lgkmcnt(0)
	s_ashr_i32 s74, s58, 31
	s_ashr_i32 s75, s59, 31
	v_mov_b32_e32 v219, v213
	v_lshl_add_u32 v220, v13, 1, v2
	v_mov_b32_e32 v221, v213
	v_add_u32_e32 v253, s76, v251
	v_add_u32_e32 v254, s77, v251
	v_add_u32_e32 v222, 0, v4
	s_movk_i32 s78, 0x2200
	s_barrier
	s_branch .LBB0_1505

; #define TIDX opq((int)threadIdx.x)
; template <class Epi, class Sched, class Gemm, bool ALIGN_EPI = false, bool SP2 = false>
; __device__ __forceinline__ void gemm_phase(PG8_LAS unsigned char* lds, const Gemm g, const Sched& S, const Epi& E) {
;     const int tid = TIDX, wid = __builtin_amdgcn_readfirstlane(tid >> 6), lane = tid & 63, wr = wid >> 2, wc = wid & 3, fr = lane & 15, fq = lane >> 4;
;     constexpr int K = Gemm::K, nt = K / BK, lda = Gemm::lda, ldb = Gemm::ldb;
;     constexpr int BP = epi_bperm<Epi>::value;
;     unsigned voffA[2], voffB[2], voffB1[2];
; #pragma unroll
;     for (int i = 0; i < 2; ++i) { int R, C; stage_rc(tid * 16 + i * 8192, R, C);
;         voffA[i] = (unsigned)(R * lda + C) * 2u;
;         if constexpr (BP == 2) { const int w_ = R >> 5, n_ = (R >> 4) & 1, j_ = R & 15, cb_ = w_ * 64 + 16 * (j_ >> 2) + 4 * n_ + (j_ & 3);
;             voffB[i] = (unsigned)(cb_ * ldb + C) * 2u; voffB1[i] = voffB[i]; }
;         else { const int Rb = (BP == 1) ? ((R & ~31) + perm32(R & 31)) : R; voffB[i] = (unsigned)(Rb * ldb + C) * 2u; voffB1[i] = voffB[i]; } }
;     const size_t kstep = (size_t)(BK * 2);
;     const size_t hstepA = (size_t)HALF * lda * 2, hstepB = (size_t)HALF * ldb * 2, hB1 = (BP == 2) ? (size_t)8 * ldb * 2 : hstepB;
;     ...
;     Unit cur, nxt; int ui = 0;
;     if (!S.next(0, cur)) return;
;     typename epi_pre<Epi>::Pre pre;
;     f32x4 acc[2][2][4][2];
; #pragma unroll
;     for (int a = 0; a < 2; ++a)
; #pragma unroll
;         for (int b = 0; b < 2; ++b)
; #pragma unroll
;             for (int m = 0; m < 4; ++m)
; #pragma unroll
;                 for (int n = 0; n < 2; ++n) acc[a][b][m][n] = (f32x4){0.f, 0.f, 0.f, 0.f};
;     bf16x8 At[4][2], B0[2][2], B1[2][2];
;     const char* cA = (const char*)g.A + (size_t)cur.pm * tstepA + (size_t)cur.sub * g.a_sub; const char* cB = (const char*)g.Bt + (size_t)cur.pn * tstepB + (size_t)cur.sub * g.b_sub;
;     S.a_ready(cur);
;     if constexpr (SP2) {
;         PG8_STAGE(PG8_SB(0, 0), cB, voffB); PG8_STAGE(PG8_SB(0, 1), cB + hB1, voffB1); PG8_STAGE(PG8_SA(0, 0), cA, voffA); PG8_STAGE(PG8_SA(0, 1), cA + hstepA, voffA);
;         if (wr == 1) PG8_BAR;
;         PG8_WAIT_V(2); PG8_BAR;
;         PG8_STAGE(PG8_SB(1, 0), cB + kstep, voffB); PG8_STAGE(PG8_SA(1, 0), cA + kstep, voffA); PG8_STAGE(PG8_SB(1, 1), cB + hB1 + kstep, voffB1);
;         PG8_WAIT_V(6); PG8_BAR;
.LBB0_2542:
	s_add_u32 s14, s14, 0x4000
	s_addc_u32 s15, s15, 0
	s_add_u32 s16, s12, 0x1dd2c000
	s_addc_u32 s17, s13, 0
	s_and_b32 s22, s18, 3
	s_lshl_b32 s50, s19, 6
	s_lshl_b32 s24, s19, 13
	s_lshl_b32 s26, s22, 12
	s_add_u32 s12, s12, 0x1dd08000
	s_mov_b64 s[18:19], 0x80
	s_addc_u32 s13, s13, 0
	s_add_i32 m0, s39, 0x18000
	v_lshl_add_u64 v[8:9], v[8:9], 0, s[18:19]
	s_waitcnt vmcnt(2)
	s_barrier
	global_load_lds_dwordx4 v[8:9], off
	v_lshl_add_u64 v[6:7], v[6:7], 0, s[18:19]
	s_add_i32 m0, s39, 0x1a000
	s_add_i32 s51, s39, 0x8000
	s_add_i32 s52, s39, 0xa000
	global_load_lds_dwordx4 v[6:7], off
	v_lshl_add_u64 v[2:3], v[2:3], 0, s[18:19]
	s_mov_b32 m0, s51
	s_add_u32 s20, s0, 0x2080
	global_load_lds_dwordx4 v[2:3], off
	v_lshl_add_u64 v[2:3], v[4:5], 0, s[18:19]
	s_mov_b32 m0, s52
	s_addc_u32 s21, s1, 0
	global_load_lds_dwordx4 v[2:3], off
	s_add_i32 m0, s39, 0x1c000
	v_lshl_add_u64 v[2:3], s[20:21], 0, v[148:149]
	global_load_lds_dwordx4 v148, s[20:21]
	v_lshl_add_u64 v[2:3], s[20:21], 0, v[152:153]
	s_add_i32 m0, s39, 0x1e000
	v_bfe_u32 v179, v10, 4, 2
	global_load_lds_dwordx4 v152, s[20:21]
	v_and_b32_e32 v1, 15, v10
	v_lshlrev_b32_e32 v2, 4, v179
	v_lshlrev_b32_e32 v3, 2, v10
	v_lshl_or_b32 v2, v1, 6, v2
	v_and_b32_e32 v3, 32, v3
	v_bitop3_b32 v4, v2, s24, v3 bitop3:0xde
	v_bitop3_b32 v181, v2, s26, v3 bitop3:0xde
	v_lshlrev_b32_e32 v2, 13, v14
	v_and_b32_e32 v2, 0xffffc000, v2
	v_lshl_add_u32 v2, v15, 10, v2
	v_and_b32_e32 v3, 1, v14
	v_lshl_or_b32 v2, v3, 6, v2
	v_lshl_add_u32 v156, v16, 1, v2
	v_lshlrev_b32_e32 v2, 13, v11
	v_and_b32_e32 v2, 0xffffc000, v2
	s_waitcnt vmcnt(6)
	s_cmpk_lt_u32 s5, 0x100
	v_lshl_add_u32 v2, v12, 10, v2
	v_and_b32_e32 v3, 1, v11
	s_cselect_b64 s[20:21], -1, 0
	v_lshl_or_b32 v2, v3, 6, v2
	s_add_i32 s55, 0, 0x10000
	s_add_i32 s56, 0, 0x14000
	s_sext_i32_i8 s59, s4
	s_lshl_b32 s53, s22, 6
	s_ashr_i32 s54, s23, 31
	v_mov_b32_e32 v157, v155
	v_lshl_add_u32 v158, v13, 1, v2
	v_mov_b32_e32 v159, v155
	v_mov_b64_e32 v[252:253], 0x800
	v_add_u32_e32 v183, s55, v181
	v_add_u32_e32 v185, s56, v181
	v_add_u32_e32 v187, 0, v4
	s_mov_b32 s22, 0xbfb8aa3b
	s_movk_i32 s57, 0x2200
	s_mov_b32 s24, 0x4b000000
	s_mov_b32 s26, 0x437f0000
	s_mov_b32 s58, 0xc0c0400
	s_barrier
	s_waitcnt vmcnt(0)
	s_nop 0
	s_branch .LBB0_2545

; #define PG8_STAGE(bufoff, gbase, voff) do { _Pragma("unroll") for (int _i = 0; _i < 2; ++_i) \
;         __builtin_amdgcn_global_load_lds((const unsigned*)((const char*)(gbase) + (voff)[_i]), (PG8_LAS unsigned*)(lds + (bufoff) + ldsw + _i * 8192), 16, 0, 0); } while (0)
; #define PG8_LDA(dst, b, h) do { _Pragma("unroll") for (int m = 0; m < 4; ++m) _Pragma("unroll") for (int k = 0; k < 2; ++k) dst[m][k] = *(const PG8_LAS bf16x8*)(lds + PG8_SA(b, h) + aoff + m * 2048 + k * 1024); } while (0)
; #define PG8_WAIT_V(n) asm volatile("s_waitcnt vmcnt(" #n ")" ::: "memory")
; template <class Epi, class Sched, class Gemm, bool ALIGN_EPI = false, bool SP2 = false>
; __device__ __forceinline__ void gemm_phase(PG8_LAS unsigned char* lds, const Gemm g, const Sched& S, const Epi& E) {
;     ...
;         for (int t = 0; t < nt; t += 2) {
;             const bool last = (t == nt - 2);
;             const char* a1 = cA + (size_t)(t + 1) * kstep;
;             const char* a2 = last ? nA : cA + (size_t)(t + 2) * kstep; const char* b2 = last ? nB : cB + (size_t)(t + 2) * kstep;
;             const char* a3 = a2 + kstep; const char* b3 = b2 + kstep;
;             if (last && has_next) S.a_ready(nxt);
;             if constexpr (SP2) {
;             PG8_LDB(B0, 0, 0); PG8_LDB(B1, 0, 1); PG8_SCHED; PG8_LDA(At, 0, 0); PG8_STAGE(PG8_SA(1, 1), a1 + hstepA, voffA);
;             PG8_WAIT_V(8); PG8_WAIT_L(0); PG8_BAR; PG8_MMA(0, 0, At, B0); PG8_MMA(0, 1, At, B1); PG8_BAR; PG8_SCHED;
;             PG8_LDA(At, 0, 1); PG8_STAGE(PG8_SB(0, 0), b2, voffB); PG8_STAGE(PG8_SB(0, 1), b2 + hB1, voffB1); PG8_STAGE(PG8_SA(0, 0), a2, voffA);
;             PG8_WAIT_V(8); PG8_WAIT_L(0); PG8_BAR; PG8_MMA(1, 0, At, B0); PG8_MMA(1, 1, At, B1); PG8_BAR; PG8_SCHED;
;             PG8_LDB(B0, 1, 0); PG8_LDB(B1, 1, 1); PG8_SCHED; PG8_LDA(At, 1, 0); PG8_STAGE(PG8_SA(0, 1), a2 + hstepA, voffA);
;             PG8_WAIT_V(8); PG8_WAIT_L(0); PG8_BAR; PG8_MMA(0, 0, At, B0); PG8_MMA(0, 1, At, B1); PG8_BAR; PG8_SCHED;
;             PG8_LDA(At, 1, 1); PG8_STAGE(PG8_SB(1, 0), b3, voffB); PG8_STAGE(PG8_SB(1, 1), b3 + hB1, voffB1); PG8_STAGE(PG8_SA(1, 0), a3, voffA);
;             PG8_WAIT_V(8);
;             if constexpr (epi_pre<Epi>::value) { if (last) E.pre(pre, cur, wr, wc, lane); }
;             PG8_WAIT_L(0); PG8_BAR; PG8_MMA(1, 0, At, B0); PG8_MMA(1, 1, At, B1); PG8_BAR; PG8_SCHED;
.Lfw_2:
	s_waitcnt lgkmcnt(0)
	s_barrier
	s_setprio 1
	s_waitcnt lgkmcnt(0)
	v_mfma_i32_16x16x64_i8 v[224:227], v[172:175], v[164:167], v[126:129]
	v_mfma_i32_16x16x64_i8 v[126:129], v[188:191], v[168:171], v[224:227]
	v_mfma_i32_16x16x64_i8 v[228:231], v[192:195], v[164:167], v[122:125]
	v_mfma_i32_16x16x64_i8 v[232:235], v[172:175], v[200:203], v[110:113]
	v_mfma_i32_16x16x64_i8 v[236:239], v[192:195], v[200:203], v[106:109]
	v_mfma_i32_16x16x64_i8 v[240:243], v[172:175], v[208:211], v[94:97]
	v_mfma_i32_16x16x64_i8 v[244:247], v[192:195], v[208:211], v[90:93]
	v_mfma_i32_16x16x64_i8 v[224:227], v[172:175], v[216:219], v[78:81]
	v_mfma_i32_16x16x64_i8 v[74:77], v[192:195], v[216:219], v[74:77]
	v_mfma_i32_16x16x64_i8 v[122:125], v[196:199], v[168:171], v[228:231]
	v_mfma_i32_16x16x64_i8 v[110:113], v[188:191], v[204:207], v[232:235]
	v_mfma_i32_16x16x64_i8 v[106:109], v[196:199], v[204:207], v[236:239]
	v_mfma_i32_16x16x64_i8 v[94:97], v[188:191], v[212:215], v[240:243]
	v_mfma_i32_16x16x64_i8 v[90:93], v[196:199], v[212:215], v[244:247]
	v_mfma_i32_16x16x64_i8 v[78:81], v[188:191], v[220:223], v[224:227]
	v_mfma_i32_16x16x64_i8 v[74:77], v[196:199], v[220:223], v[74:77]
	s_setprio 0
	s_setprio 1
	v_mfma_i32_16x16x64_i8 v[224:227], v[134:137], v[164:167], v[118:121]
	v_mfma_i32_16x16x64_i8 v[118:121], v[138:141], v[168:171], v[224:227]
	v_mfma_i32_16x16x64_i8 v[228:231], v[142:145], v[164:167], v[114:117]
	v_mfma_i32_16x16x64_i8 v[232:235], v[134:137], v[200:203], v[102:105]
	v_mfma_i32_16x16x64_i8 v[236:239], v[142:145], v[200:203], v[98:101]
	v_mfma_i32_16x16x64_i8 v[240:243], v[134:137], v[208:211], v[86:89]
	v_mfma_i32_16x16x64_i8 v[244:247], v[142:145], v[208:211], v[82:85]
	v_mfma_i32_16x16x64_i8 v[164:167], v[134:137], v[216:219], v[70:73]
	v_mfma_i32_16x16x64_i8 v[66:69], v[142:145], v[216:219], v[66:69]
	v_mfma_i32_16x16x64_i8 v[114:117], v[130:133], v[168:171], v[228:231]
	v_mfma_i32_16x16x64_i8 v[102:105], v[138:141], v[204:207], v[232:235]
	v_mfma_i32_16x16x64_i8 v[98:101], v[130:133], v[204:207], v[236:239]
	v_mfma_i32_16x16x64_i8 v[86:89], v[138:141], v[212:215], v[240:243]
	v_mfma_i32_16x16x64_i8 v[82:85], v[130:133], v[212:215], v[244:247]
	v_mfma_i32_16x16x64_i8 v[70:73], v[138:141], v[220:223], v[164:167]
	v_mfma_i32_16x16x64_i8 v[66:69], v[130:133], v[220:223], v[66:69]
	s_setprio 0
	s_barrier
	s_add_i32 s65, s55, s43
	v_lshl_add_u64 v[164:165], s[40:41], 0, v[148:149]
	s_mov_b32 m0, s65
	ds_read_b128 v[200:203], v187 offset:16384
	ds_read_b128 v[204:207], v187 offset:17408
	ds_read_b128 v[208:211], v187 offset:18432
	ds_read_b128 v[212:215], v187 offset:19456
	ds_read_b128 v[216:219], v187 offset:20480
	ds_read_b128 v[220:223], v187 offset:21504
	ds_read_b128 v[224:227], v187 offset:22528
	ds_read_b128 v[228:231], v187 offset:23552
	global_load_lds_dwordx4 v148, s[40:41]
	s_add_i32 m0, s65, 0x2000
	s_add_u32 s66, s40, 0x2000
	v_lshl_add_u64 v[166:167], s[40:41], 0, v[152:153]
	s_addc_u32 s67, s41, 0
	s_add_i32 s65, s56, s43
	global_load_lds_dwordx4 v152, s[40:41]
	s_mov_b32 m0, s65
	v_lshl_add_u64 v[168:169], s[2:3], 0, v[146:147]
	global_load_lds_dwordx4 v148, s[66:67]
	v_lshl_add_u64 v[160:161], s[66:67], 0, v[152:153]
	s_add_i32 m0, s65, 0x2000
	v_lshl_add_u64 v[170:171], s[2:3], 0, v[150:151]
	global_load_lds_dwordx4 v152, s[66:67]
	s_mov_b32 m0, s39
	s_nop 0
	global_load_lds_dwordx4 v146, s[2:3]
	s_mov_b32 m0, s46
	s_nop 0
	global_load_lds_dwordx4 v150, s[2:3]
	s_cbranch_vccnz .Lfw_3
	s_waitcnt vmcnt(8)
.Lfw_3:
	s_waitcnt lgkmcnt(0)
	s_barrier
	s_setprio 1
	s_waitcnt lgkmcnt(0)
	v_mfma_i32_16x16x64_i8 v[232:235], v[172:175], v[200:203], v[62:65]
	v_mfma_i32_16x16x64_i8 v[62:65], v[188:191], v[204:207], v[232:235]
	v_mfma_i32_16x16x64_i8 v[236:239], v[192:195], v[200:203], v[58:61]
	v_mfma_i32_16x16x64_i8 v[240:243], v[172:175], v[208:211], v[46:49]
	v_mfma_i32_16x16x64_i8 v[244:247], v[192:195], v[208:211], v[42:45]
	v_mfma_i32_16x16x64_i8 v[248:251], v[172:175], v[216:219], v[30:33]
	v_mfma_i32_16x16x64_i8 v[160:163], v[192:195], v[216:219], v[26:29]
	v_mfma_i32_16x16x64_i8 v[232:235], v[172:175], v[224:227], v[14:17]
	v_mfma_i32_16x16x64_i8 v[10:13], v[192:195], v[224:227], v[10:13]
	v_mfma_i32_16x16x64_i8 v[58:61], v[196:199], v[204:207], v[236:239]
	v_mfma_i32_16x16x64_i8 v[46:49], v[188:191], v[212:215], v[240:243]
	v_mfma_i32_16x16x64_i8 v[42:45], v[196:199], v[212:215], v[244:247]
	v_mfma_i32_16x16x64_i8 v[30:33], v[188:191], v[220:223], v[248:251]
	v_mfma_i32_16x16x64_i8 v[26:29], v[196:199], v[220:223], v[160:163]
	v_mfma_i32_16x16x64_i8 v[14:17], v[188:191], v[228:231], v[232:235]
	v_mfma_i32_16x16x64_i8 v[10:13], v[196:199], v[228:231], v[10:13]
	s_setprio 0
	s_setprio 1
	v_mfma_i32_16x16x64_i8 v[160:163], v[134:137], v[200:203], v[54:57]
	v_mfma_i32_16x16x64_i8 v[54:57], v[138:141], v[204:207], v[160:163]
	v_mfma_i32_16x16x64_i8 v[172:175], v[142:145], v[200:203], v[50:53]
	v_mfma_i32_16x16x64_i8 v[188:191], v[134:137], v[208:211], v[38:41]
	v_mfma_i32_16x16x64_i8 v[192:195], v[142:145], v[208:211], v[34:37]
	v_mfma_i32_16x16x64_i8 v[196:199], v[134:137], v[216:219], v[22:25]
	v_mfma_i32_16x16x64_i8 v[232:235], v[142:145], v[216:219], v[18:21]
	v_mfma_i32_16x16x64_i8 v[160:163], v[134:137], v[224:227], v[6:9]
	v_mfma_i32_16x16x64_i8 v[2:5], v[142:145], v[224:227], v[2:5]
	v_mfma_i32_16x16x64_i8 v[50:53], v[130:133], v[204:207], v[172:175]
	v_mfma_i32_16x16x64_i8 v[38:41], v[138:141], v[212:215], v[188:191]
	v_mfma_i32_16x16x64_i8 v[34:37], v[130:133], v[212:215], v[192:195]
	v_mfma_i32_16x16x64_i8 v[22:25], v[138:141], v[220:223], v[196:199]
	v_mfma_i32_16x16x64_i8 v[18:21], v[130:133], v[220:223], v[232:235]
	v_mfma_i32_16x16x64_i8 v[6:9], v[138:141], v[228:231], v[160:163]
	v_mfma_i32_16x16x64_i8 v[2:5], v[130:133], v[228:231], v[2:5]
	s_setprio 0
	s_barrier
; #define PG8_STAGE(bufoff, gbase, voff) do { _Pragma("unroll") for (int _i = 0; _i < 2; ++_i) \
;         __builtin_amdgcn_global_load_lds((const unsigned*)((const char*)(gbase) + (voff)[_i]), (PG8_LAS unsigned*)(lds + (bufoff) + ldsw + _i * 8192), 16, 0, 0); } while (0)
; #define PG8_LDA(dst, b, h) do { _Pragma("unroll") for (int m = 0; m < 4; ++m) _Pragma("unroll") for (int k = 0; k < 2; ++k) dst[m][k] = *(const PG8_LAS bf16x8*)(lds + PG8_SA(b, h) + aoff + m * 2048 + k * 1024); } while (0)
; #define PG8_WAIT_V(n) asm volatile("s_waitcnt vmcnt(" #n ")" ::: "memory")
; template <class Epi, class Sched, class Gemm, bool ALIGN_EPI = false, bool SP2 = false>
; __device__ __forceinline__ void gemm_phase(PG8_LAS unsigned char* lds, const Gemm g, const Sched& S, const Epi& E) {
;     ...
;         for (int t = 0; t < nt; t += 2) {
;             const bool last = (t == nt - 2);
;             const char* a1 = cA + (size_t)(t + 1) * kstep;
;             const char* a2 = last ? nA : cA + (size_t)(t + 2) * kstep; const char* b2 = last ? nB : cB + (size_t)(t + 2) * kstep;
;             const char* a3 = a2 + kstep; const char* b3 = b2 + kstep;
;             if (last && has_next) S.a_ready(nxt);
;             if constexpr (SP2) {
;             PG8_LDB(B0, 0, 0); PG8_LDB(B1, 0, 1); PG8_SCHED; PG8_LDA(At, 0, 0); PG8_STAGE(PG8_SA(1, 1), a1 + hstepA, voffA);
;             PG8_WAIT_V(8); PG8_WAIT_L(0); PG8_BAR; PG8_MMA(0, 0, At, B0); PG8_MMA(0, 1, At, B1); PG8_BAR; PG8_SCHED;
;             PG8_LDA(At, 0, 1); PG8_STAGE(PG8_SB(0, 0), b2, voffB); PG8_STAGE(PG8_SB(0, 1), b2 + hB1, voffB1); PG8_STAGE(PG8_SA(0, 0), a2, voffA);
;             PG8_WAIT_V(8); PG8_WAIT_L(0); PG8_BAR; PG8_MMA(1, 0, At, B0); PG8_MMA(1, 1, At, B1); PG8_BAR; PG8_SCHED;
;             PG8_LDB(B0, 1, 0); PG8_LDB(B1, 1, 1); PG8_SCHED; PG8_LDA(At, 1, 0); PG8_STAGE(PG8_SA(0, 1), a2 + hstepA, voffA);
;             PG8_WAIT_V(8); PG8_WAIT_L(0); PG8_BAR; PG8_MMA(0, 0, At, B0); PG8_MMA(0, 1, At, B1); PG8_BAR; PG8_SCHED;
;             PG8_LDA(At, 1, 1); PG8_STAGE(PG8_SB(1, 0), b3, voffB); PG8_STAGE(PG8_SB(1, 1), b3 + hB1, voffB1); PG8_STAGE(PG8_SA(1, 0), a3, voffA);
;             PG8_WAIT_V(8);
;             if constexpr (epi_pre<Epi>::value) { if (last) E.pre(pre, cur, wr, wc, lane); }
;             PG8_WAIT_L(0); PG8_BAR; PG8_MMA(1, 0, At, B0); PG8_MMA(1, 1, At, B1); PG8_BAR; PG8_SCHED;
	s_add_i32 s65, 0, 0x18000
	s_add_i32 s66, 0, 0x1c000
	v_add_u32_e32 v130, s65, v181
	v_add_u32_e32 v131, s66, v181
	ds_read_b128 v[160:163], v130
	ds_read_b128 v[172:175], v130 offset:1024
	ds_read_b128 v[188:191], v130 offset:2048
	ds_read_b128 v[192:195], v130 offset:3072
	ds_read_b128 v[134:137], v131
	ds_read_b128 v[138:141], v131 offset:1024
	ds_read_b128 v[142:145], v131 offset:2048
	ds_read_b128 v[130:133], v131 offset:3072
	s_add_u32 s2, s2, 0x20000
	s_addc_u32 s3, s3, 0
	s_mov_b32 m0, s47
	ds_read_b128 v[196:199], v187 offset:32768
	ds_read_b128 v[200:203], v187 offset:33792
	ds_read_b128 v[204:207], v187 offset:34816
	ds_read_b128 v[208:211], v187 offset:35840
	ds_read_b128 v[212:215], v187 offset:36864
	ds_read_b128 v[216:219], v187 offset:37888
	ds_read_b128 v[220:223], v187 offset:38912
	ds_read_b128 v[224:227], v187 offset:39936
	global_load_lds_dwordx4 v146, s[2:3]
	v_lshl_add_u64 v[176:177], s[2:3], 0, v[150:151]
	s_mov_b32 m0, s48
	s_nop 0
	global_load_lds_dwordx4 v150, s[2:3]
	s_waitcnt vmcnt(8)
	s_waitcnt lgkmcnt(0)
	s_barrier
	s_setprio 1
	s_waitcnt lgkmcnt(0)
	v_mfma_i32_16x16x64_i8 v[228:231], v[160:163], v[196:199], v[126:129]
	v_mfma_i32_16x16x64_i8 v[126:129], v[172:175], v[200:203], v[228:231]
	v_mfma_i32_16x16x64_i8 v[232:235], v[188:191], v[196:199], v[122:125]
	v_mfma_i32_16x16x64_i8 v[236:239], v[160:163], v[204:207], v[110:113]
	v_mfma_i32_16x16x64_i8 v[240:243], v[188:191], v[204:207], v[106:109]
	v_mfma_i32_16x16x64_i8 v[244:247], v[160:163], v[212:215], v[94:97]
	v_mfma_i32_16x16x64_i8 v[248:251], v[188:191], v[212:215], v[90:93]
	v_mfma_i32_16x16x64_i8 v[228:231], v[160:163], v[220:223], v[78:81]
	v_mfma_i32_16x16x64_i8 v[74:77], v[188:191], v[220:223], v[74:77]
	v_mfma_i32_16x16x64_i8 v[122:125], v[192:195], v[200:203], v[232:235]
	v_mfma_i32_16x16x64_i8 v[110:113], v[172:175], v[208:211], v[236:239]
	v_mfma_i32_16x16x64_i8 v[106:109], v[192:195], v[208:211], v[240:243]
	v_mfma_i32_16x16x64_i8 v[94:97], v[172:175], v[216:219], v[244:247]
	v_mfma_i32_16x16x64_i8 v[90:93], v[192:195], v[216:219], v[248:251]
	v_mfma_i32_16x16x64_i8 v[78:81], v[172:175], v[224:227], v[228:231]
	v_mfma_i32_16x16x64_i8 v[74:77], v[192:195], v[224:227], v[74:77]
	s_setprio 0
	s_setprio 1
	v_mfma_i32_16x16x64_i8 v[228:231], v[134:137], v[196:199], v[118:121]
	v_mfma_i32_16x16x64_i8 v[118:121], v[138:141], v[200:203], v[228:231]
	v_mfma_i32_16x16x64_i8 v[232:235], v[142:145], v[196:199], v[114:117]
	v_mfma_i32_16x16x64_i8 v[236:239], v[134:137], v[204:207], v[102:105]
	v_mfma_i32_16x16x64_i8 v[240:243], v[142:145], v[204:207], v[98:101]
	v_mfma_i32_16x16x64_i8 v[244:247], v[134:137], v[212:215], v[86:89]
	v_mfma_i32_16x16x64_i8 v[248:251], v[142:145], v[212:215], v[82:85]
	v_mfma_i32_16x16x64_i8 v[196:199], v[134:137], v[220:223], v[70:73]
	v_mfma_i32_16x16x64_i8 v[66:69], v[142:145], v[220:223], v[66:69]
	v_mfma_i32_16x16x64_i8 v[114:117], v[130:133], v[200:203], v[232:235]
	v_mfma_i32_16x16x64_i8 v[102:105], v[138:141], v[208:211], v[236:239]
	v_mfma_i32_16x16x64_i8 v[98:101], v[130:133], v[208:211], v[240:243]
	v_mfma_i32_16x16x64_i8 v[86:89], v[138:141], v[216:219], v[244:247]
	v_mfma_i32_16x16x64_i8 v[82:85], v[130:133], v[216:219], v[248:251]
	v_mfma_i32_16x16x64_i8 v[70:73], v[138:141], v[224:227], v[196:199]
	v_mfma_i32_16x16x64_i8 v[66:69], v[130:133], v[224:227], v[66:69]
	s_setprio 0
	s_barrier
	s_add_i32 s2, s65, s43
	v_lshl_add_u64 v[164:165], v[164:165], 0, s[18:19]
	s_mov_b32 m0, s2
	ds_read_b128 v[196:199], v187 offset:49152
	ds_read_b128 v[200:203], v187 offset:50176
	ds_read_b128 v[204:207], v187 offset:51200
	ds_read_b128 v[208:211], v187 offset:52224
	ds_read_b128 v[212:215], v187 offset:53248
	ds_read_b128 v[216:219], v187 offset:54272
	ds_read_b128 v[220:223], v187 offset:55296
	ds_read_b128 v[224:227], v187 offset:56320
	global_load_lds_dwordx4 v[164:165], off
	s_add_i32 m0, s2, 0x2000
	s_add_u32 s2, s40, 0x2080
	v_lshl_add_u64 v[164:165], v[166:167], 0, s[18:19]
	s_addc_u32 s3, s41, 0
	s_add_i32 s40, s66, s43
	global_load_lds_dwordx4 v[164:165], off
	s_mov_b32 m0, s40
	s_nop 0
	global_load_lds_dwordx4 v148, s[2:3]
	s_add_i32 m0, s40, 0x2000
	s_nop 0
	global_load_lds_dwordx4 v152, s[2:3]
	v_lshl_add_u64 v[164:165], v[168:169], 0, s[18:19]
	s_mov_b32 m0, s51
	s_nop 0
	global_load_lds_dwordx4 v[164:165], off
	v_lshl_add_u64 v[164:165], v[170:171], 0, s[18:19]
	s_mov_b32 m0, s52
	s_nop 0
	global_load_lds_dwordx4 v[164:165], off
	s_waitcnt vmcnt(8)
	s_waitcnt lgkmcnt(0)
	s_barrier
	s_setprio 1
	s_waitcnt lgkmcnt(0)
	v_mfma_i32_16x16x64_i8 v[164:167], v[160:163], v[196:199], v[62:65]
	v_mfma_i32_16x16x64_i8 v[62:65], v[172:175], v[200:203], v[164:167]
	v_mfma_i32_16x16x64_i8 v[168:171], v[188:191], v[196:199], v[58:61]
	v_mfma_i32_16x16x64_i8 v[228:231], v[160:163], v[204:207], v[46:49]
	v_mfma_i32_16x16x64_i8 v[232:235], v[188:191], v[204:207], v[42:45]
	v_mfma_i32_16x16x64_i8 v[236:239], v[160:163], v[212:215], v[30:33]
	v_mfma_i32_16x16x64_i8 v[240:243], v[188:191], v[212:215], v[26:29]
	v_mfma_i32_16x16x64_i8 v[164:167], v[160:163], v[220:223], v[14:17]
	v_mfma_i32_16x16x64_i8 v[10:13], v[188:191], v[220:223], v[10:13]
	v_mfma_i32_16x16x64_i8 v[58:61], v[192:195], v[200:203], v[168:171]
	v_mfma_i32_16x16x64_i8 v[46:49], v[172:175], v[208:211], v[228:231]
	v_mfma_i32_16x16x64_i8 v[42:45], v[192:195], v[208:211], v[232:235]
	v_mfma_i32_16x16x64_i8 v[30:33], v[172:175], v[216:219], v[236:239]
	v_mfma_i32_16x16x64_i8 v[26:29], v[192:195], v[216:219], v[240:243]
	v_mfma_i32_16x16x64_i8 v[14:17], v[172:175], v[224:227], v[164:167]
	v_mfma_i32_16x16x64_i8 v[10:13], v[192:195], v[224:227], v[10:13]
	s_setprio 0
	s_setprio 1
	v_mfma_i32_16x16x64_i8 v[160:163], v[134:137], v[196:199], v[54:57]
	v_mfma_i32_16x16x64_i8 v[54:57], v[138:141], v[200:203], v[160:163]
	v_mfma_i32_16x16x64_i8 v[164:167], v[142:145], v[196:199], v[50:53]
	v_mfma_i32_16x16x64_i8 v[168:171], v[134:137], v[204:207], v[38:41]
	v_mfma_i32_16x16x64_i8 v[172:175], v[142:145], v[204:207], v[34:37]
	v_mfma_i32_16x16x64_i8 v[188:191], v[134:137], v[212:215], v[22:25]
	v_mfma_i32_16x16x64_i8 v[192:195], v[142:145], v[212:215], v[18:21]
	v_mfma_i32_16x16x64_i8 v[160:163], v[134:137], v[220:223], v[6:9]
	v_mfma_i32_16x16x64_i8 v[2:5], v[142:145], v[220:223], v[2:5]
	v_mfma_i32_16x16x64_i8 v[50:53], v[130:133], v[200:203], v[164:167]
	v_mfma_i32_16x16x64_i8 v[38:41], v[138:141], v[208:211], v[168:171]
	v_mfma_i32_16x16x64_i8 v[34:37], v[130:133], v[208:211], v[172:175]
	v_mfma_i32_16x16x64_i8 v[22:25], v[138:141], v[216:219], v[188:191]
	v_mfma_i32_16x16x64_i8 v[18:21], v[130:133], v[216:219], v[192:195]
	v_mfma_i32_16x16x64_i8 v[6:9], v[138:141], v[224:227], v[160:163]
	v_mfma_i32_16x16x64_i8 v[2:5], v[130:133], v[224:227], v[2:5]
	s_setprio 0
	s_barrier
;     __device__ __forceinline__ void operator()(const f32x4 (&acc)[2][2][4][2], const Unit& u, int wr, int wc, int fr, int fq) const {
;         asm volatile("" : "+v"(fr), "+v"(fq));
;         const int row0 = u.pm * BM + wr * 64 + fr, col0 = u.pn * BM + wc * 64 + 16 * fq;
;         const int gn = u.pn >> 2, gbase = (gn < 3) ? 3072 + 1024 * gn : 0;
;         f32x4 bv[2][2];
; #pragma unroll
;         for (int bj = 0; bj < 2; ++bj)
; #pragma unroll
;             for (int n = 0; n < 2; ++n) bv[bj][n] = *(const f32x4*)(bias + col0 + 8 * bj + 4 * n) * -1.44269504f;
;         f32x4 wv[2][2];
; #pragma unroll
;         for (int bj = 0; bj < 2; ++bj)
; #pragma unroll
;             for (int n = 0; n < 2; ++n) wv[bj][n] = *(const f32x4*)(SW + col0 + 8 * bj + 4 * n) * -1.44269504f;
;         float rsv[8];
; #pragma unroll
;         for (int i = 0; i < 8; ++i) rsv[i] = SH[row0 + (i >> 2) * HALF + (i & 3) * 16];
	s_add_i32 s64, s64, 2
	s_add_u32 s62, s62, 0x100
	s_addc_u32 s63, s63, 0
	s_add_u32 s0, s0, 0x100
	s_addc_u32 s1, s1, 0
	s_cmp_gt_u32 s64, 5
	s_mov_b64 vcc, 0
	s_cbranch_scc0 .LBB0_2552
	s_lshl_b32 s0, s59, 8
	v_mov_b32_e32 v154, v1
	v_mov_b32_e32 v130, v179
	s_or_b32 s0, s0, s53
	v_cvt_f32_i32_e32 v212, v122
	v_lshl_add_u32 v144, v130, 4, s0
	s_lshl_b32 s0, s38, 8
	v_ashrrev_i32_e32 v145, 31, v144
	s_add_i32 s0, s0, s50
	v_lshlrev_b64 v[142:143], 2, v[144:145]
	v_add_u32_e32 v164, s0, v154
	v_lshl_add_u64 v[160:161], s[14:15], 0, v[142:143]
	v_ashrrev_i32_e32 v165, 31, v164
	global_load_dwordx4 v[130:133], v[160:161], off
	global_load_dwordx4 v[134:137], v[160:161], off offset:16
	global_load_dwordx4 v[138:141], v[160:161], off offset:32
	s_nop 0
	global_load_dwordx4 v[160:163], v[160:161], off offset:48
	v_lshl_add_u64 v[142:143], s[16:17], 0, v[142:143]
	v_lshl_add_u64 v[170:171], v[164:165], 2, s[12:13]
	global_load_dwordx4 v[166:169], v[142:143], off
	global_load_dwordx4 v[194:197], v[142:143], off offset:16
	global_load_dwordx4 v[198:201], v[142:143], off offset:32
	global_load_dwordx4 v[202:205], v[142:143], off offset:48
	global_load_dword v206, v[170:171], off
	global_load_dword v188, v[170:171], off offset:64
	global_load_dword v186, v[170:171], off offset:128
	global_load_dword v184, v[170:171], off offset:192
	global_load_dword v182, v[170:171], off offset:512
	global_load_dword v180, v[170:171], off offset:576
	global_load_dword v178, v[170:171], off offset:640
	global_load_dword v122, v[170:171], off offset:704
	s_ashr_i32 s0, s59, 2
	s_lshl_b32 s1, s0, 10
	v_mov_b64_e32 v[142:143], s[10:11]
	s_add_i32 s2, s1, 0xc00
	v_cvt_f32_i32_e32 v209, v127
	v_cvt_f32_i32_e32 v208, v126
	v_cvt_f32_i32_e32 v215, v125
	v_cvt_f32_i32_e32 v214, v124
	s_cmp_lt_i32 s0, 3
	v_mad_i64_i32 v[124:125], s[0:1], v164, s57, v[142:143]
	s_cselect_b32 s0, s2, 0
	v_cvt_f32_i32_e32 v211, v129
	v_cvt_f32_i32_e32 v210, v128
	s_ashr_i32 s1, s0, 31
	v_cvt_f32_i32_e32 v115, v115
	v_cvt_f32_i32_e32 v114, v114
	v_cvt_f32_i32_e32 v99, v99
	v_cvt_f32_i32_e32 v98, v98
	v_cvt_f32_i32_e32 v83, v83
	v_cvt_f32_i32_e32 v82, v82
	v_cvt_f32_i32_e32 v67, v67
	v_cvt_f32_i32_e32 v66, v66
	v_cvt_f32_i32_e32 v51, v51
	v_cvt_f32_i32_e32 v50, v50
	v_cvt_f32_i32_e32 v35, v35
	v_cvt_f32_i32_e32 v34, v34
	v_cvt_f32_i32_e32 v19, v19
	v_cvt_f32_i32_e32 v18, v18
	v_and_b32_e32 v154, 0x3f0, v144
	v_lshl_add_u64 v[124:125], v[124:125], 0, s[0:1]
	v_cvt_f32_i32_e32 v117, v117
	v_cvt_f32_i32_e32 v116, v116
	v_cvt_f32_i32_e32 v111, v111
	v_cvt_f32_i32_e32 v110, v110
	v_cvt_f32_i32_e32 v101, v101
	v_cvt_f32_i32_e32 v100, v100
	v_cvt_f32_i32_e32 v95, v95
	v_cvt_f32_i32_e32 v94, v94
	v_cvt_f32_i32_e32 v85, v85
	v_cvt_f32_i32_e32 v84, v84
	v_cvt_f32_i32_e32 v79, v79
	v_cvt_f32_i32_e32 v78, v78
	v_cvt_f32_i32_e32 v69, v69
	v_cvt_f32_i32_e32 v68, v68
	v_cvt_f32_i32_e32 v63, v63
	v_cvt_f32_i32_e32 v62, v62
	v_cvt_f32_i32_e32 v53, v53
	v_cvt_f32_i32_e32 v52, v52
	v_cvt_f32_i32_e32 v47, v47
	v_cvt_f32_i32_e32 v46, v46
	v_cvt_f32_i32_e32 v37, v37
	v_cvt_f32_i32_e32 v36, v36
	v_cvt_f32_i32_e32 v31, v31
	v_cvt_f32_i32_e32 v30, v30
	v_cvt_f32_i32_e32 v21, v21
	v_cvt_f32_i32_e32 v20, v20
	v_cvt_f32_i32_e32 v15, v15
	v_cvt_f32_i32_e32 v14, v14
	v_add_u32_e32 v207, 32, v164
	v_lshl_add_u64 v[216:217], v[124:125], 0, v[154:155]
	v_add_u32_e32 v189, 0xa0, v164
	v_cvt_f32_i32_e32 v213, v123
	v_add_u32_e32 v123, 0xb0, v164
	v_cvt_f32_i32_e32 v119, v119
	v_cvt_f32_i32_e32 v118, v118
	v_cvt_f32_i32_e32 v109, v109
	v_cvt_f32_i32_e32 v108, v108
	v_cvt_f32_i32_e32 v103, v103
	v_cvt_f32_i32_e32 v102, v102
	v_cvt_f32_i32_e32 v93, v93
	v_cvt_f32_i32_e32 v121, v121
	v_cvt_f32_i32_e32 v120, v120
	v_cvt_f32_i32_e32 v113, v113
	v_cvt_f32_i32_e32 v112, v112
	v_cvt_f32_i32_e32 v107, v107
	v_cvt_f32_i32_e32 v106, v106
	v_cvt_f32_i32_e32 v105, v105
	v_cvt_f32_i32_e32 v104, v104
	v_cvt_f32_i32_e32 v92, v92
	v_cvt_f32_i32_e32 v87, v87
	v_cvt_f32_i32_e32 v86, v86
	v_cvt_f32_i32_e32 v97, v97
	v_cvt_f32_i32_e32 v96, v96
	v_cvt_f32_i32_e32 v91, v91
	v_cvt_f32_i32_e32 v90, v90
	v_cvt_f32_i32_e32 v89, v89
	v_cvt_f32_i32_e32 v88, v88
	v_cvt_f32_i32_e32 v77, v77
	v_cvt_f32_i32_e32 v76, v76
	v_cvt_f32_i32_e32 v71, v71
	v_cvt_f32_i32_e32 v70, v70
	v_cvt_f32_i32_e32 v81, v81
	v_cvt_f32_i32_e32 v80, v80
	v_cvt_f32_i32_e32 v75, v75
	v_cvt_f32_i32_e32 v74, v74
	v_cvt_f32_i32_e32 v73, v73
	v_cvt_f32_i32_e32 v72, v72
	v_cvt_f32_i32_e32 v61, v61
	v_cvt_f32_i32_e32 v60, v60
	v_cvt_f32_i32_e32 v55, v55
	v_cvt_f32_i32_e32 v54, v54
	v_cvt_f32_i32_e32 v65, v65
	v_cvt_f32_i32_e32 v64, v64
	v_cvt_f32_i32_e32 v59, v59
	v_cvt_f32_i32_e32 v58, v58
	v_cvt_f32_i32_e32 v57, v57
	v_cvt_f32_i32_e32 v56, v56
	v_cvt_f32_i32_e32 v45, v45
	v_cvt_f32_i32_e32 v44, v44
	v_cvt_f32_i32_e32 v39, v39
	v_cvt_f32_i32_e32 v38, v38
	v_cvt_f32_i32_e32 v49, v49
	v_cvt_f32_i32_e32 v48, v48
	v_cvt_f32_i32_e32 v43, v43
	v_cvt_f32_i32_e32 v42, v42
	v_cvt_f32_i32_e32 v41, v41
	v_cvt_f32_i32_e32 v40, v40
	v_cvt_f32_i32_e32 v29, v29
	v_cvt_f32_i32_e32 v28, v28
	v_cvt_f32_i32_e32 v23, v23
	v_cvt_f32_i32_e32 v22, v22
	v_cvt_f32_i32_e32 v33, v33
	v_cvt_f32_i32_e32 v32, v32
	v_cvt_f32_i32_e32 v27, v27
	v_cvt_f32_i32_e32 v26, v26
	v_cvt_f32_i32_e32 v25, v25
	v_cvt_f32_i32_e32 v24, v24
	v_cvt_f32_i32_e32 v7, v7
	v_cvt_f32_i32_e32 v6, v6
	v_cvt_f32_i32_e32 v3, v3
	v_cvt_f32_i32_e32 v2, v2
	v_cvt_f32_i32_e32 v17, v17
	v_cvt_f32_i32_e32 v16, v16
	v_cvt_f32_i32_e32 v11, v11
	v_cvt_f32_i32_e32 v13, v13
	v_cvt_f32_i32_e32 v12, v12
	v_cvt_f32_i32_e32 v10, v10
	v_cvt_f32_i32_e32 v9, v9
	v_cvt_f32_i32_e32 v8, v8
	v_cvt_f32_i32_e32 v5, v5
	v_cvt_f32_i32_e32 v4, v4
	s_and_b64 vcc, exec, s[20:21]
	s_cbranch_vccz .LBB0_2555
	s_barrier

; #define PG8_STAGE(bufoff, gbase, voff) do { _Pragma("unroll") for (int _i = 0; _i < 2; ++_i) \
;         __builtin_amdgcn_global_load_lds((const unsigned*)((const char*)(gbase) + (voff)[_i]), (PG8_LAS unsigned*)(lds + (bufoff) + ldsw + _i * 8192), 16, 0, 0); } while (0)
; #define PG8_LDA(dst, b, h) do { _Pragma("unroll") for (int m = 0; m < 4; ++m) _Pragma("unroll") for (int k = 0; k < 2; ++k) dst[m][k] = *(const PG8_LAS bf16x8*)(lds + PG8_SA(b, h) + aoff + m * 2048 + k * 1024); } while (0)
; #define PG8_LDB(dst, b, h) do { _Pragma("unroll") for (int n = 0; n < 2; ++n) _Pragma("unroll") for (int k = 0; k < 2; ++k) dst[n][k] = *(const PG8_LAS bf16x8*)(lds + PG8_SB(b, h) + boff + n * 2048 + k * 1024); } while (0)
; #define PG8_MMA(ai, bj, At, Bt) do { __builtin_amdgcn_s_setprio(1); _Pragma("unroll") for (int m = 0; m < 4; ++m) _Pragma("unroll") for (int n = 0; n < 2; ++n) _Pragma("unroll") for (int k = 0; k < 2; ++k) \
;         acc[ai][bj][m][n] = Gemm::i8 ? ::mfma16i8_g(Bt[n][k], At[m][k], acc[ai][bj][m][n]) : ::mfma16_g(Bt[n][k], At[m][k], acc[ai][bj][m][n]); __builtin_amdgcn_s_setprio(0); } while (0)
; #define PG8_WAIT_V(n) asm volatile("s_waitcnt vmcnt(" #n ")" ::: "memory")
; #define PG8_WAIT_L(n) asm volatile("s_waitcnt lgkmcnt(" #n ")" ::: "memory")
; template <class Epi, class Sched, class Gemm, bool ALIGN_EPI = false, bool SP2 = false>
; __device__ __forceinline__ void gemm_phase(PG8_LAS unsigned char* lds, const Gemm g, const Sched& S, const Epi& E) {
;     ...
;             PG8_LDB(B0, 0, 0); PG8_LDB(B1, 0, 1); PG8_SCHED; PG8_LDA(At, 0, 0); PG8_STAGE(PG8_SA(1, 1), a1 + hstepA, voffA);
;             PG8_WAIT_V(8); PG8_WAIT_L(0); PG8_BAR; PG8_MMA(0, 0, At, B0); PG8_MMA(0, 1, At, B1); PG8_BAR; PG8_SCHED;
;             PG8_LDA(At, 0, 1); PG8_STAGE(PG8_SB(0, 0), b2, voffB); PG8_STAGE(PG8_SB(0, 1), b2 + hB1, voffB1); PG8_STAGE(PG8_SA(0, 0), a2, voffA);
;             PG8_WAIT_V(8); PG8_WAIT_L(0); PG8_BAR; PG8_MMA(1, 0, At, B0); PG8_MMA(1, 1, At, B1); PG8_BAR; PG8_SCHED;
;             PG8_LDB(B0, 1, 0); PG8_LDB(B1, 1, 1); PG8_SCHED; PG8_LDA(At, 1, 0); PG8_STAGE(PG8_SA(0, 1), a2 + hstepA, voffA);
;             PG8_WAIT_V(8); PG8_WAIT_L(0); PG8_BAR; PG8_MMA(0, 0, At, B0); PG8_MMA(0, 1, At, B1); PG8_BAR; PG8_SCHED;
;             PG8_LDA(At, 1, 1); PG8_STAGE(PG8_SB(1, 0), b3, voffB); PG8_STAGE(PG8_SB(1, 1), b3 + hB1, voffB1); PG8_STAGE(PG8_SA(1, 0), a3, voffA);
.LBB0_2633:
	s_add_u32 s42, s30, s36
	s_addc_u32 s43, s31, s37
	s_add_u32 s40, s42, 0x100
	s_addc_u32 s41, s43, 0
	s_and_b64 s[38:39], s[2:3], exec
	s_cselect_b32 s39, s1, s41
	s_cselect_b32 s38, s23, s40
	s_add_u32 s36, s28, s36
	s_addc_u32 s37, s29, s37
	s_add_u32 s36, s36, 0x100
	s_addc_u32 s37, s37, 0
	s_and_b64 s[2:3], s[2:3], exec
	s_cselect_b32 s41, s21, s37
	s_cselect_b32 s40, s67, s36
	s_add_u32 s74, s42, 0x40080
	s_addc_u32 s75, s43, 0
	s_add_i32 s77, s61, s49
	s_add_i32 m0, s50, 0xc000
	s_add_i32 s76, s50, 0xe000
	s_add_i32 s78, s77, 0x2000
	v_add_u32_e32 v2, s61, v184
	s_add_u32 s42, s40, 0x1000
	ds_read_b128 v[158:161], v2
	ds_read_b128 v[162:165], v2 offset:1024
	ds_read_b128 v[186:189], v2 offset:2048
	ds_read_b128 v[190:193], v2 offset:3072
	v_add_u32_e32 v2, s62, v184
	s_addc_u32 s43, s41, 0
	s_add_i32 s79, s62, s49
	ds_read_b128 v[138:141], v2
	ds_read_b128 v[142:145], v2 offset:1024
	ds_read_b128 v[146:149], v2 offset:2048
	ds_read_b128 v[134:137], v2 offset:3072
	s_add_i32 s80, s79, 0x2000
	s_add_i32 s73, 0, 0x18000
	s_add_i32 s72, 0, 0x1c000
	s_add_u32 s2, s38, 0x40000
	s_addc_u32 s3, s39, 0
	s_add_i32 s69, s73, s49
	s_add_i32 s68, s69, 0x2000
	s_add_u32 s36, s40, 0x1080
	s_addc_u32 s37, s41, 0
	s_add_i32 s71, s72, s49
	s_add_i32 s70, s71, 0x2000
	ds_read_b128 v[150:153], v185
	ds_read_b128 v[154:157], v185 offset:1024
	ds_read_b128 v[194:197], v185 offset:2048
	ds_read_b128 v[198:201], v185 offset:3072
	ds_read_b128 v[202:205], v185 offset:4096
	ds_read_b128 v[206:209], v185 offset:5120
	ds_read_b128 v[210:213], v185 offset:6144
	ds_read_b128 v[214:217], v185 offset:7168
	global_load_lds_dwordx4 v166, s[74:75]
	s_mov_b32 m0, s76
	s_nop 0
	global_load_lds_dwordx4 v170, s[74:75]
	s_waitcnt vmcnt(8)
	s_waitcnt lgkmcnt(0)
	s_barrier
	s_setprio 1
	s_waitcnt lgkmcnt(0)
	v_mfma_f32_16x16x32_bf16 v[218:221], v[158:161], v[150:153], v[78:81]
	v_mfma_f32_16x16x32_bf16 v[78:81], v[162:165], v[154:157], v[218:221]
	v_mfma_f32_16x16x32_bf16 v[222:225], v[186:189], v[150:153], v[62:65]
	v_mfma_f32_16x16x32_bf16 v[226:229], v[158:161], v[194:197], v[130:133]
	v_mfma_f32_16x16x32_bf16 v[230:233], v[186:189], v[194:197], v[126:129]
	v_mfma_f32_16x16x32_bf16 v[234:237], v[158:161], v[202:205], v[74:77]
	v_mfma_f32_16x16x32_bf16 v[238:241], v[186:189], v[202:205], v[102:105]
	v_mfma_f32_16x16x32_bf16 v[218:221], v[158:161], v[210:213], v[122:125]
	v_mfma_f32_16x16x32_bf16 v[114:117], v[186:189], v[210:213], v[114:117]
	v_mfma_f32_16x16x32_bf16 v[62:65], v[190:193], v[154:157], v[222:225]
	v_mfma_f32_16x16x32_bf16 v[130:133], v[162:165], v[198:201], v[226:229]
	v_mfma_f32_16x16x32_bf16 v[126:129], v[190:193], v[198:201], v[230:233]
	v_mfma_f32_16x16x32_bf16 v[74:77], v[162:165], v[206:209], v[234:237]
	v_mfma_f32_16x16x32_bf16 v[102:105], v[190:193], v[206:209], v[238:241]
	v_mfma_f32_16x16x32_bf16 v[122:125], v[162:165], v[214:217], v[218:221]
	v_mfma_f32_16x16x32_bf16 v[114:117], v[190:193], v[214:217], v[114:117]
	s_setprio 0
	s_setprio 1
	v_mfma_f32_16x16x32_bf16 v[218:221], v[138:141], v[150:153], v[50:53]
	v_mfma_f32_16x16x32_bf16 v[50:53], v[142:145], v[154:157], v[218:221]
	v_mfma_f32_16x16x32_bf16 v[222:225], v[146:149], v[150:153], v[30:33]
	v_mfma_f32_16x16x32_bf16 v[226:229], v[138:141], v[194:197], v[110:113]
	v_mfma_f32_16x16x32_bf16 v[230:233], v[146:149], v[194:197], v[34:37]
	v_mfma_f32_16x16x32_bf16 v[234:237], v[138:141], v[202:205], v[46:49]
	v_mfma_f32_16x16x32_bf16 v[238:241], v[146:149], v[202:205], v[18:21]
	v_mfma_f32_16x16x32_bf16 v[150:153], v[138:141], v[210:213], v[90:93]
	v_mfma_f32_16x16x32_bf16 v[26:29], v[146:149], v[210:213], v[26:29]
	v_mfma_f32_16x16x32_bf16 v[30:33], v[134:137], v[154:157], v[222:225]
	v_mfma_f32_16x16x32_bf16 v[110:113], v[142:145], v[198:201], v[226:229]
	v_mfma_f32_16x16x32_bf16 v[34:37], v[134:137], v[198:201], v[230:233]
	v_mfma_f32_16x16x32_bf16 v[46:49], v[142:145], v[206:209], v[234:237]
	v_mfma_f32_16x16x32_bf16 v[18:21], v[134:137], v[206:209], v[238:241]
	v_mfma_f32_16x16x32_bf16 v[90:93], v[142:145], v[214:217], v[150:153]
	v_mfma_f32_16x16x32_bf16 v[26:29], v[134:137], v[214:217], v[26:29]
	s_setprio 0
	s_barrier
	s_mov_b32 m0, s77
	v_lshl_add_u64 v[150:151], s[40:41], 0, v[168:169]
	ds_read_b128 v[194:197], v185 offset:16384
	ds_read_b128 v[198:201], v185 offset:17408
	ds_read_b128 v[202:205], v185 offset:18432
	ds_read_b128 v[206:209], v185 offset:19456
	ds_read_b128 v[210:213], v185 offset:20480
	ds_read_b128 v[214:217], v185 offset:21504
	ds_read_b128 v[218:221], v185 offset:22528
	ds_read_b128 v[222:225], v185 offset:23552
	global_load_lds_dwordx4 v168, s[40:41]
	v_lshl_add_u64 v[152:153], s[40:41], 0, v[172:173]
	s_mov_b32 m0, s78
	v_lshl_add_u64 v[4:5], s[42:43], 0, v[168:169]
	global_load_lds_dwordx4 v172, s[40:41]
	s_mov_b32 m0, s79
	v_lshl_add_u64 v[154:155], s[38:39], 0, v[166:167]
	global_load_lds_dwordx4 v168, s[42:43]
	v_lshl_add_u64 v[4:5], s[42:43], 0, v[172:173]
	s_mov_b32 m0, s80
	v_lshl_add_u64 v[156:157], s[38:39], 0, v[170:171]
	global_load_lds_dwordx4 v172, s[42:43]
	s_mov_b32 m0, s50
	s_nop 0
	global_load_lds_dwordx4 v166, s[38:39]
	s_mov_b32 m0, s51
	s_nop 0
	global_load_lds_dwordx4 v170, s[38:39]
	s_waitcnt vmcnt(8)
	s_waitcnt lgkmcnt(0)
	s_barrier
; #define PG8_STAGE(bufoff, gbase, voff) do { _Pragma("unroll") for (int _i = 0; _i < 2; ++_i) \
;         __builtin_amdgcn_global_load_lds((const unsigned*)((const char*)(gbase) + (voff)[_i]), (PG8_LAS unsigned*)(lds + (bufoff) + ldsw + _i * 8192), 16, 0, 0); } while (0)
; #define PG8_LDA(dst, b, h) do { _Pragma("unroll") for (int m = 0; m < 4; ++m) _Pragma("unroll") for (int k = 0; k < 2; ++k) dst[m][k] = *(const PG8_LAS bf16x8*)(lds + PG8_SA(b, h) + aoff + m * 2048 + k * 1024); } while (0)
; #define PG8_LDB(dst, b, h) do { _Pragma("unroll") for (int n = 0; n < 2; ++n) _Pragma("unroll") for (int k = 0; k < 2; ++k) dst[n][k] = *(const PG8_LAS bf16x8*)(lds + PG8_SB(b, h) + boff + n * 2048 + k * 1024); } while (0)
; #define PG8_MMA(ai, bj, At, Bt) do { __builtin_amdgcn_s_setprio(1); _Pragma("unroll") for (int m = 0; m < 4; ++m) _Pragma("unroll") for (int n = 0; n < 2; ++n) _Pragma("unroll") for (int k = 0; k < 2; ++k) \
;         acc[ai][bj][m][n] = Gemm::i8 ? ::mfma16i8_g(Bt[n][k], At[m][k], acc[ai][bj][m][n]) : ::mfma16_g(Bt[n][k], At[m][k], acc[ai][bj][m][n]); __builtin_amdgcn_s_setprio(0); } while (0)
; #define PG8_WAIT_V(n) asm volatile("s_waitcnt vmcnt(" #n ")" ::: "memory")
; #define PG8_WAIT_L(n) asm volatile("s_waitcnt lgkmcnt(" #n ")" ::: "memory")
; #define PG8_BAR __builtin_amdgcn_s_barrier()
; #define PG8_SCHED __builtin_amdgcn_sched_barrier(0)
; template <class Epi, class Sched, class Gemm, bool ALIGN_EPI = false, bool SP2 = false>
; __device__ __forceinline__ void gemm_phase(PG8_LAS unsigned char* lds, const Gemm g, const Sched& S, const Epi& E) {
;     ...
;             PG8_LDA(At, 0, 1); PG8_STAGE(PG8_SB(0, 0), b2, voffB); PG8_STAGE(PG8_SB(0, 1), b2 + hB1, voffB1); PG8_STAGE(PG8_SA(0, 0), a2, voffA);
;             PG8_WAIT_V(8); PG8_WAIT_L(0); PG8_BAR; PG8_MMA(1, 0, At, B0); PG8_MMA(1, 1, At, B1); PG8_BAR; PG8_SCHED;
;             PG8_LDB(B0, 1, 0); PG8_LDB(B1, 1, 1); PG8_SCHED; PG8_LDA(At, 1, 0); PG8_STAGE(PG8_SA(0, 1), a2 + hstepA, voffA);
;             PG8_WAIT_V(8); PG8_WAIT_L(0); PG8_BAR; PG8_MMA(0, 0, At, B0); PG8_MMA(0, 1, At, B1); PG8_BAR; PG8_SCHED;
;             PG8_LDA(At, 1, 1); PG8_STAGE(PG8_SB(1, 0), b3, voffB); PG8_STAGE(PG8_SB(1, 1), b3 + hB1, voffB1); PG8_STAGE(PG8_SA(1, 0), a3, voffA);
	s_setprio 1
	s_waitcnt lgkmcnt(0)
	v_mfma_f32_16x16x32_bf16 v[226:229], v[158:161], v[194:197], v[70:73]
	v_mfma_f32_16x16x32_bf16 v[70:73], v[162:165], v[198:201], v[226:229]
	v_mfma_f32_16x16x32_bf16 v[230:233], v[186:189], v[194:197], v[58:61]
	v_mfma_f32_16x16x32_bf16 v[234:237], v[158:161], v[202:205], v[98:101]
	v_mfma_f32_16x16x32_bf16 v[238:241], v[186:189], v[202:205], v[86:89]
	v_mfma_f32_16x16x32_bf16 v[242:245], v[158:161], v[210:213], v[66:69]
	v_mfma_f32_16x16x32_bf16 v[246:249], v[186:189], v[210:213], v[94:97]
	v_mfma_f32_16x16x32_bf16 v[226:229], v[158:161], v[218:221], v[118:121]
	v_mfma_f32_16x16x32_bf16 v[106:109], v[186:189], v[218:221], v[106:109]
	v_mfma_f32_16x16x32_bf16 v[58:61], v[190:193], v[198:201], v[230:233]
	v_mfma_f32_16x16x32_bf16 v[98:101], v[162:165], v[206:209], v[234:237]
	v_mfma_f32_16x16x32_bf16 v[86:89], v[190:193], v[206:209], v[238:241]
	v_mfma_f32_16x16x32_bf16 v[66:69], v[162:165], v[214:217], v[242:245]
	v_mfma_f32_16x16x32_bf16 v[94:97], v[190:193], v[214:217], v[246:249]
	v_mfma_f32_16x16x32_bf16 v[118:121], v[162:165], v[222:225], v[226:229]
	v_mfma_f32_16x16x32_bf16 v[106:109], v[190:193], v[222:225], v[106:109]
	s_setprio 0
	s_setprio 1
	v_mfma_f32_16x16x32_bf16 v[158:161], v[138:141], v[194:197], v[42:45]
	v_mfma_f32_16x16x32_bf16 v[42:45], v[142:145], v[198:201], v[158:161]
	v_mfma_f32_16x16x32_bf16 v[162:165], v[146:149], v[194:197], v[6:9]
	v_mfma_f32_16x16x32_bf16 v[186:189], v[138:141], v[202:205], v[54:57]
	v_mfma_f32_16x16x32_bf16 v[190:193], v[146:149], v[202:205], v[10:13]
	v_mfma_f32_16x16x32_bf16 v[226:229], v[138:141], v[210:213], v[38:41]
	v_mfma_f32_16x16x32_bf16 v[230:233], v[146:149], v[210:213], v[14:17]
	v_mfma_f32_16x16x32_bf16 v[158:161], v[138:141], v[218:221], v[82:85]
	v_mfma_f32_16x16x32_bf16 v[22:25], v[146:149], v[218:221], v[22:25]
	v_mfma_f32_16x16x32_bf16 v[4:7], v[134:137], v[198:201], v[162:165]
	v_mfma_f32_16x16x32_bf16 v[54:57], v[142:145], v[206:209], v[186:189]
	v_mfma_f32_16x16x32_bf16 v[10:13], v[134:137], v[206:209], v[190:193]
	v_mfma_f32_16x16x32_bf16 v[38:41], v[142:145], v[214:217], v[226:229]
	v_mfma_f32_16x16x32_bf16 v[14:17], v[134:137], v[214:217], v[230:233]
	v_mfma_f32_16x16x32_bf16 v[82:85], v[142:145], v[222:225], v[158:161]
	v_mfma_f32_16x16x32_bf16 v[22:25], v[134:137], v[222:225], v[22:25]
	s_setprio 0
	s_barrier
	v_add_u32_e32 v2, s73, v184
	ds_read_b128 v[158:161], v2
	ds_read_b128 v[162:165], v2 offset:1024
	ds_read_b128 v[186:189], v2 offset:2048
	ds_read_b128 v[190:193], v2 offset:3072
	v_add_u32_e32 v2, s72, v184
	ds_read_b128 v[138:141], v2
	ds_read_b128 v[142:145], v2 offset:1024
	ds_read_b128 v[146:149], v2 offset:2048
	ds_read_b128 v[134:137], v2 offset:3072
	s_mov_b32 m0, s52
	ds_read_b128 v[194:197], v185 offset:32768
	ds_read_b128 v[198:201], v185 offset:33792
	ds_read_b128 v[202:205], v185 offset:34816
	ds_read_b128 v[206:209], v185 offset:35840
	ds_read_b128 v[210:213], v185 offset:36864
	ds_read_b128 v[214:217], v185 offset:37888
	ds_read_b128 v[218:221], v185 offset:38912
	ds_read_b128 v[222:225], v185 offset:39936
	global_load_lds_dwordx4 v166, s[2:3]
	s_mov_b32 m0, s53
	s_nop 0
	global_load_lds_dwordx4 v170, s[2:3]
	s_waitcnt vmcnt(8)
	s_waitcnt lgkmcnt(0)
	s_barrier
	s_setprio 1
	s_waitcnt lgkmcnt(0)
	v_mfma_f32_16x16x32_bf16 v[226:229], v[158:161], v[194:197], v[78:81]
	v_mfma_f32_16x16x32_bf16 v[78:81], v[162:165], v[198:201], v[226:229]
	v_mfma_f32_16x16x32_bf16 v[230:233], v[186:189], v[194:197], v[62:65]
	v_mfma_f32_16x16x32_bf16 v[234:237], v[158:161], v[202:205], v[130:133]
	v_mfma_f32_16x16x32_bf16 v[238:241], v[186:189], v[202:205], v[126:129]
	v_mfma_f32_16x16x32_bf16 v[242:245], v[158:161], v[210:213], v[74:77]
	v_mfma_f32_16x16x32_bf16 v[246:249], v[186:189], v[210:213], v[102:105]
	v_mfma_f32_16x16x32_bf16 v[226:229], v[158:161], v[218:221], v[122:125]
	v_mfma_f32_16x16x32_bf16 v[114:117], v[186:189], v[218:221], v[114:117]
	v_mfma_f32_16x16x32_bf16 v[62:65], v[190:193], v[198:201], v[230:233]
	v_mfma_f32_16x16x32_bf16 v[130:133], v[162:165], v[206:209], v[234:237]
	v_mfma_f32_16x16x32_bf16 v[126:129], v[190:193], v[206:209], v[238:241]
	v_mfma_f32_16x16x32_bf16 v[74:77], v[162:165], v[214:217], v[242:245]
	v_mfma_f32_16x16x32_bf16 v[102:105], v[190:193], v[214:217], v[246:249]
	v_mfma_f32_16x16x32_bf16 v[122:125], v[162:165], v[222:225], v[226:229]
	v_mfma_f32_16x16x32_bf16 v[114:117], v[190:193], v[222:225], v[114:117]
	s_setprio 0
	s_setprio 1
	v_mfma_f32_16x16x32_bf16 v[226:229], v[138:141], v[194:197], v[50:53]
	v_mfma_f32_16x16x32_bf16 v[50:53], v[142:145], v[198:201], v[226:229]
	v_mfma_f32_16x16x32_bf16 v[230:233], v[146:149], v[194:197], v[30:33]
	v_mfma_f32_16x16x32_bf16 v[234:237], v[138:141], v[202:205], v[110:113]
	v_mfma_f32_16x16x32_bf16 v[238:241], v[146:149], v[202:205], v[34:37]
	v_mfma_f32_16x16x32_bf16 v[242:245], v[138:141], v[210:213], v[46:49]
	v_mfma_f32_16x16x32_bf16 v[246:249], v[146:149], v[210:213], v[18:21]
	v_mfma_f32_16x16x32_bf16 v[194:197], v[138:141], v[218:221], v[90:93]
	v_mfma_f32_16x16x32_bf16 v[26:29], v[146:149], v[218:221], v[26:29]
	v_mfma_f32_16x16x32_bf16 v[30:33], v[134:137], v[198:201], v[230:233]
	v_mfma_f32_16x16x32_bf16 v[110:113], v[142:145], v[206:209], v[234:237]
	v_mfma_f32_16x16x32_bf16 v[34:37], v[134:137], v[206:209], v[238:241]
	v_mfma_f32_16x16x32_bf16 v[46:49], v[142:145], v[214:217], v[242:245]
	v_mfma_f32_16x16x32_bf16 v[18:21], v[134:137], v[214:217], v[246:249]
	v_mfma_f32_16x16x32_bf16 v[90:93], v[142:145], v[222:225], v[194:197]
	v_mfma_f32_16x16x32_bf16 v[26:29], v[134:137], v[222:225], v[26:29]
	s_setprio 0
	s_barrier
; #define EPC_LOAD(i) do { const unsigned o_ = gbase + EPC_GOFF(i); gq[i] = *(const u32x4*)(MG + (o_ + go)); gr[i] = *(const u32x4*)(nbase + ((o_ + gn) & nmask)); } while (0)
; #define PG8_STAGE(bufoff, gbase, voff) do { _Pragma("unroll") for (int _i = 0; _i < 2; ++_i) \
;         __builtin_amdgcn_global_load_lds((const unsigned*)((const char*)(gbase) + (voff)[_i]), (PG8_LAS unsigned*)(lds + (bufoff) + ldsw + _i * 8192), 16, 0, 0); } while (0)
; #define PG8_LDA(dst, b, h) do { _Pragma("unroll") for (int m = 0; m < 4; ++m) _Pragma("unroll") for (int k = 0; k < 2; ++k) dst[m][k] = *(const PG8_LAS bf16x8*)(lds + PG8_SA(b, h) + aoff + m * 2048 + k * 1024); } while (0)
; #define PG8_WAIT_V(n) asm volatile("s_waitcnt vmcnt(" #n ")" ::: "memory")
;     __device__ __forceinline__ void chain(f32x4 (&acc)[2][2][4][2], const Unit& u, int wr, int wc, int fr, int fq) const {
;     ...
;         const bool last = (u.sub == 3);
;         const unsigned gbase = (unsigned)(u.pm * BM + wr * 64 + fr) * 8704u + (unsigned)(u.pn * BM + wc * 64 + 16 * fq);
;         const unsigned obase = (unsigned)(u.pm * BM + wr * 64 + fr) * 1024u + (unsigned)(u.pn * BM + wc * 64 + 16 * fq);
;         const unsigned go = last ? 0u : 3072u + 1024u * (unsigned)u.sub;
;         const unsigned gn = (u.sub < 2) ? go + 1024u : 0u, nmask = last ? 0u : 0xffffffffu;
;         const unsigned char* nbase = last ? FF : MG;
;         const float keep = last ? 0.f : 1.f;
;         u32x4 gq[8], gr[8];
;     ...
; #pragma unroll
;         for (int i = 0; i < DEPTH; ++i) EPC_LOAD(i);
; template <class Epi, class Sched, class Gemm, bool ALIGN_EPI = false, bool SP2 = false>
; __device__ __forceinline__ void gemm_phase(PG8_LAS unsigned char* lds, const Gemm g, const Sched& S, const Epi& E) {
;     ...
;             PG8_LDB(B0, 1, 0); PG8_LDB(B1, 1, 1); PG8_SCHED; PG8_LDA(At, 1, 0); PG8_STAGE(PG8_SA(0, 1), a2 + hstepA, voffA);
;             PG8_WAIT_V(8); PG8_WAIT_L(0); PG8_BAR; PG8_MMA(0, 0, At, B0); PG8_MMA(0, 1, At, B1); PG8_BAR; PG8_SCHED;
;             PG8_LDA(At, 1, 1); PG8_STAGE(PG8_SB(1, 0), b3, voffB); PG8_STAGE(PG8_SB(1, 1), b3 + hB1, voffB1); PG8_STAGE(PG8_SA(1, 0), a3, voffA);
;             PG8_WAIT_V(8);
;             if constexpr (epi_pre<Epi>::value) { if (last) E.pre(pre, cur, wr, wc, lane); }
;             PG8_WAIT_L(0); PG8_BAR; PG8_MMA(1, 0, At, B0); PG8_MMA(1, 1, At, B1); PG8_BAR; PG8_SCHED;
	s_mov_b32 m0, s69
	v_lshl_add_u64 v[8:9], v[150:151], 0, s[16:17]
	ds_read_b128 v[194:197], v185 offset:49152
	ds_read_b128 v[198:201], v185 offset:50176
	ds_read_b128 v[202:205], v185 offset:51200
	ds_read_b128 v[206:209], v185 offset:52224
	ds_read_b128 v[210:213], v185 offset:53248
	ds_read_b128 v[214:217], v185 offset:54272
	ds_read_b128 v[218:221], v185 offset:55296
	ds_read_b128 v[222:225], v185 offset:56320
	global_load_lds_dwordx4 v[8:9], off
	v_lshl_add_u64 v[8:9], v[152:153], 0, s[16:17]
	s_mov_b32 m0, s68
	s_nop 0
	global_load_lds_dwordx4 v[8:9], off
	s_mov_b32 m0, s71
	s_nop 0
	global_load_lds_dwordx4 v168, s[36:37]
	s_mov_b32 m0, s70
	s_nop 0
	global_load_lds_dwordx4 v172, s[36:37]
	v_lshl_add_u64 v[8:9], v[154:155], 0, s[16:17]
	s_mov_b32 m0, s57
	s_nop 0
	global_load_lds_dwordx4 v[8:9], off
	v_lshl_add_u64 v[8:9], v[156:157], 0, s[16:17]
	s_mov_b32 m0, s58
	s_nop 0
	global_load_lds_dwordx4 v[8:9], off
	s_waitcnt vmcnt(8)
	s_waitcnt lgkmcnt(0)
	s_barrier
	s_setprio 1
	s_waitcnt lgkmcnt(0)
	v_mfma_f32_16x16x32_bf16 v[150:153], v[158:161], v[194:197], v[70:73]
	v_mfma_f32_16x16x32_bf16 v[70:73], v[162:165], v[198:201], v[150:153]
	v_mfma_f32_16x16x32_bf16 v[154:157], v[186:189], v[194:197], v[58:61]
	v_mfma_f32_16x16x32_bf16 v[226:229], v[158:161], v[202:205], v[98:101]
	v_mfma_f32_16x16x32_bf16 v[230:233], v[186:189], v[202:205], v[86:89]
	v_mfma_f32_16x16x32_bf16 v[234:237], v[158:161], v[210:213], v[66:69]
	v_mfma_f32_16x16x32_bf16 v[238:241], v[186:189], v[210:213], v[94:97]
	v_mfma_f32_16x16x32_bf16 v[150:153], v[158:161], v[218:221], v[118:121]
	v_mfma_f32_16x16x32_bf16 v[106:109], v[186:189], v[218:221], v[106:109]
	v_mfma_f32_16x16x32_bf16 v[58:61], v[190:193], v[198:201], v[154:157]
	v_mfma_f32_16x16x32_bf16 v[98:101], v[162:165], v[206:209], v[226:229]
	v_mfma_f32_16x16x32_bf16 v[86:89], v[190:193], v[206:209], v[230:233]
	v_mfma_f32_16x16x32_bf16 v[66:69], v[162:165], v[214:217], v[234:237]
	v_mfma_f32_16x16x32_bf16 v[94:97], v[190:193], v[214:217], v[238:241]
	v_mfma_f32_16x16x32_bf16 v[118:121], v[162:165], v[222:225], v[150:153]
	v_mfma_f32_16x16x32_bf16 v[106:109], v[190:193], v[222:225], v[106:109]
	s_setprio 0
	s_setprio 1
	v_mfma_f32_16x16x32_bf16 v[150:153], v[138:141], v[194:197], v[42:45]
	v_mfma_f32_16x16x32_bf16 v[42:45], v[142:145], v[198:201], v[150:153]
	v_mfma_f32_16x16x32_bf16 v[154:157], v[146:149], v[194:197], v[4:7]
	v_mfma_f32_16x16x32_bf16 v[158:161], v[138:141], v[202:205], v[54:57]
	v_mfma_f32_16x16x32_bf16 v[162:165], v[146:149], v[202:205], v[10:13]
	v_mfma_f32_16x16x32_bf16 v[186:189], v[138:141], v[210:213], v[38:41]
	v_mfma_f32_16x16x32_bf16 v[190:193], v[146:149], v[210:213], v[14:17]
	v_mfma_f32_16x16x32_bf16 v[150:153], v[138:141], v[218:221], v[82:85]
	v_mfma_f32_16x16x32_bf16 v[22:25], v[146:149], v[218:221], v[22:25]
	v_mfma_f32_16x16x32_bf16 v[6:9], v[134:137], v[198:201], v[154:157]
	v_mfma_f32_16x16x32_bf16 v[54:57], v[142:145], v[206:209], v[158:161]
	v_mfma_f32_16x16x32_bf16 v[10:13], v[134:137], v[206:209], v[162:165]
	v_mfma_f32_16x16x32_bf16 v[38:41], v[142:145], v[214:217], v[186:189]
	v_mfma_f32_16x16x32_bf16 v[14:17], v[134:137], v[214:217], v[190:193]
	v_mfma_f32_16x16x32_bf16 v[82:85], v[142:145], v[222:225], v[150:153]
	v_mfma_f32_16x16x32_bf16 v[22:25], v[134:137], v[222:225], v[22:25]
	s_setprio 0
	s_barrier
	s_andn2_b64 vcc, exec, s[34:35]
	s_mov_b64 s[2:3], -1
	s_mov_b64 s[34:35], 0
	s_mov_b64 s[36:37], 0x100
	s_cbranch_vccz .LBB0_2633
	s_lshl_b32 s0, s0, 8
	s_lshl_b32 s1, s6, 8
	s_or_b32 s21, s0, s59
	s_lshl_b32 s0, s7, 10
	s_add_i32 s6, s1, s56
	s_add_i32 s23, s0, 0xc00
	s_cmp_eq_u32 s7, 3
	v_mov_b32_e32 v2, v181
	v_mov_b32_e32 v4, v1
	s_cselect_b64 s[0:1], -1, 0
	s_and_b64 s[2:3], s[0:1], exec
	s_cselect_b32 s2, 0, s23
	v_add_u32_e32 v4, s6, v4
	v_mul_lo_u32 v5, v4, s63
	v_lshlrev_b32_e32 v2, 4, v2
	s_cselect_b32 s28, s54, s14
	s_cselect_b32 s29, s55, s15
	s_add_i32 s3, s2, 0x400
	v_add3_u32 v180, s21, v2, v5
	s_cmp_lt_u32 s7, 2
	v_add_u32_e32 v2, s2, v180
	s_cselect_b32 s3, s3, 0
	global_load_dwordx4 v[142:145], v2, s[14:15]
	v_add_u32_e32 v2, s3, v180
	v_cndmask_b32_e64 v2, v2, 0, s[0:1]
	global_load_dwordx4 v[146:149], v2, s[28:29]
	v_add_u32_e32 v2, 0x22000, v180
	v_add_u32_e32 v138, 0x66000, v180
	v_add_u32_e32 v5, 0x44000, v180
	v_add_u32_e32 v134, s2, v2
	v_add_u32_e32 v136, s2, v138
	v_add_u32_e32 v2, s3, v2
	v_add_u32_e32 v138, s3, v138
	v_add_u32_e32 v135, s2, v5
	v_add_u32_e32 v5, s3, v5
	v_cndmask_b32_e64 v2, v2, 0, s[0:1]
	v_cndmask_b32_e64 v138, v138, 0, s[0:1]
	global_load_dwordx4 v[150:153], v134, s[14:15]
	global_load_dwordx4 v[154:157], v135, s[14:15]
	s_nop 0
	global_load_dwordx4 v[134:137], v136, s[14:15]
	v_cndmask_b32_e64 v5, v5, 0, s[0:1]
	global_load_dwordx4 v[158:161], v2, s[28:29]
	global_load_dwordx4 v[162:165], v5, s[28:29]
	s_nop 0
	global_load_dwordx4 v[138:141], v138, s[28:29]
	v_mad_u64_u32 v[4:5], s[30:31], v4, s64, v[180:181]
	s_and_b64 vcc, exec, s[18:19]
	s_cbranch_vccz .LBB0_2636
	s_barrier

; #define PG8_STAGE(bufoff, gbase, voff) do { _Pragma("unroll") for (int _i = 0; _i < 2; ++_i) \
;         __builtin_amdgcn_global_load_lds((const unsigned*)((const char*)(gbase) + (voff)[_i]), (PG8_LAS unsigned*)(lds + (bufoff) + ldsw + _i * 8192), 16, 0, 0); } while (0)
; #define PG8_WAIT_V(n) asm volatile("s_waitcnt vmcnt(" #n ")" ::: "memory")
; #define PG8_BAR __builtin_amdgcn_s_barrier()
; template <class Epi, class Sched, class Gemm, bool ALIGN_EPI = false, bool SP2 = false>
; __device__ __forceinline__ void gemm_phase(PG8_LAS unsigned char* lds, const Gemm g, const Sched& S, const Epi& E) {
;     ...
;     if constexpr (SP2) {
;         PG8_STAGE(PG8_SB(0, 0), cB, voffB); PG8_STAGE(PG8_SB(0, 1), cB + hB1, voffB1); PG8_STAGE(PG8_SA(0, 0), cA, voffA); PG8_STAGE(PG8_SA(0, 1), cA + hstepA, voffA);
;         if (wr == 1) PG8_BAR;
;         PG8_WAIT_V(2); PG8_BAR;
;         PG8_STAGE(PG8_SB(1, 0), cB + kstep, voffB); PG8_STAGE(PG8_SA(1, 0), cA + kstep, voffA); PG8_STAGE(PG8_SB(1, 1), cB + hB1 + kstep, voffB1);
;         PG8_WAIT_V(6); PG8_BAR;
;     } else {
;         PG8_STAGE(PG8_SB(0, 0), cB, voffB); PG8_STAGE(PG8_SA(0, 0), cA, voffA); PG8_STAGE(PG8_SB(0, 1), cB + hB1, voffB1); PG8_STAGE(PG8_SA(0, 1), cA + hstepA, voffA);
;         if (wr == 1) PG8_BAR;
;         PG8_WAIT_V(4); PG8_BAR;
;         PG8_STAGE(PG8_SB(1, 0), cB + kstep, voffB); PG8_STAGE(PG8_SA(1, 0), cA + kstep, voffA); PG8_STAGE(PG8_SB(1, 1), cB + hB1 + kstep, voffB1);
;         PG8_WAIT_V(6); PG8_BAR;
.LBB0_2720:
	s_add_u32 s14, s0, 0x1dcc8000
	s_addc_u32 s15, s1, 0
	s_add_u32 s60, s0, 0x6000
	s_addc_u32 s61, s1, 0
	s_lshl_b32 s62, s16, 6
	s_lshl_b32 s5, s16, 13
	s_lshl_b32 s0, s17, 5
	s_mov_b64 s[16:17], 0x80
	s_and_b32 s63, s0, 0x60
	s_add_i32 m0, s55, 0x18000
	v_lshl_add_u64 v[8:9], v[8:9], 0, s[16:17]
	s_lshl_b32 s19, s63, 7
	s_waitcnt vmcnt(2)
	s_barrier
	global_load_lds_dwordx4 v[8:9], off
	v_lshl_add_u64 v[6:7], v[6:7], 0, s[16:17]
	s_add_i32 m0, s55, 0x1a000
	s_add_i32 s64, s55, 0x8000
	s_add_i32 s65, s55, 0xa000
	global_load_lds_dwordx4 v[6:7], off
	v_lshl_add_u64 v[2:3], v[2:3], 0, s[16:17]
	s_mov_b32 m0, s64
	s_add_u32 s0, s2, 0x40080
	global_load_lds_dwordx4 v[2:3], off
	v_lshl_add_u64 v[2:3], v[4:5], 0, s[16:17]
	s_mov_b32 m0, s65
	s_addc_u32 s1, s3, 0
	global_load_lds_dwordx4 v[2:3], off
	s_add_i32 m0, s55, 0x1c000
	v_lshl_add_u64 v[2:3], s[0:1], 0, v[178:179]
	global_load_lds_dwordx4 v178, s[0:1]
	v_lshl_add_u64 v[2:3], s[0:1], 0, v[182:183]
	s_add_i32 m0, s55, 0x1e000
	v_bfe_u32 v231, v0, 4, 2
	global_load_lds_dwordx4 v182, s[0:1]
	v_and_b32_e32 v230, 15, v0
	v_lshlrev_b32_e32 v2, 4, v231
	v_lshlrev_b32_e32 v0, 2, v0
	v_lshl_or_b32 v2, v230, 6, v2
	v_and_b32_e32 v0, 32, v0
	v_bitop3_b32 v3, v2, s5, v0 bitop3:0xde
	v_bitop3_b32 v232, v2, s19, v0 bitop3:0xde
	v_lshlrev_b32_e32 v0, 14, v12
	v_and_b32_e32 v0, 0xffff8000, v0
	v_lshl_add_u32 v0, v13, 11, v0
	v_and_b32_e32 v2, 1, v12
	v_lshl_or_b32 v0, v2, 6, v0
	v_lshl_add_u32 v184, v14, 1, v0
	v_lshlrev_b32_e32 v0, 14, v1
	v_and_b32_e32 v0, 0xffff8000, v0
	v_lshl_add_u32 v0, v10, 11, v0
	v_and_b32_e32 v1, 1, v1
	s_waitcnt vmcnt(6)
	s_cmpk_lt_u32 s18, 0x100
	v_lshl_or_b32 v0, v1, 6, v0
	s_cselect_b64 s[18:19], -1, 0
	v_lshl_add_u32 v186, v11, 1, v0
	s_add_i32 s68, 0, 0x10000
	s_add_i32 s69, 0, 0x14000
	v_mbcnt_lo_u32_b32 v0, -1, 0
	s_waitcnt lgkmcnt(0)
	s_ashr_i32 s66, s33, 31
	s_ashr_i32 s67, s88, 31
	v_mov_b32_e32 v185, v179
	v_mov_b32_e32 v187, v179
	v_mov_b64_e32 v[188:189], 0x200
	v_mov_b64_e32 v[190:191], 0x1ff
	v_add_u32_e32 v233, s68, v232
	v_add_u32_e32 v234, s69, v232
	v_add_u32_e32 v235, 0, v3
	s_mov_b64 s[20:21], 0x10000
	s_mov_b64 s[22:23], 0x20000
	s_mov_b64 s[24:25], 0x30000
	s_mov_b64 s[26:27], 0x80000
	s_mov_b32 s70, 0x80000
	v_mbcnt_hi_u32_b32 v236, -1, v0
	s_mov_b64 s[28:29], 0x90000
	s_mov_b32 s71, 0x90000
	s_mov_b64 s[30:31], 0xa0000
	s_mov_b32 s72, 0xa0000
	s_mov_b64 s[34:35], 0xb0000
	s_mov_b32 s73, 0xb0000
	v_mov_b32_e32 v237, 0x358637bd
	s_mov_b32 s74, 0xf800000
	v_mov_b32_e32 v238, 0x260
	s_barrier
	s_branch .LBB0_2723

; #define PG8_STAGE(bufoff, gbase, voff) do { _Pragma("unroll") for (int _i = 0; _i < 2; ++_i) \
;         __builtin_amdgcn_global_load_lds((const unsigned*)((const char*)(gbase) + (voff)[_i]), (PG8_LAS unsigned*)(lds + (bufoff) + ldsw + _i * 8192), 16, 0, 0); } while (0)
; #define PG8_LDA(dst, b, h) do { _Pragma("unroll") for (int m = 0; m < 4; ++m) _Pragma("unroll") for (int k = 0; k < 2; ++k) dst[m][k] = *(const PG8_LAS bf16x8*)(lds + PG8_SA(b, h) + aoff + m * 2048 + k * 1024); } while (0)
; #define PG8_LDB(dst, b, h) do { _Pragma("unroll") for (int n = 0; n < 2; ++n) _Pragma("unroll") for (int k = 0; k < 2; ++k) dst[n][k] = *(const PG8_LAS bf16x8*)(lds + PG8_SB(b, h) + boff + n * 2048 + k * 1024); } while (0)
; #define PG8_MMA(ai, bj, At, Bt) do { __builtin_amdgcn_s_setprio(1); _Pragma("unroll") for (int m = 0; m < 4; ++m) _Pragma("unroll") for (int n = 0; n < 2; ++n) _Pragma("unroll") for (int k = 0; k < 2; ++k) \
;         acc[ai][bj][m][n] = Gemm::i8 ? ::mfma16i8_g(Bt[n][k], At[m][k], acc[ai][bj][m][n]) : ::mfma16_g(Bt[n][k], At[m][k], acc[ai][bj][m][n]); __builtin_amdgcn_s_setprio(0); } while (0)
; #define PG8_WAIT_V(n) asm volatile("s_waitcnt vmcnt(" #n ")" ::: "memory")
; #define PG8_WAIT_L(n) asm volatile("s_waitcnt lgkmcnt(" #n ")" ::: "memory")
; #define PG8_BAR __builtin_amdgcn_s_barrier()
; #define PG8_SCHED __builtin_amdgcn_sched_barrier(0)
; template <class Epi, class Sched, class Gemm, bool ALIGN_EPI = false, bool SP2 = false>
; __device__ __forceinline__ void gemm_phase(PG8_LAS unsigned char* lds, const Gemm g, const Sched& S, const Epi& E) {
;     ...
;             PG8_LDB(B0, 0, 0); PG8_LDB(B1, 0, 1); PG8_SCHED; PG8_LDA(At, 0, 0); PG8_STAGE(PG8_SA(1, 1), a1 + hstepA, voffA);
;             PG8_WAIT_V(8); PG8_WAIT_L(0); PG8_BAR; PG8_MMA(0, 0, At, B0); PG8_MMA(0, 1, At, B1); PG8_BAR; PG8_SCHED;
;             PG8_LDA(At, 0, 1); PG8_STAGE(PG8_SB(0, 0), b2, voffB); PG8_STAGE(PG8_SB(0, 1), b2 + hB1, voffB1); PG8_STAGE(PG8_SA(0, 0), a2, voffA);
;             PG8_WAIT_V(8); PG8_WAIT_L(0); PG8_BAR; PG8_MMA(1, 0, At, B0); PG8_MMA(1, 1, At, B1); PG8_BAR; PG8_SCHED;
.LBB0_2730:
	ds_read_b128 v[152:155], v233
	ds_read_b128 v[156:159], v233 offset:1024
	ds_read_b128 v[160:163], v233 offset:2048
	ds_read_b128 v[164:167], v233 offset:3072
	ds_read_b128 v[132:135], v234
	ds_read_b128 v[136:139], v234 offset:1024
	ds_read_b128 v[140:143], v234 offset:2048
	ds_read_b128 v[128:131], v234 offset:3072
	s_add_u32 s2, s46, 0xfffc0080
	s_addc_u32 s3, s47, -1
	s_cmp_eq_u32 s77, 12
	s_cselect_b32 s3, s5, s3
	s_cselect_b32 s2, s39, s2
	s_cselect_b32 s49, s37, s76
	s_cselect_b32 s48, s45, s75
	s_add_i32 m0, s55, 0xc000
	ds_read_b128 v[144:147], v235
	ds_read_b128 v[148:151], v235 offset:1024
	ds_read_b128 v[168:171], v235 offset:2048
	ds_read_b128 v[172:175], v235 offset:3072
	ds_read_b128 v[192:195], v235 offset:4096
	ds_read_b128 v[196:199], v235 offset:5120
	ds_read_b128 v[200:203], v235 offset:6144
	ds_read_b128 v[204:207], v235 offset:7168
	global_load_lds_dwordx4 v186, s[46:47]
	v_lshl_add_u64 v[208:209], s[46:47], 0, v[184:185]
	s_add_i32 m0, s55, 0xe000
	s_nop 0
	global_load_lds_dwordx4 v184, s[46:47]
	s_waitcnt vmcnt(8)
	s_waitcnt lgkmcnt(0)
	s_barrier
	s_setprio 1
	s_waitcnt lgkmcnt(0)
	v_mfma_f32_16x16x32_bf16 v[208:211], v[152:155], v[144:147], v[124:127]
	v_mfma_f32_16x16x32_bf16 v[124:127], v[156:159], v[148:151], v[208:211]
	v_mfma_f32_16x16x32_bf16 v[212:215], v[160:163], v[144:147], v[120:123]
	v_mfma_f32_16x16x32_bf16 v[216:219], v[152:155], v[168:171], v[108:111]
	v_mfma_f32_16x16x32_bf16 v[220:223], v[160:163], v[168:171], v[104:107]
	v_mfma_f32_16x16x32_bf16 v[224:227], v[152:155], v[192:195], v[92:95]
	v_mfma_f32_16x16x32_bf16 v[240:243], v[160:163], v[192:195], v[88:91]
	v_mfma_f32_16x16x32_bf16 v[208:211], v[152:155], v[200:203], v[76:79]
	v_mfma_f32_16x16x32_bf16 v[72:75], v[160:163], v[200:203], v[72:75]
	v_mfma_f32_16x16x32_bf16 v[120:123], v[164:167], v[148:151], v[212:215]
	v_mfma_f32_16x16x32_bf16 v[108:111], v[156:159], v[172:175], v[216:219]
	v_mfma_f32_16x16x32_bf16 v[104:107], v[164:167], v[172:175], v[220:223]
	v_mfma_f32_16x16x32_bf16 v[92:95], v[156:159], v[196:199], v[224:227]
	v_mfma_f32_16x16x32_bf16 v[88:91], v[164:167], v[196:199], v[240:243]
	v_mfma_f32_16x16x32_bf16 v[76:79], v[156:159], v[204:207], v[208:211]
	v_mfma_f32_16x16x32_bf16 v[72:75], v[164:167], v[204:207], v[72:75]
	s_setprio 0
	s_setprio 1
	v_mfma_f32_16x16x32_bf16 v[208:211], v[132:135], v[144:147], v[116:119]
	v_mfma_f32_16x16x32_bf16 v[116:119], v[136:139], v[148:151], v[208:211]
	v_mfma_f32_16x16x32_bf16 v[212:215], v[140:143], v[144:147], v[112:115]
	v_mfma_f32_16x16x32_bf16 v[216:219], v[132:135], v[168:171], v[100:103]
	v_mfma_f32_16x16x32_bf16 v[220:223], v[140:143], v[168:171], v[96:99]
	v_mfma_f32_16x16x32_bf16 v[224:227], v[132:135], v[192:195], v[84:87]
	v_mfma_f32_16x16x32_bf16 v[240:243], v[140:143], v[192:195], v[80:83]
	v_mfma_f32_16x16x32_bf16 v[144:147], v[132:135], v[200:203], v[68:71]
	v_mfma_f32_16x16x32_bf16 v[64:67], v[140:143], v[200:203], v[64:67]
	v_mfma_f32_16x16x32_bf16 v[112:115], v[128:131], v[148:151], v[212:215]
	v_mfma_f32_16x16x32_bf16 v[100:103], v[136:139], v[172:175], v[216:219]
	v_mfma_f32_16x16x32_bf16 v[96:99], v[128:131], v[172:175], v[220:223]
	v_mfma_f32_16x16x32_bf16 v[84:87], v[136:139], v[196:199], v[224:227]
	v_mfma_f32_16x16x32_bf16 v[80:83], v[128:131], v[196:199], v[240:243]
	v_mfma_f32_16x16x32_bf16 v[68:71], v[136:139], v[204:207], v[144:147]
	v_mfma_f32_16x16x32_bf16 v[64:67], v[128:131], v[204:207], v[64:67]
	s_setprio 0
	s_barrier
	s_add_i32 s78, s68, s54
	v_lshl_add_u64 v[144:145], s[48:49], 0, v[178:179]
	s_mov_b32 m0, s78
	ds_read_b128 v[168:171], v235 offset:16384
	ds_read_b128 v[172:175], v235 offset:17408
	ds_read_b128 v[192:195], v235 offset:18432
	ds_read_b128 v[196:199], v235 offset:19456
	ds_read_b128 v[200:203], v235 offset:20480
	ds_read_b128 v[204:207], v235 offset:21504
	ds_read_b128 v[208:211], v235 offset:22528
	ds_read_b128 v[212:215], v235 offset:23552
	global_load_lds_dwordx4 v178, s[48:49]
	s_add_i32 m0, s78, 0x2000
	s_add_u32 s78, s48, 0x40000
	v_lshl_add_u64 v[146:147], s[48:49], 0, v[182:183]
	s_addc_u32 s79, s49, 0
	s_add_i32 s80, s69, s54
	global_load_lds_dwordx4 v182, s[48:49]
	s_mov_b32 m0, s80
	v_lshl_add_u64 v[150:151], s[2:3], 0, v[180:181]
	global_load_lds_dwordx4 v178, s[78:79]
	s_add_i32 m0, s80, 0x2000
	s_nop 0
	global_load_lds_dwordx4 v182, s[78:79]
	v_lshl_add_u64 v[148:149], s[2:3], 0, v[176:177]
	s_mov_b32 m0, s55
	s_nop 0
	global_load_lds_dwordx4 v176, s[2:3]
	s_mov_b32 m0, s56
	s_nop 0
	global_load_lds_dwordx4 v180, s[2:3]
	s_waitcnt vmcnt(8)
	s_waitcnt lgkmcnt(0)
	s_barrier
; #define PG8_STAGE(bufoff, gbase, voff) do { _Pragma("unroll") for (int _i = 0; _i < 2; ++_i) \
;         __builtin_amdgcn_global_load_lds((const unsigned*)((const char*)(gbase) + (voff)[_i]), (PG8_LAS unsigned*)(lds + (bufoff) + ldsw + _i * 8192), 16, 0, 0); } while (0)
; #define PG8_LDA(dst, b, h) do { _Pragma("unroll") for (int m = 0; m < 4; ++m) _Pragma("unroll") for (int k = 0; k < 2; ++k) dst[m][k] = *(const PG8_LAS bf16x8*)(lds + PG8_SA(b, h) + aoff + m * 2048 + k * 1024); } while (0)
; #define PG8_LDB(dst, b, h) do { _Pragma("unroll") for (int n = 0; n < 2; ++n) _Pragma("unroll") for (int k = 0; k < 2; ++k) dst[n][k] = *(const PG8_LAS bf16x8*)(lds + PG8_SB(b, h) + boff + n * 2048 + k * 1024); } while (0)
; #define PG8_MMA(ai, bj, At, Bt) do { __builtin_amdgcn_s_setprio(1); _Pragma("unroll") for (int m = 0; m < 4; ++m) _Pragma("unroll") for (int n = 0; n < 2; ++n) _Pragma("unroll") for (int k = 0; k < 2; ++k) \
;         acc[ai][bj][m][n] = Gemm::i8 ? ::mfma16i8_g(Bt[n][k], At[m][k], acc[ai][bj][m][n]) : ::mfma16_g(Bt[n][k], At[m][k], acc[ai][bj][m][n]); __builtin_amdgcn_s_setprio(0); } while (0)
; #define PG8_WAIT_V(n) asm volatile("s_waitcnt vmcnt(" #n ")" ::: "memory")
; #define PG8_WAIT_L(n) asm volatile("s_waitcnt lgkmcnt(" #n ")" ::: "memory")
; #define PG8_BAR __builtin_amdgcn_s_barrier()
; #define PG8_SCHED __builtin_amdgcn_sched_barrier(0)
; template <class Epi, class Sched, class Gemm, bool ALIGN_EPI = false, bool SP2 = false>
; __device__ __forceinline__ void gemm_phase(PG8_LAS unsigned char* lds, const Gemm g, const Sched& S, const Epi& E) {
;     ...
;             PG8_WAIT_V(8); PG8_WAIT_L(0); PG8_BAR; PG8_MMA(1, 0, At, B0); PG8_MMA(1, 1, At, B1); PG8_BAR; PG8_SCHED;
;             PG8_LDB(B0, 1, 0); PG8_LDB(B1, 1, 1); PG8_SCHED; PG8_LDA(At, 1, 0); PG8_STAGE(PG8_SA(0, 1), a2 + hstepA, voffA);
;             PG8_WAIT_V(8); PG8_WAIT_L(0); PG8_BAR; PG8_MMA(0, 0, At, B0); PG8_MMA(0, 1, At, B1); PG8_BAR; PG8_SCHED;
;             PG8_LDA(At, 1, 1); PG8_STAGE(PG8_SB(1, 0), b3, voffB); PG8_STAGE(PG8_SB(1, 1), b3 + hB1, voffB1); PG8_STAGE(PG8_SA(1, 0), a3, voffA);
	s_setprio 1
	s_waitcnt lgkmcnt(0)
	v_mfma_f32_16x16x32_bf16 v[216:219], v[152:155], v[168:171], v[60:63]
	v_mfma_f32_16x16x32_bf16 v[60:63], v[156:159], v[172:175], v[216:219]
	v_mfma_f32_16x16x32_bf16 v[220:223], v[160:163], v[168:171], v[56:59]
	v_mfma_f32_16x16x32_bf16 v[224:227], v[152:155], v[192:195], v[44:47]
	v_mfma_f32_16x16x32_bf16 v[240:243], v[160:163], v[192:195], v[40:43]
	v_mfma_f32_16x16x32_bf16 v[244:247], v[152:155], v[200:203], v[28:31]
	v_mfma_f32_16x16x32_bf16 v[248:251], v[160:163], v[200:203], v[24:27]
	v_mfma_f32_16x16x32_bf16 v[216:219], v[152:155], v[208:211], v[12:15]
	v_mfma_f32_16x16x32_bf16 v[8:11], v[160:163], v[208:211], v[8:11]
	v_mfma_f32_16x16x32_bf16 v[56:59], v[164:167], v[172:175], v[220:223]
	v_mfma_f32_16x16x32_bf16 v[44:47], v[156:159], v[196:199], v[224:227]
	v_mfma_f32_16x16x32_bf16 v[40:43], v[164:167], v[196:199], v[240:243]
	v_mfma_f32_16x16x32_bf16 v[28:31], v[156:159], v[204:207], v[244:247]
	v_mfma_f32_16x16x32_bf16 v[24:27], v[164:167], v[204:207], v[248:251]
	v_mfma_f32_16x16x32_bf16 v[12:15], v[156:159], v[212:215], v[216:219]
	v_mfma_f32_16x16x32_bf16 v[8:11], v[164:167], v[212:215], v[8:11]
	s_setprio 0
	s_setprio 1
	v_mfma_f32_16x16x32_bf16 v[152:155], v[132:135], v[168:171], v[52:55]
	v_mfma_f32_16x16x32_bf16 v[52:55], v[136:139], v[172:175], v[152:155]
	v_mfma_f32_16x16x32_bf16 v[156:159], v[140:143], v[168:171], v[48:51]
	v_mfma_f32_16x16x32_bf16 v[160:163], v[132:135], v[192:195], v[36:39]
	v_mfma_f32_16x16x32_bf16 v[164:167], v[140:143], v[192:195], v[32:35]
	v_mfma_f32_16x16x32_bf16 v[216:219], v[132:135], v[200:203], v[20:23]
	v_mfma_f32_16x16x32_bf16 v[220:223], v[140:143], v[200:203], v[16:19]
	v_mfma_f32_16x16x32_bf16 v[152:155], v[132:135], v[208:211], v[4:7]
	v_mfma_f32_16x16x32_bf16 v[0:3], v[140:143], v[208:211], v[0:3]
	v_mfma_f32_16x16x32_bf16 v[48:51], v[128:131], v[172:175], v[156:159]
	v_mfma_f32_16x16x32_bf16 v[36:39], v[136:139], v[196:199], v[160:163]
	v_mfma_f32_16x16x32_bf16 v[32:35], v[128:131], v[196:199], v[164:167]
	v_mfma_f32_16x16x32_bf16 v[20:23], v[136:139], v[204:207], v[216:219]
	v_mfma_f32_16x16x32_bf16 v[16:19], v[128:131], v[204:207], v[220:223]
	v_mfma_f32_16x16x32_bf16 v[4:7], v[136:139], v[212:215], v[152:155]
	v_mfma_f32_16x16x32_bf16 v[0:3], v[128:131], v[212:215], v[0:3]
	s_setprio 0
	s_barrier
	s_add_i32 s78, 0, 0x18000
	v_add_u32_e32 v128, s78, v232
	s_add_i32 s79, 0, 0x1c000
	ds_read_b128 v[152:155], v128
	ds_read_b128 v[156:159], v128 offset:1024
	ds_read_b128 v[160:163], v128 offset:2048
	ds_read_b128 v[164:167], v128 offset:3072
	v_add_u32_e32 v128, s79, v232
	ds_read_b128 v[132:135], v128
	ds_read_b128 v[136:139], v128 offset:1024
	ds_read_b128 v[140:143], v128 offset:2048
	ds_read_b128 v[128:131], v128 offset:3072
	s_add_u32 s2, s2, 0x40000
	s_addc_u32 s3, s3, 0
	s_mov_b32 m0, s57
	ds_read_b128 v[168:171], v235 offset:32768
	ds_read_b128 v[172:175], v235 offset:33792
	ds_read_b128 v[192:195], v235 offset:34816
	ds_read_b128 v[196:199], v235 offset:35840
	ds_read_b128 v[200:203], v235 offset:36864
	ds_read_b128 v[204:207], v235 offset:37888
	ds_read_b128 v[208:211], v235 offset:38912
	ds_read_b128 v[212:215], v235 offset:39936
	global_load_lds_dwordx4 v176, s[2:3]
	v_lshl_add_u64 v[216:217], s[2:3], 0, v[180:181]
	s_mov_b32 m0, s58
	s_nop 0
	global_load_lds_dwordx4 v180, s[2:3]
	s_waitcnt vmcnt(8)
	s_waitcnt lgkmcnt(0)
	s_barrier
	s_setprio 1
	s_waitcnt lgkmcnt(0)
	v_mfma_f32_16x16x32_bf16 v[216:219], v[152:155], v[168:171], v[124:127]
	v_mfma_f32_16x16x32_bf16 v[124:127], v[156:159], v[172:175], v[216:219]
	v_mfma_f32_16x16x32_bf16 v[220:223], v[160:163], v[168:171], v[120:123]
	v_mfma_f32_16x16x32_bf16 v[224:227], v[152:155], v[192:195], v[108:111]
	v_mfma_f32_16x16x32_bf16 v[240:243], v[160:163], v[192:195], v[104:107]
	v_mfma_f32_16x16x32_bf16 v[244:247], v[152:155], v[200:203], v[92:95]
	v_mfma_f32_16x16x32_bf16 v[248:251], v[160:163], v[200:203], v[88:91]
	v_mfma_f32_16x16x32_bf16 v[216:219], v[152:155], v[208:211], v[76:79]
	v_mfma_f32_16x16x32_bf16 v[72:75], v[160:163], v[208:211], v[72:75]
	v_mfma_f32_16x16x32_bf16 v[120:123], v[164:167], v[172:175], v[220:223]
	v_mfma_f32_16x16x32_bf16 v[108:111], v[156:159], v[196:199], v[224:227]
	v_mfma_f32_16x16x32_bf16 v[104:107], v[164:167], v[196:199], v[240:243]
	v_mfma_f32_16x16x32_bf16 v[92:95], v[156:159], v[204:207], v[244:247]
	v_mfma_f32_16x16x32_bf16 v[88:91], v[164:167], v[204:207], v[248:251]
	v_mfma_f32_16x16x32_bf16 v[76:79], v[156:159], v[212:215], v[216:219]
	v_mfma_f32_16x16x32_bf16 v[72:75], v[164:167], v[212:215], v[72:75]
	s_setprio 0
	s_setprio 1
	v_mfma_f32_16x16x32_bf16 v[216:219], v[132:135], v[168:171], v[116:119]
	v_mfma_f32_16x16x32_bf16 v[116:119], v[136:139], v[172:175], v[216:219]
	v_mfma_f32_16x16x32_bf16 v[220:223], v[140:143], v[168:171], v[112:115]
	v_mfma_f32_16x16x32_bf16 v[224:227], v[132:135], v[192:195], v[100:103]
	v_mfma_f32_16x16x32_bf16 v[240:243], v[140:143], v[192:195], v[96:99]
	v_mfma_f32_16x16x32_bf16 v[244:247], v[132:135], v[200:203], v[84:87]
	v_mfma_f32_16x16x32_bf16 v[248:251], v[140:143], v[200:203], v[80:83]
	v_mfma_f32_16x16x32_bf16 v[168:171], v[132:135], v[208:211], v[68:71]
	v_mfma_f32_16x16x32_bf16 v[64:67], v[140:143], v[208:211], v[64:67]
	v_mfma_f32_16x16x32_bf16 v[112:115], v[128:131], v[172:175], v[220:223]
	v_mfma_f32_16x16x32_bf16 v[100:103], v[136:139], v[196:199], v[224:227]
	v_mfma_f32_16x16x32_bf16 v[96:99], v[128:131], v[196:199], v[240:243]
	v_mfma_f32_16x16x32_bf16 v[84:87], v[136:139], v[204:207], v[244:247]
	v_mfma_f32_16x16x32_bf16 v[80:83], v[128:131], v[204:207], v[248:251]
	v_mfma_f32_16x16x32_bf16 v[68:71], v[136:139], v[212:215], v[168:171]
	v_mfma_f32_16x16x32_bf16 v[64:67], v[128:131], v[212:215], v[64:67]
	s_setprio 0
	s_barrier
; #define EPN_LOAD(i) do { const size_t off_ = EPN_OFF(i); x0q[i] = *(const f32x4*)(xin + off_); x1q[i] = *(const f32x4*)(xin + off_ + 4); } while (0)
; #define PG8_STAGE(bufoff, gbase, voff) do { _Pragma("unroll") for (int _i = 0; _i < 2; ++_i) \
;         __builtin_amdgcn_global_load_lds((const unsigned*)((const char*)(gbase) + (voff)[_i]), (PG8_LAS unsigned*)(lds + (bufoff) + ldsw + _i * 8192), 16, 0, 0); } while (0)
; #define PG8_LDA(dst, b, h) do { _Pragma("unroll") for (int m = 0; m < 4; ++m) _Pragma("unroll") for (int k = 0; k < 2; ++k) dst[m][k] = *(const PG8_LAS bf16x8*)(lds + PG8_SA(b, h) + aoff + m * 2048 + k * 1024); } while (0)
; #define PG8_MMA(ai, bj, At, Bt) do { __builtin_amdgcn_s_setprio(1); _Pragma("unroll") for (int m = 0; m < 4; ++m) _Pragma("unroll") for (int n = 0; n < 2; ++n) _Pragma("unroll") for (int k = 0; k < 2; ++k) \
;         acc[ai][bj][m][n] = Gemm::i8 ? ::mfma16i8_g(Bt[n][k], At[m][k], acc[ai][bj][m][n]) : ::mfma16_g(Bt[n][k], At[m][k], acc[ai][bj][m][n]); __builtin_amdgcn_s_setprio(0); } while (0)
; #define PG8_WAIT_V(n) asm volatile("s_waitcnt vmcnt(" #n ")" ::: "memory")
; #define PG8_WAIT_L(n) asm volatile("s_waitcnt lgkmcnt(" #n ")" ::: "memory")
; #define PG8_BAR __builtin_amdgcn_s_barrier()
;     __device__ __forceinline__ void operator()(f32x4 (&acc)[2][2][4][2], const Unit& u, int wr, int wc, int fr, int fq) const {
;     ...
; #pragma unroll
;         for (int i = 0; i < DEPTH; ++i) EPN_LOAD(i);
;         asm volatile("" ::: "memory");
; #pragma unroll
;         for (int i = 0; i < 16; ++i) {
;             const int ai = i >> 3, m = (i >> 1) & 3, bj = i & 1;
;             acc[ai][bj][m][0] += x0q[i]; acc[ai][bj][m][1] += x1q[i];
; template <class Epi, class Sched, class Gemm, bool ALIGN_EPI = false, bool SP2 = false>
; __device__ __forceinline__ void gemm_phase(PG8_LAS unsigned char* lds, const Gemm g, const Sched& S, const Epi& E) {
;     ...
;             PG8_WAIT_V(8); PG8_WAIT_L(0); PG8_BAR; PG8_MMA(0, 0, At, B0); PG8_MMA(0, 1, At, B1); PG8_BAR; PG8_SCHED;
;             PG8_LDA(At, 1, 1); PG8_STAGE(PG8_SB(1, 0), b3, voffB); PG8_STAGE(PG8_SB(1, 1), b3 + hB1, voffB1); PG8_STAGE(PG8_SA(1, 0), a3, voffA);
;             PG8_WAIT_V(8);
;             if constexpr (epi_pre<Epi>::value) { if (last) E.pre(pre, cur, wr, wc, lane); }
;             PG8_WAIT_L(0); PG8_BAR; PG8_MMA(1, 0, At, B0); PG8_MMA(1, 1, At, B1); PG8_BAR; PG8_SCHED;
	s_add_i32 s2, s78, s54
	v_lshl_add_u64 v[144:145], v[144:145], 0, s[16:17]
	s_mov_b32 m0, s2
	ds_read_b128 v[168:171], v235 offset:49152
	ds_read_b128 v[172:175], v235 offset:50176
	ds_read_b128 v[192:195], v235 offset:51200
	ds_read_b128 v[196:199], v235 offset:52224
	ds_read_b128 v[200:203], v235 offset:53248
	ds_read_b128 v[204:207], v235 offset:54272
	ds_read_b128 v[208:211], v235 offset:55296
	ds_read_b128 v[212:215], v235 offset:56320
	global_load_lds_dwordx4 v[144:145], off
	s_add_i32 m0, s2, 0x2000
	s_add_u32 s2, s48, 0x40080
	v_lshl_add_u64 v[144:145], v[146:147], 0, s[16:17]
	s_addc_u32 s3, s49, 0
	s_add_i32 s48, s79, s54
	global_load_lds_dwordx4 v[144:145], off
	s_mov_b32 m0, s48
	s_nop 0
	global_load_lds_dwordx4 v178, s[2:3]
	s_add_i32 m0, s48, 0x2000
	s_nop 0
	global_load_lds_dwordx4 v182, s[2:3]
	v_lshl_add_u64 v[144:145], v[148:149], 0, s[16:17]
	s_mov_b32 m0, s64
	s_nop 0
	global_load_lds_dwordx4 v[144:145], off
	v_lshl_add_u64 v[144:145], v[150:151], 0, s[16:17]
	s_mov_b32 m0, s65
	s_nop 0
	global_load_lds_dwordx4 v[144:145], off
	s_waitcnt vmcnt(8)
	s_waitcnt lgkmcnt(0)
	s_barrier
	s_setprio 1
	s_waitcnt lgkmcnt(0)
	v_mfma_f32_16x16x32_bf16 v[144:147], v[152:155], v[168:171], v[60:63]
	v_mfma_f32_16x16x32_bf16 v[60:63], v[156:159], v[172:175], v[144:147]
	v_mfma_f32_16x16x32_bf16 v[148:151], v[160:163], v[168:171], v[56:59]
	v_mfma_f32_16x16x32_bf16 v[216:219], v[152:155], v[192:195], v[44:47]
	v_mfma_f32_16x16x32_bf16 v[220:223], v[160:163], v[192:195], v[40:43]
	v_mfma_f32_16x16x32_bf16 v[224:227], v[152:155], v[200:203], v[28:31]
	v_mfma_f32_16x16x32_bf16 v[240:243], v[160:163], v[200:203], v[24:27]
	v_mfma_f32_16x16x32_bf16 v[144:147], v[152:155], v[208:211], v[12:15]
	v_mfma_f32_16x16x32_bf16 v[8:11], v[160:163], v[208:211], v[8:11]
	v_mfma_f32_16x16x32_bf16 v[56:59], v[164:167], v[172:175], v[148:151]
	v_mfma_f32_16x16x32_bf16 v[44:47], v[156:159], v[196:199], v[216:219]
	v_mfma_f32_16x16x32_bf16 v[40:43], v[164:167], v[196:199], v[220:223]
	v_mfma_f32_16x16x32_bf16 v[28:31], v[156:159], v[204:207], v[224:227]
	v_mfma_f32_16x16x32_bf16 v[24:27], v[164:167], v[204:207], v[240:243]
	v_mfma_f32_16x16x32_bf16 v[12:15], v[156:159], v[212:215], v[144:147]
	v_mfma_f32_16x16x32_bf16 v[8:11], v[164:167], v[212:215], v[8:11]
	s_setprio 0
	s_setprio 1
	v_mfma_f32_16x16x32_bf16 v[144:147], v[132:135], v[168:171], v[52:55]
	v_mfma_f32_16x16x32_bf16 v[52:55], v[136:139], v[172:175], v[144:147]
	v_mfma_f32_16x16x32_bf16 v[148:151], v[140:143], v[168:171], v[48:51]
	v_mfma_f32_16x16x32_bf16 v[152:155], v[132:135], v[192:195], v[36:39]
	v_mfma_f32_16x16x32_bf16 v[156:159], v[140:143], v[192:195], v[32:35]
	v_mfma_f32_16x16x32_bf16 v[160:163], v[132:135], v[200:203], v[20:23]
	v_mfma_f32_16x16x32_bf16 v[164:167], v[140:143], v[200:203], v[16:19]
	v_mfma_f32_16x16x32_bf16 v[144:147], v[132:135], v[208:211], v[4:7]
	v_mfma_f32_16x16x32_bf16 v[0:3], v[140:143], v[208:211], v[0:3]
	v_mfma_f32_16x16x32_bf16 v[48:51], v[128:131], v[172:175], v[148:151]
	v_mfma_f32_16x16x32_bf16 v[36:39], v[136:139], v[196:199], v[152:155]
	v_mfma_f32_16x16x32_bf16 v[32:35], v[128:131], v[196:199], v[156:159]
	v_mfma_f32_16x16x32_bf16 v[20:23], v[136:139], v[204:207], v[160:163]
	v_mfma_f32_16x16x32_bf16 v[16:19], v[128:131], v[204:207], v[164:167]
	v_mfma_f32_16x16x32_bf16 v[4:7], v[136:139], v[212:215], v[144:147]
	v_mfma_f32_16x16x32_bf16 v[0:3], v[128:131], v[212:215], v[0:3]
	s_setprio 0
	s_barrier
	s_add_i32 s77, s77, 2
	s_add_u32 s75, s75, 0x100
	s_addc_u32 s76, s76, 0
	s_add_u32 s46, s46, 0x100
	s_addc_u32 s47, s47, 0
	s_cmp_gt_u32 s77, 13
	s_cbranch_scc0 .LBB0_2730
	s_and_b64 vcc, exec, s[18:19]
	s_cbranch_vccz .LBB0_2733
	s_barrier
.LBB0_2733:
	s_lshl_b32 s2, s44, 8
	v_mov_b32_e32 v239, v230
	v_mov_b32_e32 v240, v231
	s_add_i32 s2, s2, s62
	s_nop 0
	v_add_u32_e32 v196, s2, v239
	s_lshl_b32 s2, s4, 8
	s_or_b32 s2, s2, s63
	v_lshl_add_u32 v224, v240, 3, s2
	v_ashrrev_i32_e32 v225, 31, v224
	v_lshlrev_b64 v[194:195], 2, v[224:225]
	v_ashrrev_i32_e32 v197, 31, v196
	v_lshl_add_u64 v[128:129], s[10:11], 0, v[194:195]
	v_lshlrev_b64 v[192:193], 12, v[196:197]
	v_lshl_add_u64 v[130:131], v[128:129], 0, v[192:193]
	global_load_dwordx4 v[204:207], v[130:131], off offset:16
	global_load_dwordx4 v[208:211], v[130:131], off
	global_load_dwordx4 v[242:245], v[130:131], off offset:528
	global_load_dwordx4 v[214:217], v[130:131], off offset:512
	v_lshl_add_u64 v[202:203], v[192:193], 0, s[20:21]
	v_lshl_add_u64 v[130:131], v[128:129], 0, v[202:203]
	v_lshl_add_u64 v[200:201], v[192:193], 0, s[22:23]
	v_lshl_add_u64 v[198:199], v[192:193], 0, s[24:25]
	v_lshl_add_u64 v[226:227], s[10:11], 0, v[192:193]
	global_load_dwordx4 v[168:171], v[130:131], off offset:16
	global_load_dwordx4 v[172:175], v[130:131], off
	global_load_dwordx4 v[160:163], v[130:131], off offset:528
	global_load_dwordx4 v[164:167], v[130:131], off offset:512
	v_lshl_add_u64 v[130:131], v[128:129], 0, v[200:201]
	v_lshl_add_u64 v[132:133], v[128:129], 0, v[198:199]
	global_load_dwordx4 v[152:155], v[130:131], off offset:16
	global_load_dwordx4 v[156:159], v[130:131], off
	global_load_dwordx4 v[144:147], v[130:131], off offset:528
	global_load_dwordx4 v[148:151], v[130:131], off offset:512
	global_load_dwordx4 v[136:139], v[132:133], off offset:16
	global_load_dwordx4 v[140:143], v[132:133], off
	s_nop 0
	global_load_dwordx4 v[128:131], v[132:133], off offset:528
	s_nop 0
	global_load_dwordx4 v[132:135], v[132:133], off offset:512
	v_cmp_eq_u32_e64 s[4:5], 0, v240
	v_lshl_add_u64 v[196:197], v[196:197], 2, s[14:15]
	s_waitcnt vmcnt(15)
	v_pk_add_f32 v[206:207], v[122:123], v[206:207]
	s_waitcnt vmcnt(14)
; #define EPN_LOAD(i) do { const size_t off_ = EPN_OFF(i); x0q[i] = *(const f32x4*)(xin + off_); x1q[i] = *(const f32x4*)(xin + off_ + 4); } while (0)
;     __device__ __forceinline__ void operator()(f32x4 (&acc)[2][2][4][2], const Unit& u, int wr, int wc, int fr, int fq) const {
;     ...
;         for (int i = 0; i < 16; ++i) {
;             const int ai = i >> 3, m = (i >> 1) & 3, bj = i & 1;
;             acc[ai][bj][m][0] += x0q[i]; acc[ai][bj][m][1] += x1q[i];
;             asm volatile("" ::: "memory");
;             if (i + DEPTH < 16) { EPN_LOAD(i + DEPTH); asm volatile("" ::: "memory"); }
;             if (bj == 1) {
;                 float q = 0.f;
; #pragma unroll
;                 for (int b2 = 0; b2 < 2; ++b2)
; #pragma unroll
;                     for (int n = 0; n < 2; ++n) { const f32x4 v = acc[ai][b2][m][n]; q += (v[0] * v[0] + v[1] * v[1]) + (v[2] * v[2] + v[3] * v[3]); }
;                 q += __shfl_xor(q, 16); q += __shfl_xor(q, 32);
;                 if (fq == 0) atomicAdd(SS + row0 + ai * HALF + m * 16, q);
	v_pk_add_f32 v[212:213], v[124:125], v[208:209]
	v_pk_add_f32 v[208:209], v[120:121], v[204:205]
	v_lshl_add_u64 v[204:205], v[226:227], 0, v[194:195]
	v_add_co_u32_e32 v120, vcc, s70, v204
	v_pk_add_f32 v[210:211], v[126:127], v[210:211]
	s_nop 0
	v_addc_co_u32_e32 v121, vcc, 0, v205, vcc
	v_lshl_add_u64 v[192:193], v[204:205], 0, s[26:27]
	global_load_dwordx4 v[124:127], v[120:121], off
	s_nop 0
	global_load_dwordx4 v[120:123], v[192:193], off offset:16
	s_waitcnt vmcnt(14)
	v_pk_add_f32 v[218:219], v[118:119], v[216:217]
	v_pk_add_f32 v[220:221], v[116:117], v[214:215]
	v_pk_add_f32 v[214:215], v[114:115], v[244:245]
	v_pk_add_f32 v[216:217], v[112:113], v[242:243]
	global_load_dwordx4 v[112:115], v[192:193], off offset:528
	global_load_dwordx4 v[116:119], v[192:193], off offset:512
	v_mul_f32_e32 v222, v213, v213
	v_mul_f32_e32 v223, v211, v211
	v_fmac_f32_e32 v222, v212, v212
	v_fmac_f32_e32 v223, v210, v210
	v_add_f32_e32 v222, v222, v223
	v_mul_f32_e32 v223, v209, v209
	v_mul_f32_e32 v228, v207, v207
	v_fmac_f32_e32 v223, v208, v208
	v_fmac_f32_e32 v228, v206, v206
	v_add_f32_e32 v223, v223, v228
	v_add_f32_e32 v222, v222, v223
	v_mul_f32_e32 v223, v221, v221
	v_mul_f32_e32 v228, v219, v219
	v_fmac_f32_e32 v223, v220, v220
	v_fmac_f32_e32 v228, v218, v218
	v_add_f32_e32 v223, v223, v228
	v_add_f32_e32 v222, v222, v223
	v_mul_f32_e32 v223, v217, v217
	v_mul_f32_e32 v228, v215, v215
	v_fmac_f32_e32 v223, v216, v216
	v_fmac_f32_e32 v228, v214, v214
	v_add_f32_e32 v223, v223, v228
	v_and_b32_e32 v228, 64, v236
	v_add_f32_e32 v222, v222, v223
	v_xor_b32_e32 v223, 16, v236
	v_add_u32_e32 v228, 64, v228
	v_cmp_lt_i32_e32 vcc, v223, v228
	s_nop 1
	v_cndmask_b32_e32 v223, v236, v223, vcc
	v_lshlrev_b32_e32 v241, 2, v223
	v_mov_b32_e32 v223, v222
	s_nop 1
	v_permlane16_swap_b32_e32 v222, v223
	s_nop 0
	s_waitcnt lgkmcnt(0)
	v_add_f32_e32 v222, v222, v223
	v_xor_b32_e32 v223, 32, v236
	v_cmp_lt_i32_e32 vcc, v223, v228
	s_nop 1
	v_cndmask_b32_e32 v223, v236, v223, vcc
	v_lshlrev_b32_e32 v242, 2, v223
	v_mov_b32_e32 v223, v222
	s_nop 1
	v_permlane32_swap_b32_e32 v222, v223
	s_nop 0
	s_and_saveexec_b64 s[2:3], s[4:5]
	s_cbranch_execz .LBB0_2735
	s_waitcnt lgkmcnt(0)
	v_add_f32_e32 v222, v222, v223
	global_atomic_add_f32 v[196:197], v222, off
.LBB0_2735:
	s_or_b64 exec, exec, s[2:3]
	v_lshl_add_u64 v[228:229], v[224:225], 2, v[226:227]
	s_waitcnt lgkmcnt(0)
	s_waitcnt vmcnt(14)
	v_pk_add_f32 v[222:223], v[108:109], v[172:173]
	v_pk_add_f32 v[172:173], v[104:105], v[168:169]
	v_add_co_u32_e32 v104, vcc, s71, v228
	v_pk_add_f32 v[174:175], v[110:111], v[174:175]
	s_nop 0
	v_addc_co_u32_e32 v105, vcc, 0, v229, vcc
	v_pk_add_f32 v[170:171], v[106:107], v[170:171]
	v_lshl_add_u64 v[168:169], v[228:229], 0, s[28:29]
	global_load_dwordx4 v[108:111], v[104:105], off
	s_nop 0
	global_load_dwordx4 v[104:107], v[168:169], off offset:16
	s_waitcnt vmcnt(14)
	v_pk_add_f32 v[166:167], v[102:103], v[166:167]
	v_pk_add_f32 v[164:165], v[100:101], v[164:165]
	v_pk_add_f32 v[162:163], v[98:99], v[162:163]
	v_pk_add_f32 v[160:161], v[96:97], v[160:161]
	global_load_dwordx4 v[96:99], v[168:169], off offset:528
	global_load_dwordx4 v[100:103], v[168:169], off offset:512
	v_mul_f32_e32 v224, v223, v223
	v_mul_f32_e32 v225, v175, v175
	v_fmac_f32_e32 v224, v222, v222
	v_fmac_f32_e32 v225, v174, v174
	v_add_f32_e32 v224, v224, v225
	v_mul_f32_e32 v225, v173, v173
	v_mul_f32_e32 v226, v171, v171
	v_fmac_f32_e32 v225, v172, v172
	v_fmac_f32_e32 v226, v170, v170
	v_add_f32_e32 v225, v225, v226
	v_add_f32_e32 v224, v224, v225
	v_mul_f32_e32 v225, v165, v165
	v_mul_f32_e32 v226, v167, v167
	v_fmac_f32_e32 v225, v164, v164
	v_fmac_f32_e32 v226, v166, v166
	v_add_f32_e32 v225, v225, v226
	v_add_f32_e32 v224, v224, v225
	v_mul_f32_e32 v225, v161, v161
	v_mul_f32_e32 v226, v163, v163
	v_fmac_f32_e32 v225, v160, v160
	v_fmac_f32_e32 v226, v162, v162
	v_add_f32_e32 v225, v225, v226
	v_add_f32_e32 v224, v224, v225
	v_mov_b32_e32 v225, v224
	s_nop 1
	v_permlane16_swap_b32_e32 v224, v225
	s_nop 0
	s_waitcnt lgkmcnt(0)
	v_add_f32_e32 v224, v224, v225
	v_mov_b32_e32 v225, v224
	s_nop 1
	v_permlane32_swap_b32_e32 v224, v225
	s_nop 0
	s_and_saveexec_b64 s[2:3], s[4:5]
	s_cbranch_execz .LBB0_2737
	s_waitcnt lgkmcnt(0)
	v_add_f32_e32 v224, v224, v225
	global_atomic_add_f32 v[196:197], v224, off offset:64
.LBB0_2737:
	s_or_b64 exec, exec, s[2:3]
	s_waitcnt lgkmcnt(0)
	s_waitcnt vmcnt(14)
	v_pk_add_f32 v[224:225], v[92:93], v[156:157]
	v_pk_add_f32 v[156:157], v[88:89], v[152:153]
	v_add_co_u32_e32 v88, vcc, s72, v228
	v_pk_add_f32 v[158:159], v[94:95], v[158:159]
	s_nop 0
	v_addc_co_u32_e32 v89, vcc, 0, v229, vcc
	v_pk_add_f32 v[154:155], v[90:91], v[154:155]
	v_lshl_add_u64 v[152:153], v[228:229], 0, s[30:31]
	global_load_dwordx4 v[92:95], v[88:89], off
	s_nop 0
	global_load_dwordx4 v[88:91], v[152:153], off offset:16
	s_waitcnt vmcnt(14)
	v_pk_add_f32 v[150:151], v[86:87], v[150:151]
	v_pk_add_f32 v[148:149], v[84:85], v[148:149]
	v_pk_add_f32 v[146:147], v[82:83], v[146:147]
	v_pk_add_f32 v[144:145], v[80:81], v[144:145]
	global_load_dwordx4 v[80:83], v[152:153], off offset:528
	global_load_dwordx4 v[84:87], v[152:153], off offset:512
	v_mul_f32_e32 v226, v225, v225
	v_mul_f32_e32 v227, v159, v159
	v_fmac_f32_e32 v226, v224, v224
	v_fmac_f32_e32 v227, v158, v158
	v_add_f32_e32 v226, v226, v227
	v_mul_f32_e32 v227, v157, v157
	v_mul_f32_e32 v243, v155, v155
	v_fmac_f32_e32 v227, v156, v156
	v_fmac_f32_e32 v243, v154, v154
	v_add_f32_e32 v227, v227, v243
	v_add_f32_e32 v226, v226, v227
	v_mul_f32_e32 v227, v149, v149
	v_mul_f32_e32 v243, v151, v151
	v_fmac_f32_e32 v227, v148, v148
	v_fmac_f32_e32 v243, v150, v150
	v_add_f32_e32 v227, v227, v243
	v_add_f32_e32 v226, v226, v227
	v_mul_f32_e32 v227, v145, v145
	v_mul_f32_e32 v243, v147, v147
	v_fmac_f32_e32 v227, v144, v144
	v_fmac_f32_e32 v243, v146, v146
	v_add_f32_e32 v227, v227, v243
	v_add_f32_e32 v226, v226, v227
	v_mov_b32_e32 v227, v226
	s_nop 1
	v_permlane16_swap_b32_e32 v226, v227
	s_nop 0
	s_waitcnt lgkmcnt(0)
	v_add_f32_e32 v226, v226, v227
	v_mov_b32_e32 v227, v226
	s_nop 1
	v_permlane32_swap_b32_e32 v226, v227
	s_nop 0
	s_and_saveexec_b64 s[2:3], s[4:5]
	s_cbranch_execz .LBB0_2739
	s_waitcnt lgkmcnt(0)
	v_add_f32_e32 v226, v226, v227
	global_atomic_add_f32 v[196:197], v226, off offset:128
; #define EPN_LOAD(i) do { const size_t off_ = EPN_OFF(i); x0q[i] = *(const f32x4*)(xin + off_); x1q[i] = *(const f32x4*)(xin + off_ + 4); } while (0)
;     __device__ __forceinline__ void operator()(f32x4 (&acc)[2][2][4][2], const Unit& u, int wr, int wc, int fr, int fq) const {
;     ...
;         for (int i = 0; i < 16; ++i) {
;             const int ai = i >> 3, m = (i >> 1) & 3, bj = i & 1;
;             acc[ai][bj][m][0] += x0q[i]; acc[ai][bj][m][1] += x1q[i];
;             asm volatile("" ::: "memory");
;             if (i + DEPTH < 16) { EPN_LOAD(i + DEPTH); asm volatile("" ::: "memory"); }
;             if (bj == 1) {
;                 float q = 0.f;
; #pragma unroll
;                 for (int b2 = 0; b2 < 2; ++b2)
; #pragma unroll
;                     for (int n = 0; n < 2; ++n) { const f32x4 v = acc[ai][b2][m][n]; q += (v[0] * v[0] + v[1] * v[1]) + (v[2] * v[2] + v[3] * v[3]); }
;                 q += __shfl_xor(q, 16); q += __shfl_xor(q, 32);
;                 if (fq == 0) atomicAdd(SS + row0 + ai * HALF + m * 16, q);
.LBB0_2739:
	s_or_b64 exec, exec, s[2:3]
	s_waitcnt lgkmcnt(0)
	s_waitcnt vmcnt(14)
	v_pk_add_f32 v[226:227], v[76:77], v[140:141]
	v_pk_add_f32 v[140:141], v[72:73], v[136:137]
	v_add_co_u32_e32 v72, vcc, s73, v228
	v_pk_add_f32 v[142:143], v[78:79], v[142:143]
	s_nop 0
	v_addc_co_u32_e32 v73, vcc, 0, v229, vcc
	v_pk_add_f32 v[138:139], v[74:75], v[138:139]
	v_lshl_add_u64 v[136:137], v[228:229], 0, s[34:35]
	global_load_dwordx4 v[76:79], v[72:73], off
	s_nop 0
	global_load_dwordx4 v[72:75], v[136:137], off offset:16
	s_waitcnt vmcnt(14)
	v_pk_add_f32 v[134:135], v[70:71], v[134:135]
	v_pk_add_f32 v[132:133], v[68:69], v[132:133]
	v_pk_add_f32 v[130:131], v[66:67], v[130:131]
	v_pk_add_f32 v[128:129], v[64:65], v[128:129]
	global_load_dwordx4 v[64:67], v[136:137], off offset:528
	global_load_dwordx4 v[68:71], v[136:137], off offset:512
	v_mul_f32_e32 v243, v227, v227
	v_mul_f32_e32 v244, v143, v143
	v_fmac_f32_e32 v243, v226, v226
	v_fmac_f32_e32 v244, v142, v142
	v_add_f32_e32 v243, v243, v244
	v_mul_f32_e32 v244, v141, v141
	v_mul_f32_e32 v245, v139, v139
	v_fmac_f32_e32 v244, v140, v140
	v_fmac_f32_e32 v245, v138, v138
	v_add_f32_e32 v244, v244, v245
	v_add_f32_e32 v243, v243, v244
	v_mul_f32_e32 v244, v133, v133
	v_mul_f32_e32 v245, v135, v135
	v_fmac_f32_e32 v244, v132, v132
	v_fmac_f32_e32 v245, v134, v134
	v_add_f32_e32 v244, v244, v245
	v_add_f32_e32 v243, v243, v244
	v_mul_f32_e32 v244, v129, v129
	v_mul_f32_e32 v245, v131, v131
	v_fmac_f32_e32 v244, v128, v128
	v_fmac_f32_e32 v245, v130, v130
	v_add_f32_e32 v244, v244, v245
	v_add_f32_e32 v243, v243, v244
	v_mov_b32_e32 v244, v243
	s_nop 1
	v_permlane16_swap_b32_e32 v243, v244
	s_nop 0
	s_waitcnt lgkmcnt(0)
	v_add_f32_e32 v243, v243, v244
	ds_bpermute_b32 v244, v242, v243
	s_and_saveexec_b64 s[2:3], s[4:5]
	s_cbranch_execz .LBB0_2741
	s_waitcnt lgkmcnt(0)
	v_add_f32_e32 v243, v243, v244
	global_atomic_add_f32 v[196:197], v243, off offset:192
.LBB0_2741:
	s_or_b64 exec, exec, s[2:3]
	s_waitcnt vmcnt(15)
	v_pk_add_f32 v[126:127], v[62:63], v[126:127]
	v_pk_add_f32 v[124:125], v[60:61], v[124:125]
	s_waitcnt vmcnt(13)
	v_pk_add_f32 v[112:113], v[48:49], v[112:113]
	v_mul_f32_e32 v48, v125, v125
	v_mul_f32_e32 v49, v127, v127
	v_pk_add_f32 v[122:123], v[58:59], v[122:123]
	v_pk_add_f32 v[120:121], v[56:57], v[120:121]
	v_fmac_f32_e32 v48, v124, v124
	v_fmac_f32_e32 v49, v126, v126
	v_pk_add_f32 v[60:61], v[50:51], v[114:115]
	v_add_f32_e32 v48, v48, v49
	v_mul_f32_e32 v49, v121, v121
	v_mul_f32_e32 v50, v123, v123
	v_fmac_f32_e32 v49, v120, v120
	v_fmac_f32_e32 v50, v122, v122
	s_waitcnt vmcnt(12)
	v_pk_add_f32 v[62:63], v[54:55], v[118:119]
	v_pk_add_f32 v[116:117], v[52:53], v[116:117]
	v_add_f32_e32 v49, v49, v50
	v_add_f32_e32 v48, v48, v49
	v_mul_f32_e32 v49, v117, v117
	v_mul_f32_e32 v50, v63, v63
	v_fmac_f32_e32 v49, v116, v116
	v_fmac_f32_e32 v50, v62, v62
	v_add_f32_e32 v49, v49, v50
	v_add_f32_e32 v48, v48, v49
	v_mul_f32_e32 v49, v113, v113
	v_mul_f32_e32 v50, v61, v61
	v_fmac_f32_e32 v49, v112, v112
	v_fmac_f32_e32 v50, v60, v60
	v_add_f32_e32 v49, v49, v50
	v_add_f32_e32 v48, v48, v49
	v_mov_b32_e32 v49, v48
	s_nop 1
	v_permlane16_swap_b32_e32 v48, v49
	s_nop 0
	s_waitcnt lgkmcnt(0)
	v_add_f32_e32 v48, v48, v49
	ds_bpermute_b32 v49, v242, v48
	s_and_saveexec_b64 s[2:3], s[4:5]
	s_cbranch_execz .LBB0_2743
	s_waitcnt lgkmcnt(0)
	v_add_f32_e32 v48, v48, v49
	global_atomic_add_f32 v[196:197], v48, off offset:512
; #define EPN_LOAD(i) do { const size_t off_ = EPN_OFF(i); x0q[i] = *(const f32x4*)(xin + off_); x1q[i] = *(const f32x4*)(xin + off_ + 4); } while (0)
;     __device__ __forceinline__ void operator()(f32x4 (&acc)[2][2][4][2], const Unit& u, int wr, int wc, int fr, int fq) const {
;     ...
;         for (int i = 0; i < 16; ++i) {
;             const int ai = i >> 3, m = (i >> 1) & 3, bj = i & 1;
;             acc[ai][bj][m][0] += x0q[i]; acc[ai][bj][m][1] += x1q[i];
;             asm volatile("" ::: "memory");
;             if (i + DEPTH < 16) { EPN_LOAD(i + DEPTH); asm volatile("" ::: "memory"); }
;             if (bj == 1) {
;                 float q = 0.f;
; #pragma unroll
;                 for (int b2 = 0; b2 < 2; ++b2)
; #pragma unroll
;                     for (int n = 0; n < 2; ++n) { const f32x4 v = acc[ai][b2][m][n]; q += (v[0] * v[0] + v[1] * v[1]) + (v[2] * v[2] + v[3] * v[3]); }
;                 q += __shfl_xor(q, 16); q += __shfl_xor(q, 32);
;                 if (fq == 0) atomicAdd(SS + row0 + ai * HALF + m * 16, q);
.LBB0_2743:
	s_or_b64 exec, exec, s[2:3]
	s_waitcnt vmcnt(11)
	v_pk_add_f32 v[58:59], v[46:47], v[110:111]
	v_pk_add_f32 v[108:109], v[44:45], v[108:109]
	s_waitcnt vmcnt(9)
	v_pk_add_f32 v[54:55], v[32:33], v[96:97]
	v_mul_f32_e32 v32, v109, v109
	v_mul_f32_e32 v33, v59, v59
	v_pk_add_f32 v[56:57], v[42:43], v[106:107]
	v_pk_add_f32 v[104:105], v[40:41], v[104:105]
	v_fmac_f32_e32 v32, v108, v108
	v_fmac_f32_e32 v33, v58, v58
	v_pk_add_f32 v[44:45], v[34:35], v[98:99]
	v_add_f32_e32 v32, v32, v33
	v_mul_f32_e32 v33, v105, v105
	v_mul_f32_e32 v34, v57, v57
	v_fmac_f32_e32 v33, v104, v104
	v_fmac_f32_e32 v34, v56, v56
	s_waitcnt vmcnt(8)
	v_pk_add_f32 v[46:47], v[38:39], v[102:103]
	v_pk_add_f32 v[52:53], v[36:37], v[100:101]
	v_add_f32_e32 v33, v33, v34
	v_add_f32_e32 v32, v32, v33
	v_mul_f32_e32 v33, v53, v53
	v_mul_f32_e32 v34, v47, v47
	v_fmac_f32_e32 v33, v52, v52
	v_fmac_f32_e32 v34, v46, v46
	v_add_f32_e32 v33, v33, v34
	v_add_f32_e32 v32, v32, v33
	v_mul_f32_e32 v33, v55, v55
	v_mul_f32_e32 v34, v45, v45
	v_fmac_f32_e32 v33, v54, v54
	v_fmac_f32_e32 v34, v44, v44
	v_add_f32_e32 v33, v33, v34
	v_add_f32_e32 v32, v32, v33
	v_mov_b32_e32 v33, v32
	s_nop 1
	v_permlane16_swap_b32_e32 v32, v33
	s_nop 0
	s_waitcnt lgkmcnt(0)
	v_add_f32_e32 v32, v32, v33
	v_mov_b32_e32 v33, v32
	s_nop 1
	v_permlane32_swap_b32_e32 v32, v33
	s_nop 0
	s_and_saveexec_b64 s[2:3], s[4:5]
	s_cbranch_execz .LBB0_2745
	s_waitcnt lgkmcnt(0)
	v_add_f32_e32 v32, v32, v33
	global_atomic_add_f32 v[196:197], v32, off offset:576
.LBB0_2745:
	s_or_b64 exec, exec, s[2:3]
	s_waitcnt vmcnt(7)
	v_pk_add_f32 v[42:43], v[30:31], v[94:95]
	v_pk_add_f32 v[48:49], v[28:29], v[92:93]
	s_waitcnt vmcnt(5)
	v_pk_add_f32 v[38:39], v[16:17], v[80:81]
	v_mul_f32_e32 v16, v49, v49
	v_mul_f32_e32 v17, v43, v43
	v_pk_add_f32 v[40:41], v[26:27], v[90:91]
	v_pk_add_f32 v[50:51], v[24:25], v[88:89]
	v_fmac_f32_e32 v16, v48, v48
	v_fmac_f32_e32 v17, v42, v42
	s_waitcnt lgkmcnt(0)
	v_pk_add_f32 v[32:33], v[18:19], v[82:83]
	v_add_f32_e32 v16, v16, v17
	v_mul_f32_e32 v17, v51, v51
	v_mul_f32_e32 v18, v41, v41
	v_fmac_f32_e32 v17, v50, v50
	v_fmac_f32_e32 v18, v40, v40
	s_waitcnt vmcnt(4)
	v_pk_add_f32 v[34:35], v[22:23], v[86:87]
	v_pk_add_f32 v[36:37], v[20:21], v[84:85]
	v_add_f32_e32 v17, v17, v18
	v_add_f32_e32 v16, v16, v17
	v_mul_f32_e32 v17, v37, v37
	v_mul_f32_e32 v18, v35, v35
	v_fmac_f32_e32 v17, v36, v36
	v_fmac_f32_e32 v18, v34, v34
	v_add_f32_e32 v17, v17, v18
	v_add_f32_e32 v16, v16, v17
	v_mul_f32_e32 v17, v39, v39
	v_mul_f32_e32 v18, v33, v33
	v_fmac_f32_e32 v17, v38, v38
	v_fmac_f32_e32 v18, v32, v32
	v_add_f32_e32 v17, v17, v18
	v_add_f32_e32 v16, v16, v17
	v_mov_b32_e32 v17, v16
	s_nop 1
	v_permlane16_swap_b32_e32 v16, v17
	s_nop 0
	s_waitcnt lgkmcnt(0)
	v_add_f32_e32 v16, v16, v17
	v_mov_b32_e32 v17, v16
	s_nop 1
	v_permlane32_swap_b32_e32 v16, v17
	s_nop 0
	s_and_saveexec_b64 s[2:3], s[4:5]
	s_cbranch_execz .LBB0_2747
	s_waitcnt lgkmcnt(0)
	v_add_f32_e32 v16, v16, v17
	global_atomic_add_f32 v[196:197], v16, off offset:640
.LBB0_2747:
	s_or_b64 exec, exec, s[2:3]
	s_waitcnt vmcnt(3) lgkmcnt(0)
	v_pk_add_f32 v[16:17], v[14:15], v[78:79]
	v_pk_add_f32 v[18:19], v[12:13], v[76:77]
	s_waitcnt vmcnt(1)
	v_pk_add_f32 v[30:31], v[0:1], v[64:65]
	v_mul_f32_e32 v0, v19, v19
	v_mul_f32_e32 v1, v17, v17
	v_pk_add_f32 v[20:21], v[10:11], v[74:75]
	v_pk_add_f32 v[22:23], v[8:9], v[72:73]
	v_fmac_f32_e32 v0, v18, v18
	v_fmac_f32_e32 v1, v16, v16
	v_pk_add_f32 v[28:29], v[2:3], v[66:67]
	v_add_f32_e32 v0, v0, v1
	v_mul_f32_e32 v1, v23, v23
	v_mul_f32_e32 v2, v21, v21
	v_fmac_f32_e32 v1, v22, v22
	v_fmac_f32_e32 v2, v20, v20
	s_waitcnt vmcnt(0)
	v_pk_add_f32 v[24:25], v[6:7], v[70:71]
	v_pk_add_f32 v[26:27], v[4:5], v[68:69]
	v_add_f32_e32 v1, v1, v2
	v_add_f32_e32 v0, v0, v1
	v_mul_f32_e32 v1, v27, v27
	v_mul_f32_e32 v2, v25, v25
	v_fmac_f32_e32 v1, v26, v26
	v_fmac_f32_e32 v2, v24, v24
	v_add_f32_e32 v1, v1, v2
	v_add_f32_e32 v0, v0, v1
	v_mul_f32_e32 v1, v31, v31
	v_mul_f32_e32 v2, v29, v29
	v_fmac_f32_e32 v1, v30, v30
	v_fmac_f32_e32 v2, v28, v28
	v_add_f32_e32 v1, v1, v2
	v_add_f32_e32 v0, v0, v1
	v_mov_b32_e32 v1, v0
	s_nop 1
	v_permlane16_swap_b32_e32 v0, v1
	s_nop 0
	s_waitcnt lgkmcnt(0)
	v_add_f32_e32 v0, v0, v1
	ds_bpermute_b32 v1, v242, v0
	s_and_saveexec_b64 s[2:3], s[4:5]
	s_cbranch_execz .LBB0_2749
	s_waitcnt lgkmcnt(0)
	v_add_f32_e32 v0, v0, v1
	global_atomic_add_f32 v[196:197], v0, off offset:704

; __device__ __forceinline__ unsigned xb_ld(unsigned* p)              { return __hip_atomic_load(p, __ATOMIC_RELAXED, __HIP_MEMORY_SCOPE_AGENT); }
; #define XB_SPIN(cond, bar) do { unsigned _sp = 0; while (cond) { __builtin_amdgcn_s_sleep(1); \
;     if ((++_sp & 255u) == 0u) { if (xb_ld(&(bar)[XB_TMO])) break; if (_sp > XB_SPIN_CAP) { atomicAdd(&(bar)[XB_TMO], 1u); break; } } } } while (0)
; __device__ __forceinline__ void xcd_barrier(const XcdBarrier& b) {
;     ...
;             XB_SPIN(xb_ld(&bar[XB_XGEN(b.x)]) == gen, bar);
;             __builtin_amdgcn_fence(__ATOMIC_ACQUIRE, "agent");
;             asm volatile("s_waitcnt vmcnt(0)" ::: "memory");
;         }
;     }
;     __syncthreads();
.LBB0_2823:
	s_or_b64 exec, exec, s[0:1]
	s_waitcnt lgkmcnt(0)
	s_barrier
	s_nop 0
	s_nop 0
	s_nop 0
	s_nop 0
	s_nop 0
	s_nop 0
	s_nop 0
	s_nop 0
	s_nop 0
	s_nop 0
	s_nop 0
	s_nop 0
	s_nop 0
	s_nop 0
	s_nop 0
	s_nop 0
	s_nop 0
	s_nop 0
	s_nop 0
	s_nop 0
	s_nop 0
	s_nop 0
	s_nop 0
	s_nop 0
	s_nop 0
	s_nop 0
	s_nop 0
	s_nop 0
	s_nop 0
	s_nop 0
	s_nop 0
	s_nop 0
	s_nop 0
	s_nop 0
	s_nop 0
	s_nop 0
	s_nop 0
	s_nop 0
	s_nop 0
	s_nop 0
	s_nop 0
	s_nop 0
	s_nop 0
	s_nop 0
	s_nop 0
	s_nop 0
	s_nop 0
	s_nop 0
	s_nop 0
	s_nop 0
	s_nop 0
	s_nop 0
	s_nop 0
	s_nop 0
	s_nop 0
	s_nop 0
	s_nop 0
	s_nop 0
	s_nop 0
	s_nop 0
	s_nop 0
	s_nop 0
	s_nop 0
	s_nop 0
	s_nop 0
	s_nop 0
	s_nop 0
	s_nop 0
	s_nop 0
	s_nop 0
	s_nop 0
	s_nop 0
	s_nop 0
	s_nop 0
	s_nop 0
	s_nop 0
	s_nop 0
	s_nop 0
	s_nop 0
	s_nop 0
	s_nop 0
	s_nop 0
	s_nop 0
	s_nop 0
	s_nop 0
	s_nop 0
	s_nop 0
	s_nop 0
	s_nop 0
	s_nop 0
	s_nop 0
	s_nop 0
	s_nop 0
	s_nop 0
	s_nop 0
	s_nop 0
	s_nop 0
	s_nop 0
	s_nop 0
	s_nop 0
	s_nop 0
	s_nop 0
	s_nop 0
	s_nop 0
	s_nop 0
	s_nop 0
